# pool rewrite + GEMM K-loops: s_setprio flips deleted, no static raise (separates instruction removal from priority)
# baseline (speedup 1.0000x reference)
; #define PG8_STAGE(bufoff, gbase, voff) do { _Pragma("unroll") for (int _i = 0; _i < 2; ++_i) \
;         __builtin_amdgcn_global_load_lds((const unsigned*)((const char*)(gbase) + (voff)[_i]), (LAS unsigned*)(lds + (bufoff) + ldsw + _i * 8192), 16, 0, 0); } while (0)
; #define PG8_LDA(dst, b, h) do { _Pragma("unroll") for (int m = 0; m < 4; ++m) _Pragma("unroll") for (int k = 0; k < 2; ++k) dst[m][k] = *(const LAS bf16x8*)(lds + PG8_SA(b, h) + aoff + m * 2048 + k * 1024); } while (0)
; #define PG8_LDB(dst, b, h) do { _Pragma("unroll") for (int n = 0; n < 2; ++n) _Pragma("unroll") for (int k = 0; k < 2; ++k) dst[n][k] = *(const LAS bf16x8*)(lds + PG8_SB(b, h) + boff + n * 2048 + k * 1024); } while (0)
; #define PG8_MMA(ai, bj, At, Bt) do { __builtin_amdgcn_s_setprio(1); _Pragma("unroll") for (int m = 0; m < 4; ++m) _Pragma("unroll") for (int n = 0; n < 2; ++n) _Pragma("unroll") for (int k = 0; k < 2; ++k) \
;         acc[ai][bj][m][n] = __builtin_amdgcn_mfma_f32_16x16x32_bf16(Bt[n][k], At[m][k], acc[ai][bj][m][n], 0, 0, 0); __builtin_amdgcn_s_setprio(0); } while (0)
; #define PG8_WAIT_V(n) asm volatile("s_waitcnt vmcnt(" #n ")" ::: "memory")
; #define PG8_WAIT_L(n) asm volatile("s_waitcnt lgkmcnt(" #n ")" ::: "memory")
; #define PG8_BAR __builtin_amdgcn_s_barrier()
; #define PG8_SCHED __builtin_amdgcn_sched_barrier(0)
; template <class Epi>
; __device__ __forceinline__ void gemm_phase(LAS unsigned char* lds, const Gemm g, const StaticOrder& S, const Epi& E) {
;     ...
;             PG8_LDB(B0, 0, 0); PG8_SCHED; PG8_LDA(At, 0, 0); PG8_STAGE(PG8_SA(1, 1), a1 + hstepA, voffA);
;             PG8_WAIT_L(8); PG8_BAR; PG8_WAIT_L(0); PG8_MMA(0, 0, At, B0); PG8_BAR; PG8_SCHED;
;             PG8_LDB(B1, 0, 1); PG8_STAGE(PG8_SB(0, 0), b2, voffB);
;             PG8_BAR; PG8_WAIT_L(0); PG8_MMA(0, 1, At, B1); PG8_BAR;
;             PG8_LDA(At, 0, 1); PG8_STAGE(PG8_SA(0, 0), a2, voffA);
;             PG8_BAR; PG8_WAIT_L(0); PG8_MMA(1, 0, At, B0); PG8_BAR; PG8_SCHED;
;             PG8_STAGE(PG8_SB(0, 1), b2 + hstepB, voffB);
;             PG8_WAIT_V(6); PG8_BAR; PG8_MMA(1, 1, At, B1); PG8_BAR;
.LBB0_158:
	s_add_u32 s42, s38, 0x100
	s_addc_u32 s43, s39, 0
	s_add_i32 s60, 0, 0x10000
	v_add_u32_e32 v0, s60, v152
	ds_read_b128 v[146:149], v0
	ds_read_b128 v[162:165], v0 offset:1024
	ds_read_b128 v[166:169], v0 offset:2048
	ds_read_b128 v[170:173], v0 offset:3072
	s_cmp_eq_u32 s59, 28
	s_cselect_b32 s25, s23, s43
	s_cselect_b32 s24, s55, s42
	s_cselect_b32 s5, s21, s58
	s_cselect_b32 s4, s56, s57
	v_lshl_add_u64 v[150:151], s[38:39], 0, v[140:141]
	s_add_i32 m0, s46, 0xc000
	ds_read_b128 v[174:177], v154
	ds_read_b128 v[188:191], v154 offset:1024
	ds_read_b128 v[192:195], v154 offset:2048
	ds_read_b128 v[196:199], v154 offset:3072
	ds_read_b128 v[200:203], v154 offset:4096
	ds_read_b128 v[204:207], v154 offset:5120
	ds_read_b128 v[208:211], v154 offset:6144
	ds_read_b128 v[212:215], v154 offset:7168
	global_load_lds_dwordx4 v[150:151], off
	v_lshl_add_u64 v[150:151], s[38:39], 0, v[142:143]
	s_add_i32 m0, s46, 0xe000
	s_nop 0
	global_load_lds_dwordx4 v[150:151], off
	s_waitcnt lgkmcnt(8)
	s_barrier
	s_waitcnt lgkmcnt(0)
	s_waitcnt lgkmcnt(0)
	v_mfma_f32_16x16x32_bf16 v[126:129], v[146:149], v[174:177], v[126:129]
	v_mfma_f32_16x16x32_bf16 v[122:125], v[166:169], v[174:177], v[122:125]
	v_mfma_f32_16x16x32_bf16 v[110:113], v[146:149], v[192:195], v[110:113]
	v_mfma_f32_16x16x32_bf16 v[106:109], v[166:169], v[192:195], v[106:109]
	v_mfma_f32_16x16x32_bf16 v[94:97], v[146:149], v[200:203], v[94:97]
	v_mfma_f32_16x16x32_bf16 v[90:93], v[166:169], v[200:203], v[90:93]
	v_mfma_f32_16x16x32_bf16 v[78:81], v[146:149], v[208:211], v[78:81]
	v_mfma_f32_16x16x32_bf16 v[74:77], v[166:169], v[208:211], v[74:77]
	v_mfma_f32_16x16x32_bf16 v[126:129], v[162:165], v[188:191], v[126:129]
	v_mfma_f32_16x16x32_bf16 v[122:125], v[170:173], v[188:191], v[122:125]
	v_mfma_f32_16x16x32_bf16 v[110:113], v[162:165], v[196:199], v[110:113]
	v_mfma_f32_16x16x32_bf16 v[106:109], v[170:173], v[196:199], v[106:109]
	v_mfma_f32_16x16x32_bf16 v[94:97], v[162:165], v[204:207], v[94:97]
	v_mfma_f32_16x16x32_bf16 v[90:93], v[170:173], v[204:207], v[90:93]
	v_mfma_f32_16x16x32_bf16 v[78:81], v[162:165], v[212:215], v[78:81]
	v_mfma_f32_16x16x32_bf16 v[74:77], v[170:173], v[212:215], v[74:77]
	s_barrier
	s_add_i32 s61, 0, 0x14000
	s_add_i32 s38, s60, s45
	v_add_u32_e32 v0, s61, v152
	v_lshl_add_u64 v[150:151], s[4:5], 0, v[134:135]
	s_mov_b32 m0, s38
	ds_read_b128 v[216:219], v0
	ds_read_b128 v[220:223], v0 offset:1024
	ds_read_b128 v[224:227], v0 offset:2048
	ds_read_b128 v[228:231], v0 offset:3072
	global_load_lds_dwordx4 v[150:151], off
	v_lshl_add_u64 v[184:185], s[4:5], 0, v[130:131]
	s_add_i32 m0, s38, 0x2000
	s_nop 0
	global_load_lds_dwordx4 v[184:185], off
	s_barrier
	s_waitcnt lgkmcnt(0)
	s_waitcnt lgkmcnt(0)
	v_mfma_f32_16x16x32_bf16 v[118:121], v[216:219], v[174:177], v[118:121]
	v_mfma_f32_16x16x32_bf16 v[114:117], v[224:227], v[174:177], v[114:117]
	v_mfma_f32_16x16x32_bf16 v[102:105], v[216:219], v[192:195], v[102:105]
	v_mfma_f32_16x16x32_bf16 v[98:101], v[224:227], v[192:195], v[98:101]
	v_mfma_f32_16x16x32_bf16 v[86:89], v[216:219], v[200:203], v[86:89]
	v_mfma_f32_16x16x32_bf16 v[82:85], v[224:227], v[200:203], v[82:85]
	v_mfma_f32_16x16x32_bf16 v[70:73], v[216:219], v[208:211], v[70:73]
	v_mfma_f32_16x16x32_bf16 v[66:69], v[224:227], v[208:211], v[66:69]
	v_mfma_f32_16x16x32_bf16 v[118:121], v[220:223], v[188:191], v[118:121]
	v_mfma_f32_16x16x32_bf16 v[114:117], v[228:231], v[188:191], v[114:117]
	v_mfma_f32_16x16x32_bf16 v[102:105], v[220:223], v[196:199], v[102:105]
	v_mfma_f32_16x16x32_bf16 v[98:101], v[228:231], v[196:199], v[98:101]
	v_mfma_f32_16x16x32_bf16 v[86:89], v[220:223], v[204:207], v[86:89]
	v_mfma_f32_16x16x32_bf16 v[82:85], v[228:231], v[204:207], v[82:85]
	v_mfma_f32_16x16x32_bf16 v[70:73], v[220:223], v[212:215], v[70:73]
	v_mfma_f32_16x16x32_bf16 v[66:69], v[228:231], v[212:215], v[66:69]
	s_mov_b32 m0, s46
	v_lshl_add_u64 v[186:187], s[24:25], 0, v[136:137]
	s_barrier
	ds_read_b128 v[174:177], v154 offset:16384
	ds_read_b128 v[188:191], v154 offset:17408
	ds_read_b128 v[192:195], v154 offset:18432
	ds_read_b128 v[196:199], v154 offset:19456
	ds_read_b128 v[200:203], v154 offset:20480
	ds_read_b128 v[204:207], v154 offset:21504
	ds_read_b128 v[208:211], v154 offset:22528
	ds_read_b128 v[212:215], v154 offset:23552
	global_load_lds_dwordx4 v[186:187], off
	v_lshl_add_u64 v[244:245], s[24:25], 0, v[132:133]
	s_mov_b32 m0, s47
	s_nop 0
	global_load_lds_dwordx4 v[244:245], off
	s_barrier
	s_waitcnt lgkmcnt(0)
	s_waitcnt lgkmcnt(0)
	v_mfma_f32_16x16x32_bf16 v[62:65], v[146:149], v[174:177], v[62:65]
	v_mfma_f32_16x16x32_bf16 v[58:61], v[166:169], v[174:177], v[58:61]
	v_mfma_f32_16x16x32_bf16 v[46:49], v[146:149], v[192:195], v[46:49]
	v_mfma_f32_16x16x32_bf16 v[42:45], v[166:169], v[192:195], v[42:45]
	v_mfma_f32_16x16x32_bf16 v[30:33], v[146:149], v[200:203], v[30:33]
	v_mfma_f32_16x16x32_bf16 v[26:29], v[166:169], v[200:203], v[26:29]
	v_mfma_f32_16x16x32_bf16 v[14:17], v[146:149], v[208:211], v[14:17]
	v_mfma_f32_16x16x32_bf16 v[10:13], v[166:169], v[208:211], v[10:13]
	v_mfma_f32_16x16x32_bf16 v[62:65], v[162:165], v[188:191], v[62:65]
	v_mfma_f32_16x16x32_bf16 v[58:61], v[170:173], v[188:191], v[58:61]
	v_mfma_f32_16x16x32_bf16 v[46:49], v[162:165], v[196:199], v[46:49]
	v_mfma_f32_16x16x32_bf16 v[42:45], v[170:173], v[196:199], v[42:45]
	v_mfma_f32_16x16x32_bf16 v[30:33], v[162:165], v[204:207], v[30:33]
	v_mfma_f32_16x16x32_bf16 v[26:29], v[170:173], v[204:207], v[26:29]
	v_mfma_f32_16x16x32_bf16 v[14:17], v[162:165], v[212:215], v[14:17]
	v_mfma_f32_16x16x32_bf16 v[10:13], v[170:173], v[212:215], v[10:13]
	s_barrier
; #define PG8_STAGE(bufoff, gbase, voff) do { _Pragma("unroll") for (int _i = 0; _i < 2; ++_i) \
;         __builtin_amdgcn_global_load_lds((const unsigned*)((const char*)(gbase) + (voff)[_i]), (LAS unsigned*)(lds + (bufoff) + ldsw + _i * 8192), 16, 0, 0); } while (0)
; #define PG8_LDA(dst, b, h) do { _Pragma("unroll") for (int m = 0; m < 4; ++m) _Pragma("unroll") for (int k = 0; k < 2; ++k) dst[m][k] = *(const LAS bf16x8*)(lds + PG8_SA(b, h) + aoff + m * 2048 + k * 1024); } while (0)
; #define PG8_LDB(dst, b, h) do { _Pragma("unroll") for (int n = 0; n < 2; ++n) _Pragma("unroll") for (int k = 0; k < 2; ++k) dst[n][k] = *(const LAS bf16x8*)(lds + PG8_SB(b, h) + boff + n * 2048 + k * 1024); } while (0)
; #define PG8_MMA(ai, bj, At, Bt) do { __builtin_amdgcn_s_setprio(1); _Pragma("unroll") for (int m = 0; m < 4; ++m) _Pragma("unroll") for (int n = 0; n < 2; ++n) _Pragma("unroll") for (int k = 0; k < 2; ++k) \
;         acc[ai][bj][m][n] = __builtin_amdgcn_mfma_f32_16x16x32_bf16(Bt[n][k], At[m][k], acc[ai][bj][m][n], 0, 0, 0); __builtin_amdgcn_s_setprio(0); } while (0)
; #define PG8_WAIT_V(n) asm volatile("s_waitcnt vmcnt(" #n ")" ::: "memory")
; #define PG8_WAIT_L(n) asm volatile("s_waitcnt lgkmcnt(" #n ")" ::: "memory")
; #define PG8_BAR __builtin_amdgcn_s_barrier()
; #define PG8_SCHED __builtin_amdgcn_sched_barrier(0)
; template <class Epi>
; __device__ __forceinline__ void gemm_phase(LAS unsigned char* lds, const Gemm g, const StaticOrder& S, const Epi& E) {
;     ...
;             PG8_WAIT_V(6); PG8_BAR; PG8_MMA(1, 1, At, B1); PG8_BAR;
;             PG8_LDB(B0, 1, 0); PG8_SCHED; PG8_LDA(At, 1, 0); PG8_STAGE(PG8_SA(0, 1), a2 + hstepA, voffA);
;             PG8_WAIT_L(8); PG8_BAR; PG8_WAIT_L(0); PG8_MMA(0, 0, At, B0); PG8_BAR; PG8_SCHED;
;             PG8_LDB(B1, 1, 1); PG8_STAGE(PG8_SB(1, 0), b3, voffB);
;             PG8_BAR; PG8_WAIT_L(0); PG8_MMA(0, 1, At, B1); PG8_BAR;
;             PG8_LDA(At, 1, 1); PG8_STAGE(PG8_SA(1, 0), a3, voffA);
;             PG8_BAR; PG8_WAIT_L(0); PG8_MMA(1, 0, At, B0); PG8_BAR; PG8_SCHED;
	s_add_u32 s38, s4, 0x80000
	s_addc_u32 s39, s5, 0
	s_add_i32 s60, s61, s45
	v_lshl_add_u64 v[146:147], s[38:39], 0, v[134:135]
	s_mov_b32 m0, s60
	s_nop 0
	global_load_lds_dwordx4 v[146:147], off
	v_lshl_add_u64 v[146:147], s[38:39], 0, v[130:131]
	s_add_i32 m0, s60, 0x2000
	s_nop 0
	global_load_lds_dwordx4 v[146:147], off
	s_waitcnt vmcnt(6)
	s_barrier
	v_mfma_f32_16x16x32_bf16 v[54:57], v[216:219], v[174:177], v[54:57]
	v_mfma_f32_16x16x32_bf16 v[50:53], v[224:227], v[174:177], v[50:53]
	v_mfma_f32_16x16x32_bf16 v[38:41], v[216:219], v[192:195], v[38:41]
	v_mfma_f32_16x16x32_bf16 v[34:37], v[224:227], v[192:195], v[34:37]
	v_mfma_f32_16x16x32_bf16 v[22:25], v[216:219], v[200:203], v[22:25]
	v_mfma_f32_16x16x32_bf16 v[18:21], v[224:227], v[200:203], v[18:21]
	v_mfma_f32_16x16x32_bf16 v[6:9], v[216:219], v[208:211], v[6:9]
	v_mfma_f32_16x16x32_bf16 v[2:5], v[224:227], v[208:211], v[2:5]
	v_mfma_f32_16x16x32_bf16 v[54:57], v[220:223], v[188:191], v[54:57]
	v_mfma_f32_16x16x32_bf16 v[50:53], v[228:231], v[188:191], v[50:53]
	v_mfma_f32_16x16x32_bf16 v[38:41], v[220:223], v[196:199], v[38:41]
	v_mfma_f32_16x16x32_bf16 v[34:37], v[228:231], v[196:199], v[34:37]
	v_mfma_f32_16x16x32_bf16 v[22:25], v[220:223], v[204:207], v[22:25]
	v_mfma_f32_16x16x32_bf16 v[18:21], v[228:231], v[204:207], v[18:21]
	v_mfma_f32_16x16x32_bf16 v[6:9], v[220:223], v[212:215], v[6:9]
	v_mfma_f32_16x16x32_bf16 v[2:5], v[228:231], v[212:215], v[2:5]
	s_add_i32 s38, 0, 0x18000
	v_add_u32_e32 v0, s38, v152
	s_barrier
	ds_read_b128 v[146:149], v0
	ds_read_b128 v[162:165], v0 offset:1024
	ds_read_b128 v[166:169], v0 offset:2048
	ds_read_b128 v[170:173], v0 offset:3072
	s_add_u32 s24, s24, 0x80000
	s_addc_u32 s25, s25, 0
	s_mov_b32 m0, s48
	v_lshl_add_u64 v[216:217], s[24:25], 0, v[136:137]
	ds_read_b128 v[174:177], v154 offset:32768
	ds_read_b128 v[188:191], v154 offset:33792
	ds_read_b128 v[192:195], v154 offset:34816
	ds_read_b128 v[196:199], v154 offset:35840
	ds_read_b128 v[200:203], v154 offset:36864
	ds_read_b128 v[204:207], v154 offset:37888
	ds_read_b128 v[208:211], v154 offset:38912
	ds_read_b128 v[212:215], v154 offset:39936
	global_load_lds_dwordx4 v[216:217], off
	v_lshl_add_u64 v[216:217], s[24:25], 0, v[132:133]
	s_mov_b32 m0, s49
	s_nop 0
	global_load_lds_dwordx4 v[216:217], off
	s_waitcnt lgkmcnt(8)
	s_barrier
	s_waitcnt lgkmcnt(0)
	s_waitcnt lgkmcnt(0)
	v_mfma_f32_16x16x32_bf16 v[126:129], v[146:149], v[174:177], v[126:129]
	v_mfma_f32_16x16x32_bf16 v[122:125], v[166:169], v[174:177], v[122:125]
	v_mfma_f32_16x16x32_bf16 v[110:113], v[146:149], v[192:195], v[110:113]
	v_mfma_f32_16x16x32_bf16 v[106:109], v[166:169], v[192:195], v[106:109]
	v_mfma_f32_16x16x32_bf16 v[94:97], v[146:149], v[200:203], v[94:97]
	v_mfma_f32_16x16x32_bf16 v[90:93], v[166:169], v[200:203], v[90:93]
	v_mfma_f32_16x16x32_bf16 v[78:81], v[146:149], v[208:211], v[78:81]
	v_mfma_f32_16x16x32_bf16 v[74:77], v[166:169], v[208:211], v[74:77]
	v_mfma_f32_16x16x32_bf16 v[126:129], v[162:165], v[188:191], v[126:129]
	v_mfma_f32_16x16x32_bf16 v[122:125], v[170:173], v[188:191], v[122:125]
	v_mfma_f32_16x16x32_bf16 v[110:113], v[162:165], v[196:199], v[110:113]
	v_mfma_f32_16x16x32_bf16 v[106:109], v[170:173], v[196:199], v[106:109]
	v_mfma_f32_16x16x32_bf16 v[94:97], v[162:165], v[204:207], v[94:97]
	v_mfma_f32_16x16x32_bf16 v[90:93], v[170:173], v[204:207], v[90:93]
	v_mfma_f32_16x16x32_bf16 v[78:81], v[162:165], v[212:215], v[78:81]
	v_mfma_f32_16x16x32_bf16 v[74:77], v[170:173], v[212:215], v[74:77]
	s_barrier
	s_add_i32 s24, 0, 0x1c000
	s_add_i32 s25, s38, s45
	v_add_u32_e32 v0, s24, v152
	v_lshl_add_u64 v[150:151], v[150:151], 0, s[6:7]
	s_mov_b32 m0, s25
	ds_read_b128 v[216:219], v0
	ds_read_b128 v[220:223], v0 offset:1024
	ds_read_b128 v[224:227], v0 offset:2048
	ds_read_b128 v[228:231], v0 offset:3072
	global_load_lds_dwordx4 v[150:151], off
	v_lshl_add_u64 v[150:151], v[184:185], 0, s[6:7]
	s_add_i32 m0, s25, 0x2000
	s_nop 0
	global_load_lds_dwordx4 v[150:151], off
	s_barrier
	s_waitcnt lgkmcnt(0)
	s_waitcnt lgkmcnt(0)
	v_mfma_f32_16x16x32_bf16 v[118:121], v[216:219], v[174:177], v[118:121]
	v_mfma_f32_16x16x32_bf16 v[114:117], v[224:227], v[174:177], v[114:117]
	v_mfma_f32_16x16x32_bf16 v[102:105], v[216:219], v[192:195], v[102:105]
	v_mfma_f32_16x16x32_bf16 v[98:101], v[224:227], v[192:195], v[98:101]
	v_mfma_f32_16x16x32_bf16 v[86:89], v[216:219], v[200:203], v[86:89]
	v_mfma_f32_16x16x32_bf16 v[82:85], v[224:227], v[200:203], v[82:85]
	v_mfma_f32_16x16x32_bf16 v[70:73], v[216:219], v[208:211], v[70:73]
	v_mfma_f32_16x16x32_bf16 v[66:69], v[224:227], v[208:211], v[66:69]
	v_mfma_f32_16x16x32_bf16 v[118:121], v[220:223], v[188:191], v[118:121]
	v_mfma_f32_16x16x32_bf16 v[114:117], v[228:231], v[188:191], v[114:117]
	v_mfma_f32_16x16x32_bf16 v[102:105], v[220:223], v[196:199], v[102:105]
	v_mfma_f32_16x16x32_bf16 v[98:101], v[228:231], v[196:199], v[98:101]
	v_mfma_f32_16x16x32_bf16 v[86:89], v[220:223], v[204:207], v[86:89]
	v_mfma_f32_16x16x32_bf16 v[82:85], v[228:231], v[204:207], v[82:85]
	v_mfma_f32_16x16x32_bf16 v[70:73], v[220:223], v[212:215], v[70:73]
	v_mfma_f32_16x16x32_bf16 v[66:69], v[228:231], v[212:215], v[66:69]
	s_mov_b32 m0, s50
	v_lshl_add_u64 v[150:151], v[186:187], 0, s[6:7]
	s_barrier
; __device__ __forceinline__ unsigned cvt_pk_bf16(float lo, float hi) { unsigned r; asm volatile("v_cvt_pk_bf16_f32 %0, %1, %2" : "=v"(r) : "v"(lo), "v"(hi)); return r; }
; #define PG8_STAGE(bufoff, gbase, voff) do { _Pragma("unroll") for (int _i = 0; _i < 2; ++_i) \
;         __builtin_amdgcn_global_load_lds((const unsigned*)((const char*)(gbase) + (voff)[_i]), (LAS unsigned*)(lds + (bufoff) + ldsw + _i * 8192), 16, 0, 0); } while (0)
; #define PG8_MMA(ai, bj, At, Bt) do { __builtin_amdgcn_s_setprio(1); _Pragma("unroll") for (int m = 0; m < 4; ++m) _Pragma("unroll") for (int n = 0; n < 2; ++n) _Pragma("unroll") for (int k = 0; k < 2; ++k) \
;         acc[ai][bj][m][n] = __builtin_amdgcn_mfma_f32_16x16x32_bf16(Bt[n][k], At[m][k], acc[ai][bj][m][n], 0, 0, 0); __builtin_amdgcn_s_setprio(0); } while (0)
; #define PG8_WAIT_V(n) asm volatile("s_waitcnt vmcnt(" #n ")" ::: "memory")
; #define PG8_WAIT_L(n) asm volatile("s_waitcnt lgkmcnt(" #n ")" ::: "memory")
; #define PG8_BAR __builtin_amdgcn_s_barrier()
; #define PG8_SCHED __builtin_amdgcn_sched_barrier(0)
; template <class Epi>
; __device__ __forceinline__ void gemm_phase(LAS unsigned char* lds, const Gemm g, const StaticOrder& S, const Epi& E) {
;     ...
;             PG8_BAR; PG8_WAIT_L(0); PG8_MMA(1, 0, At, B0); PG8_BAR; PG8_SCHED;
;             PG8_STAGE(PG8_SB(1, 1), b3 + hstepB, voffB);
;             PG8_WAIT_V(6); PG8_BAR; PG8_MMA(1, 1, At, B1); PG8_BAR;
;     __device__ __forceinline__ void operator()(const f32x4 (&acc)[2][2][4][2], const Unit& u, int wr, int wc, int fr, int fq, const Pre& pp) const {
;     ...
;             for (int m = 0; m < 4; ++m) { const int r = row0 + ai * HALF + m * 16; const float inv = rsqrtf(rs[ai * 4 + m] * (1.0f / DM) + EPS);
; #pragma unroll
;                 for (int bj = 0; bj < 2; ++bj) { const f32x4 v0 = acc[ai][bj][m][0] * inv, v1 = acc[ai][bj][m][1] * inv; const int c = col0 + bj * HALF;
;                     u32x4 w; w.x = cvt_pk_bf16(v0[0], v0[1]); w.y = cvt_pk_bf16(v0[2], v0[3]); w.z = cvt_pk_bf16(v1[0], v1[1]); w.w = cvt_pk_bf16(v1[2], v1[3]);
;                     bf16_t* dst = gm ? UG + (size_t)(c >> 4) * GSTR + r * 16 + (c & 15) : O + (size_t)r * DE2 + c;
;                     *(u32x4*)dst = w; } }
	ds_read_b128 v[174:177], v154 offset:49152
	ds_read_b128 v[188:191], v154 offset:50176
	ds_read_b128 v[192:195], v154 offset:51200
	ds_read_b128 v[196:199], v154 offset:52224
	ds_read_b128 v[200:203], v154 offset:53248
	ds_read_b128 v[204:207], v154 offset:54272
	ds_read_b128 v[208:211], v154 offset:55296
	ds_read_b128 v[212:215], v154 offset:56320
	global_load_lds_dwordx4 v[150:151], off
	v_lshl_add_u64 v[150:151], v[244:245], 0, s[6:7]
	s_mov_b32 m0, s51
	s_nop 0
	global_load_lds_dwordx4 v[150:151], off
	s_barrier
	s_waitcnt lgkmcnt(0)
	s_waitcnt lgkmcnt(0)
	v_mfma_f32_16x16x32_bf16 v[62:65], v[146:149], v[174:177], v[62:65]
	v_mfma_f32_16x16x32_bf16 v[58:61], v[166:169], v[174:177], v[58:61]
	v_mfma_f32_16x16x32_bf16 v[46:49], v[146:149], v[192:195], v[46:49]
	v_mfma_f32_16x16x32_bf16 v[42:45], v[166:169], v[192:195], v[42:45]
	v_mfma_f32_16x16x32_bf16 v[30:33], v[146:149], v[200:203], v[30:33]
	v_mfma_f32_16x16x32_bf16 v[26:29], v[166:169], v[200:203], v[26:29]
	v_mfma_f32_16x16x32_bf16 v[14:17], v[146:149], v[208:211], v[14:17]
	v_mfma_f32_16x16x32_bf16 v[10:13], v[166:169], v[208:211], v[10:13]
	v_mfma_f32_16x16x32_bf16 v[62:65], v[162:165], v[188:191], v[62:65]
	v_mfma_f32_16x16x32_bf16 v[58:61], v[170:173], v[188:191], v[58:61]
	v_mfma_f32_16x16x32_bf16 v[46:49], v[162:165], v[196:199], v[46:49]
	v_mfma_f32_16x16x32_bf16 v[42:45], v[170:173], v[196:199], v[42:45]
	v_mfma_f32_16x16x32_bf16 v[30:33], v[162:165], v[204:207], v[30:33]
	v_mfma_f32_16x16x32_bf16 v[26:29], v[170:173], v[204:207], v[26:29]
	v_mfma_f32_16x16x32_bf16 v[14:17], v[162:165], v[212:215], v[14:17]
	v_mfma_f32_16x16x32_bf16 v[10:13], v[170:173], v[212:215], v[10:13]
	s_barrier
	s_add_u32 s4, s4, 0x80080
	s_addc_u32 s5, s5, 0
	s_add_i32 s24, s24, s45
	v_lshl_add_u64 v[146:147], s[4:5], 0, v[134:135]
	s_mov_b32 m0, s24
	s_nop 0
	global_load_lds_dwordx4 v[146:147], off
	v_lshl_add_u64 v[146:147], s[4:5], 0, v[130:131]
	s_add_i32 m0, s24, 0x2000
	s_nop 0
	global_load_lds_dwordx4 v[146:147], off
	s_waitcnt vmcnt(6)
	s_barrier
	v_mfma_f32_16x16x32_bf16 v[54:57], v[216:219], v[174:177], v[54:57]
	v_mfma_f32_16x16x32_bf16 v[50:53], v[224:227], v[174:177], v[50:53]
	v_mfma_f32_16x16x32_bf16 v[38:41], v[216:219], v[192:195], v[38:41]
	v_mfma_f32_16x16x32_bf16 v[34:37], v[224:227], v[192:195], v[34:37]
	v_mfma_f32_16x16x32_bf16 v[22:25], v[216:219], v[200:203], v[22:25]
	v_mfma_f32_16x16x32_bf16 v[18:21], v[224:227], v[200:203], v[18:21]
	v_mfma_f32_16x16x32_bf16 v[6:9], v[216:219], v[208:211], v[6:9]
	v_mfma_f32_16x16x32_bf16 v[2:5], v[224:227], v[208:211], v[2:5]
	v_mfma_f32_16x16x32_bf16 v[54:57], v[220:223], v[188:191], v[54:57]
	v_mfma_f32_16x16x32_bf16 v[50:53], v[228:231], v[188:191], v[50:53]
	v_mfma_f32_16x16x32_bf16 v[38:41], v[220:223], v[196:199], v[38:41]
	v_mfma_f32_16x16x32_bf16 v[34:37], v[228:231], v[196:199], v[34:37]
	v_mfma_f32_16x16x32_bf16 v[22:25], v[220:223], v[204:207], v[22:25]
	v_mfma_f32_16x16x32_bf16 v[18:21], v[228:231], v[204:207], v[18:21]
	v_mfma_f32_16x16x32_bf16 v[6:9], v[220:223], v[212:215], v[6:9]
	v_mfma_f32_16x16x32_bf16 v[2:5], v[228:231], v[212:215], v[2:5]
	s_add_i32 s59, s59, 2
	s_add_u32 s57, s57, 0x100
	s_addc_u32 s58, s58, 0
	s_cmp_gt_u32 s59, 29
	s_mov_b64 s[38:39], s[42:43]
	s_barrier
	s_cbranch_scc0 .LBB0_158
	v_fmamk_f32 v0, v145, 0x3a000000, v233
	v_cmp_gt_f32_e32 vcc, s66, v0
	v_mul_f32_e32 v145, 0x4b800000, v0
	v_readlane_b32 s38, v254, 47
	v_cndmask_b32_e32 v0, v0, v145, vcc
	v_rsq_f32_e32 v0, v0
	v_lshl_add_u32 v146, s54, 8, v139
	s_cmp_gt_i32 s53, 15
	v_readlane_b32 s39, v254, 48
	v_mul_f32_e32 v145, 0x45800000, v0
	s_cselect_b64 s[4:5], -1, 0
	s_xor_b64 s[38:39], s[38:39], -1
	v_cndmask_b32_e32 v148, v0, v145, vcc
	v_ashrrev_i32_e32 v147, 31, v146
	s_or_b64 s[4:5], s[38:39], s[4:5]
	v_lshl_or_b32 v144, s53, 8, v153
	v_lshlrev_b64 v[150:151], 14, v[146:147]
	v_pk_mul_f32 v[128:129], v[148:149], v[128:129] op_sel_hi:[0,1]
	s_mov_b64 s[24:25], -1
	v_pk_mul_f32 v[126:127], v[148:149], v[126:127] op_sel_hi:[0,1]
	v_pk_mul_f32 v[162:163], v[148:149], v[124:125] op_sel_hi:[0,1]
	v_pk_mul_f32 v[124:125], v[148:149], v[122:123] op_sel_hi:[0,1]
	v_cvt_pk_bf16_f32 v122, v126, v127
	v_cvt_pk_bf16_f32 v123, v128, v129
	s_and_b64 vcc, exec, s[4:5]
	v_lshl_add_u64 v[128:129], s[16:17], 0, v[150:151]
	v_ashrrev_i32_e32 v145, 31, v144
	v_cvt_pk_bf16_f32 v124, v124, v125
	v_cvt_pk_bf16_f32 v125, v162, v163
	s_cbranch_vccz .LBB0_161
	v_lshl_add_u64 v[150:151], v[144:145], 1, v[128:129]
	s_mov_b64 s[24:25], 0

; #define PG8_STAGE(bufoff, gbase, voff) do { _Pragma("unroll") for (int _i = 0; _i < 2; ++_i) \
;         __builtin_amdgcn_global_load_lds((const unsigned*)((const char*)(gbase) + (voff)[_i]), (LAS unsigned*)(lds + (bufoff) + ldsw + _i * 8192), 16, 0, 0); } while (0)
; #define PG8_LDA(dst, b, h) do { _Pragma("unroll") for (int m = 0; m < 4; ++m) _Pragma("unroll") for (int k = 0; k < 2; ++k) dst[m][k] = *(const LAS bf16x8*)(lds + PG8_SA(b, h) + aoff + m * 2048 + k * 1024); } while (0)
; #define PG8_LDB(dst, b, h) do { _Pragma("unroll") for (int n = 0; n < 2; ++n) _Pragma("unroll") for (int k = 0; k < 2; ++k) dst[n][k] = *(const LAS bf16x8*)(lds + PG8_SB(b, h) + boff + n * 2048 + k * 1024); } while (0)
; #define PG8_MMA(ai, bj, At, Bt) do { __builtin_amdgcn_s_setprio(1); _Pragma("unroll") for (int m = 0; m < 4; ++m) _Pragma("unroll") for (int n = 0; n < 2; ++n) _Pragma("unroll") for (int k = 0; k < 2; ++k) \
;         acc[ai][bj][m][n] = __builtin_amdgcn_mfma_f32_16x16x32_bf16(Bt[n][k], At[m][k], acc[ai][bj][m][n], 0, 0, 0); __builtin_amdgcn_s_setprio(0); } while (0)
; #define PG8_WAIT_V(n) asm volatile("s_waitcnt vmcnt(" #n ")" ::: "memory")
; #define PG8_WAIT_L(n) asm volatile("s_waitcnt lgkmcnt(" #n ")" ::: "memory")
; #define PG8_BAR __builtin_amdgcn_s_barrier()
; #define PG8_SCHED __builtin_amdgcn_sched_barrier(0)
; template <class Epi>
; __device__ __forceinline__ void gemm_phase(LAS unsigned char* lds, const Gemm g, const StaticOrder& S, const Epi& E) {
;     ...
;             PG8_LDB(B0, 0, 0); PG8_SCHED; PG8_LDA(At, 0, 0); PG8_STAGE(PG8_SA(1, 1), a1 + hstepA, voffA);
;             PG8_WAIT_L(8); PG8_BAR; PG8_WAIT_L(0); PG8_MMA(0, 0, At, B0); PG8_BAR; PG8_SCHED;
;             PG8_LDB(B1, 0, 1); PG8_STAGE(PG8_SB(0, 0), b2, voffB);
;             PG8_BAR; PG8_WAIT_L(0); PG8_MMA(0, 1, At, B1); PG8_BAR;
;             PG8_LDA(At, 0, 1); PG8_STAGE(PG8_SA(0, 0), a2, voffA);
;             PG8_BAR; PG8_WAIT_L(0); PG8_MMA(1, 0, At, B0); PG8_BAR; PG8_SCHED;
;             PG8_STAGE(PG8_SB(0, 1), b2 + hstepB, voffB);
;             PG8_WAIT_V(6); PG8_BAR; PG8_MMA(1, 1, At, B1); PG8_BAR;
.LBB0_359:
	s_add_u32 s26, s22, 0x100
	s_addc_u32 s27, s23, 0
	s_add_i32 s65, 0, 0x10000
	v_add_u32_e32 v86, s65, v209
	ds_read_b128 v[70:73], v86
	ds_read_b128 v[74:77], v86 offset:1024
	ds_read_b128 v[82:85], v86 offset:2048
	ds_read_b128 v[86:89], v86 offset:3072
	s_cmp_eq_u32 s64, 60
	s_cselect_b32 s25, s17, s27
	s_cselect_b32 s24, s60, s26
	s_cselect_b32 s37, s15, s63
	s_cselect_b32 s36, s61, s62
	v_lshl_add_u64 v[194:195], s[22:23], 0, v[190:191]
	s_add_i32 m0, s53, 0xc000
	ds_read_b128 v[146:149], v211
	ds_read_b128 v[150:153], v211 offset:1024
	ds_read_b128 v[154:157], v211 offset:2048
	ds_read_b128 v[158:161], v211 offset:3072
	ds_read_b128 v[162:165], v211 offset:4096
	ds_read_b128 v[166:169], v211 offset:5120
	ds_read_b128 v[170:173], v211 offset:6144
	ds_read_b128 v[184:187], v211 offset:7168
	global_load_lds_dwordx4 v[194:195], off
	v_lshl_add_u64 v[194:195], s[22:23], 0, v[192:193]
	s_add_i32 m0, s53, 0xe000
	s_nop 0
	global_load_lds_dwordx4 v[194:195], off
	s_waitcnt lgkmcnt(8)
	s_barrier
	s_waitcnt lgkmcnt(0)
	s_waitcnt lgkmcnt(0)
	v_mfma_f32_16x16x32_bf16 v[142:145], v[70:73], v[146:149], v[142:145]
	v_mfma_f32_16x16x32_bf16 v[138:141], v[82:85], v[146:149], v[138:141]
	v_mfma_f32_16x16x32_bf16 v[126:129], v[70:73], v[154:157], v[126:129]
	v_mfma_f32_16x16x32_bf16 v[122:125], v[82:85], v[154:157], v[122:125]
	v_mfma_f32_16x16x32_bf16 v[110:113], v[70:73], v[162:165], v[110:113]
	v_mfma_f32_16x16x32_bf16 v[106:109], v[82:85], v[162:165], v[106:109]
	v_mfma_f32_16x16x32_bf16 v[94:97], v[70:73], v[170:173], v[94:97]
	v_mfma_f32_16x16x32_bf16 v[90:93], v[82:85], v[170:173], v[90:93]
	v_mfma_f32_16x16x32_bf16 v[142:145], v[74:77], v[150:153], v[142:145]
	v_mfma_f32_16x16x32_bf16 v[138:141], v[86:89], v[150:153], v[138:141]
	v_mfma_f32_16x16x32_bf16 v[126:129], v[74:77], v[158:161], v[126:129]
	v_mfma_f32_16x16x32_bf16 v[122:125], v[86:89], v[158:161], v[122:125]
	v_mfma_f32_16x16x32_bf16 v[110:113], v[74:77], v[166:169], v[110:113]
	v_mfma_f32_16x16x32_bf16 v[106:109], v[86:89], v[166:169], v[106:109]
	v_mfma_f32_16x16x32_bf16 v[94:97], v[74:77], v[184:187], v[94:97]
	v_mfma_f32_16x16x32_bf16 v[90:93], v[86:89], v[184:187], v[90:93]
	s_barrier
	s_add_i32 s66, 0, 0x14000
	v_add_u32_e32 v206, s66, v209
	s_add_i32 s22, s65, s52
	ds_read_b128 v[194:197], v206
	ds_read_b128 v[198:201], v206 offset:1024
	ds_read_b128 v[202:205], v206 offset:2048
	ds_read_b128 v[212:215], v206 offset:3072
	v_lshl_add_u64 v[206:207], s[36:37], 0, v[0:1]
	s_mov_b32 m0, s22
	v_lshl_add_u64 v[216:217], s[36:37], 0, v[174:175]
	global_load_lds_dwordx4 v[206:207], off
	s_add_i32 m0, s22, 0x2000
	s_nop 0
	global_load_lds_dwordx4 v[216:217], off
	s_barrier
	s_waitcnt lgkmcnt(0)
	s_waitcnt lgkmcnt(0)
	v_mfma_f32_16x16x32_bf16 v[134:137], v[194:197], v[146:149], v[134:137]
	v_mfma_f32_16x16x32_bf16 v[130:133], v[202:205], v[146:149], v[130:133]
	v_mfma_f32_16x16x32_bf16 v[118:121], v[194:197], v[154:157], v[118:121]
	v_mfma_f32_16x16x32_bf16 v[114:117], v[202:205], v[154:157], v[114:117]
	v_mfma_f32_16x16x32_bf16 v[102:105], v[194:197], v[162:165], v[102:105]
	v_mfma_f32_16x16x32_bf16 v[98:101], v[202:205], v[162:165], v[98:101]
	v_mfma_f32_16x16x32_bf16 v[78:81], v[194:197], v[170:173], v[78:81]
	v_mfma_f32_16x16x32_bf16 v[66:69], v[202:205], v[170:173], v[66:69]
	v_mfma_f32_16x16x32_bf16 v[134:137], v[198:201], v[150:153], v[134:137]
	v_mfma_f32_16x16x32_bf16 v[130:133], v[212:215], v[150:153], v[130:133]
	v_mfma_f32_16x16x32_bf16 v[118:121], v[198:201], v[158:161], v[118:121]
	v_mfma_f32_16x16x32_bf16 v[114:117], v[212:215], v[158:161], v[114:117]
	v_mfma_f32_16x16x32_bf16 v[102:105], v[198:201], v[166:169], v[102:105]
	v_mfma_f32_16x16x32_bf16 v[98:101], v[212:215], v[166:169], v[98:101]
	v_mfma_f32_16x16x32_bf16 v[78:81], v[198:201], v[184:187], v[78:81]
	v_mfma_f32_16x16x32_bf16 v[66:69], v[212:215], v[184:187], v[66:69]
	s_mov_b32 m0, s53
	v_lshl_add_u64 v[218:219], s[24:25], 0, v[188:189]
	s_barrier
	ds_read_b128 v[146:149], v211 offset:16384
	ds_read_b128 v[150:153], v211 offset:17408
	ds_read_b128 v[154:157], v211 offset:18432
	ds_read_b128 v[158:161], v211 offset:19456
	ds_read_b128 v[162:165], v211 offset:20480
	ds_read_b128 v[166:169], v211 offset:21504
	ds_read_b128 v[170:173], v211 offset:22528
	ds_read_b128 v[184:187], v211 offset:23552
	global_load_lds_dwordx4 v[218:219], off
	v_lshl_add_u64 v[220:221], s[24:25], 0, v[176:177]
	s_mov_b32 m0, s54
	s_nop 0
	global_load_lds_dwordx4 v[220:221], off
	s_barrier
	s_waitcnt lgkmcnt(0)
	s_waitcnt lgkmcnt(0)
	v_mfma_f32_16x16x32_bf16 v[62:65], v[70:73], v[146:149], v[62:65]
	v_mfma_f32_16x16x32_bf16 v[58:61], v[82:85], v[146:149], v[58:61]
	v_mfma_f32_16x16x32_bf16 v[46:49], v[70:73], v[154:157], v[46:49]
	v_mfma_f32_16x16x32_bf16 v[42:45], v[82:85], v[154:157], v[42:45]
	v_mfma_f32_16x16x32_bf16 v[30:33], v[70:73], v[162:165], v[30:33]
	v_mfma_f32_16x16x32_bf16 v[26:29], v[82:85], v[162:165], v[26:29]
	v_mfma_f32_16x16x32_bf16 v[14:17], v[70:73], v[170:173], v[14:17]
	v_mfma_f32_16x16x32_bf16 v[10:13], v[82:85], v[170:173], v[10:13]
	v_mfma_f32_16x16x32_bf16 v[62:65], v[74:77], v[150:153], v[62:65]
	v_mfma_f32_16x16x32_bf16 v[58:61], v[86:89], v[150:153], v[58:61]
	v_mfma_f32_16x16x32_bf16 v[46:49], v[74:77], v[158:161], v[46:49]
	v_mfma_f32_16x16x32_bf16 v[42:45], v[86:89], v[158:161], v[42:45]
	v_mfma_f32_16x16x32_bf16 v[30:33], v[74:77], v[166:169], v[30:33]
	v_mfma_f32_16x16x32_bf16 v[26:29], v[86:89], v[166:169], v[26:29]
	v_mfma_f32_16x16x32_bf16 v[14:17], v[74:77], v[184:187], v[14:17]
	v_mfma_f32_16x16x32_bf16 v[10:13], v[86:89], v[184:187], v[10:13]
	s_barrier
; #define PG8_STAGE(bufoff, gbase, voff) do { _Pragma("unroll") for (int _i = 0; _i < 2; ++_i) \
;         __builtin_amdgcn_global_load_lds((const unsigned*)((const char*)(gbase) + (voff)[_i]), (LAS unsigned*)(lds + (bufoff) + ldsw + _i * 8192), 16, 0, 0); } while (0)
; #define PG8_LDA(dst, b, h) do { _Pragma("unroll") for (int m = 0; m < 4; ++m) _Pragma("unroll") for (int k = 0; k < 2; ++k) dst[m][k] = *(const LAS bf16x8*)(lds + PG8_SA(b, h) + aoff + m * 2048 + k * 1024); } while (0)
; #define PG8_LDB(dst, b, h) do { _Pragma("unroll") for (int n = 0; n < 2; ++n) _Pragma("unroll") for (int k = 0; k < 2; ++k) dst[n][k] = *(const LAS bf16x8*)(lds + PG8_SB(b, h) + boff + n * 2048 + k * 1024); } while (0)
; #define PG8_MMA(ai, bj, At, Bt) do { __builtin_amdgcn_s_setprio(1); _Pragma("unroll") for (int m = 0; m < 4; ++m) _Pragma("unroll") for (int n = 0; n < 2; ++n) _Pragma("unroll") for (int k = 0; k < 2; ++k) \
;         acc[ai][bj][m][n] = __builtin_amdgcn_mfma_f32_16x16x32_bf16(Bt[n][k], At[m][k], acc[ai][bj][m][n], 0, 0, 0); __builtin_amdgcn_s_setprio(0); } while (0)
; #define PG8_WAIT_V(n) asm volatile("s_waitcnt vmcnt(" #n ")" ::: "memory")
; #define PG8_WAIT_L(n) asm volatile("s_waitcnt lgkmcnt(" #n ")" ::: "memory")
; #define PG8_BAR __builtin_amdgcn_s_barrier()
; #define PG8_SCHED __builtin_amdgcn_sched_barrier(0)
; template <class Epi>
; __device__ __forceinline__ void gemm_phase(LAS unsigned char* lds, const Gemm g, const StaticOrder& S, const Epi& E) {
;     ...
;             PG8_WAIT_V(6); PG8_BAR; PG8_MMA(1, 1, At, B1); PG8_BAR;
;             PG8_LDB(B0, 1, 0); PG8_SCHED; PG8_LDA(At, 1, 0); PG8_STAGE(PG8_SA(0, 1), a2 + hstepA, voffA);
;             PG8_WAIT_L(8); PG8_BAR; PG8_WAIT_L(0); PG8_MMA(0, 0, At, B0); PG8_BAR; PG8_SCHED;
;             PG8_LDB(B1, 1, 1); PG8_STAGE(PG8_SB(1, 0), b3, voffB);
;             PG8_BAR; PG8_WAIT_L(0); PG8_MMA(0, 1, At, B1); PG8_BAR;
;             PG8_LDA(At, 1, 1); PG8_STAGE(PG8_SA(1, 0), a3, voffA);
;             PG8_BAR; PG8_WAIT_L(0); PG8_MMA(1, 0, At, B0); PG8_BAR; PG8_SCHED;
	s_add_u32 s22, s36, 0x100000
	s_addc_u32 s23, s37, 0
	s_add_i32 s65, s66, s52
	v_lshl_add_u64 v[70:71], s[22:23], 0, v[0:1]
	s_mov_b32 m0, s65
	s_nop 0
	global_load_lds_dwordx4 v[70:71], off
	v_lshl_add_u64 v[70:71], s[22:23], 0, v[174:175]
	s_add_i32 m0, s65, 0x2000
	s_nop 0
	global_load_lds_dwordx4 v[70:71], off
	s_waitcnt vmcnt(6)
	s_barrier
	v_mfma_f32_16x16x32_bf16 v[54:57], v[194:197], v[146:149], v[54:57]
	v_mfma_f32_16x16x32_bf16 v[50:53], v[202:205], v[146:149], v[50:53]
	v_mfma_f32_16x16x32_bf16 v[38:41], v[194:197], v[154:157], v[38:41]
	v_mfma_f32_16x16x32_bf16 v[34:37], v[202:205], v[154:157], v[34:37]
	v_mfma_f32_16x16x32_bf16 v[22:25], v[194:197], v[162:165], v[22:25]
	v_mfma_f32_16x16x32_bf16 v[18:21], v[202:205], v[162:165], v[18:21]
	v_mfma_f32_16x16x32_bf16 v[6:9], v[194:197], v[170:173], v[6:9]
	v_mfma_f32_16x16x32_bf16 v[2:5], v[202:205], v[170:173], v[2:5]
	v_mfma_f32_16x16x32_bf16 v[54:57], v[198:201], v[150:153], v[54:57]
	v_mfma_f32_16x16x32_bf16 v[50:53], v[212:215], v[150:153], v[50:53]
	v_mfma_f32_16x16x32_bf16 v[38:41], v[198:201], v[158:161], v[38:41]
	v_mfma_f32_16x16x32_bf16 v[34:37], v[212:215], v[158:161], v[34:37]
	v_mfma_f32_16x16x32_bf16 v[22:25], v[198:201], v[166:169], v[22:25]
	v_mfma_f32_16x16x32_bf16 v[18:21], v[212:215], v[166:169], v[18:21]
	v_mfma_f32_16x16x32_bf16 v[6:9], v[198:201], v[184:187], v[6:9]
	v_mfma_f32_16x16x32_bf16 v[2:5], v[212:215], v[184:187], v[2:5]
	s_add_i32 s65, 0, 0x18000
	v_add_u32_e32 v86, s65, v209
	s_barrier
	ds_read_b128 v[70:73], v86
	ds_read_b128 v[74:77], v86 offset:1024
	ds_read_b128 v[82:85], v86 offset:2048
	ds_read_b128 v[86:89], v86 offset:3072
	s_add_u32 s22, s24, 0x100000
	s_addc_u32 s23, s25, 0
	s_mov_b32 m0, s55
	v_lshl_add_u64 v[194:195], s[22:23], 0, v[188:189]
	ds_read_b128 v[146:149], v211 offset:32768
	ds_read_b128 v[150:153], v211 offset:33792
	ds_read_b128 v[154:157], v211 offset:34816
	ds_read_b128 v[158:161], v211 offset:35840
	ds_read_b128 v[162:165], v211 offset:36864
	ds_read_b128 v[166:169], v211 offset:37888
	ds_read_b128 v[170:173], v211 offset:38912
	ds_read_b128 v[184:187], v211 offset:39936
	global_load_lds_dwordx4 v[194:195], off
	v_lshl_add_u64 v[194:195], s[22:23], 0, v[176:177]
	s_mov_b32 m0, s56
	s_nop 0
	global_load_lds_dwordx4 v[194:195], off
	s_waitcnt lgkmcnt(8)
	s_barrier
	s_waitcnt lgkmcnt(0)
	s_waitcnt lgkmcnt(0)
	v_mfma_f32_16x16x32_bf16 v[142:145], v[70:73], v[146:149], v[142:145]
	v_mfma_f32_16x16x32_bf16 v[138:141], v[82:85], v[146:149], v[138:141]
	v_mfma_f32_16x16x32_bf16 v[126:129], v[70:73], v[154:157], v[126:129]
	v_mfma_f32_16x16x32_bf16 v[122:125], v[82:85], v[154:157], v[122:125]
	v_mfma_f32_16x16x32_bf16 v[110:113], v[70:73], v[162:165], v[110:113]
	v_mfma_f32_16x16x32_bf16 v[106:109], v[82:85], v[162:165], v[106:109]
	v_mfma_f32_16x16x32_bf16 v[94:97], v[70:73], v[170:173], v[94:97]
	v_mfma_f32_16x16x32_bf16 v[90:93], v[82:85], v[170:173], v[90:93]
	v_mfma_f32_16x16x32_bf16 v[142:145], v[74:77], v[150:153], v[142:145]
	v_mfma_f32_16x16x32_bf16 v[138:141], v[86:89], v[150:153], v[138:141]
	v_mfma_f32_16x16x32_bf16 v[126:129], v[74:77], v[158:161], v[126:129]
	v_mfma_f32_16x16x32_bf16 v[122:125], v[86:89], v[158:161], v[122:125]
	v_mfma_f32_16x16x32_bf16 v[110:113], v[74:77], v[166:169], v[110:113]
	v_mfma_f32_16x16x32_bf16 v[106:109], v[86:89], v[166:169], v[106:109]
	v_mfma_f32_16x16x32_bf16 v[94:97], v[74:77], v[184:187], v[94:97]
	v_mfma_f32_16x16x32_bf16 v[90:93], v[86:89], v[184:187], v[90:93]
	s_barrier
	s_add_i32 s24, 0, 0x1c000
	s_add_i32 s22, s65, s52
	v_add_u32_e32 v212, s24, v209
	v_lshl_add_u64 v[206:207], v[206:207], 0, s[6:7]
	s_mov_b32 m0, s22
	ds_read_b128 v[194:197], v212
	ds_read_b128 v[198:201], v212 offset:1024
	ds_read_b128 v[202:205], v212 offset:2048
	ds_read_b128 v[212:215], v212 offset:3072
	global_load_lds_dwordx4 v[206:207], off
	v_lshl_add_u64 v[206:207], v[216:217], 0, s[6:7]
	s_add_i32 m0, s22, 0x2000
	s_nop 0
	global_load_lds_dwordx4 v[206:207], off
	s_barrier
	s_waitcnt lgkmcnt(0)
	s_waitcnt lgkmcnt(0)
	v_mfma_f32_16x16x32_bf16 v[134:137], v[194:197], v[146:149], v[134:137]
	v_mfma_f32_16x16x32_bf16 v[130:133], v[202:205], v[146:149], v[130:133]
	v_mfma_f32_16x16x32_bf16 v[118:121], v[194:197], v[154:157], v[118:121]
	v_mfma_f32_16x16x32_bf16 v[114:117], v[202:205], v[154:157], v[114:117]
	v_mfma_f32_16x16x32_bf16 v[102:105], v[194:197], v[162:165], v[102:105]
	v_mfma_f32_16x16x32_bf16 v[98:101], v[202:205], v[162:165], v[98:101]
	v_mfma_f32_16x16x32_bf16 v[78:81], v[194:197], v[170:173], v[78:81]
	v_mfma_f32_16x16x32_bf16 v[66:69], v[202:205], v[170:173], v[66:69]
	v_mfma_f32_16x16x32_bf16 v[134:137], v[198:201], v[150:153], v[134:137]
	v_mfma_f32_16x16x32_bf16 v[130:133], v[212:215], v[150:153], v[130:133]
	v_mfma_f32_16x16x32_bf16 v[118:121], v[198:201], v[158:161], v[118:121]
	v_mfma_f32_16x16x32_bf16 v[114:117], v[212:215], v[158:161], v[114:117]
	v_mfma_f32_16x16x32_bf16 v[102:105], v[198:201], v[166:169], v[102:105]
	v_mfma_f32_16x16x32_bf16 v[98:101], v[212:215], v[166:169], v[98:101]
	v_mfma_f32_16x16x32_bf16 v[78:81], v[198:201], v[184:187], v[78:81]
	v_mfma_f32_16x16x32_bf16 v[66:69], v[212:215], v[184:187], v[66:69]
	s_mov_b32 m0, s58
	v_lshl_add_u64 v[206:207], v[218:219], 0, s[6:7]
	s_barrier
; __device__ __forceinline__ unsigned cvt_pk_bf16(float lo, float hi) { unsigned r; asm volatile("v_cvt_pk_bf16_f32 %0, %1, %2" : "=v"(r) : "v"(lo), "v"(hi)); return r; }
; #define PG8_WAIT_V(n) asm volatile("s_waitcnt vmcnt(" #n ")" ::: "memory")
; template <class Epi>
; __device__ __forceinline__ void gemm_phase(LAS unsigned char* lds, const Gemm g, const StaticOrder& S, const Epi& E) {
;     ...
;             PG8_BAR; PG8_WAIT_L(0); PG8_MMA(1, 0, At, B0); PG8_BAR; PG8_SCHED;
;             PG8_STAGE(PG8_SB(1, 1), b3 + hstepB, voffB);
;             PG8_WAIT_V(6); PG8_BAR; PG8_MMA(1, 1, At, B1); PG8_BAR;
;     __device__ __forceinline__ void operator()(const f32x4 (&acc)[2][2][4][2], const Unit& u, int wr, int wc, int fr, int fq, const Pre&) const {
;         const int row0 = u.pm * BM + wr * 64 + fr, col0 = u.pn * BM + wc * 32 + 4 * fq;
;         f32x4 gv[2][2];
; #pragma unroll
;         for (int bj = 0; bj < 2; ++bj)
; #pragma unroll
;             for (int n = 0; n < 2; ++n) gv[bj][n] = *(const f32x4*)(gnext + col0 + bj * HALF + n * 16);
;         f32x4 xb[2][2][2];
; #pragma unroll
;         for (int bj = 0; bj < 2; ++bj)
; #pragma unroll
;             for (int n = 0; n < 2; ++n) xb[0][bj][n] = *(const f32x4*)(Xin + (size_t)row0 * DM + col0 + bj * HALF + n * 16);
; #pragma unroll
;         for (int grp = 0; grp < 8; ++grp) { const int ai = grp >> 2, m = grp & 3, cur = grp & 1; const int r = row0 + ai * HALF + m * 16; float ss = 0.f;
;             if (grp < 7) { const int rn = row0 + ((grp + 1) >> 2) * HALF + ((grp + 1) & 3) * 16;
; #pragma unroll
;                 for (int bj = 0; bj < 2; ++bj)
; #pragma unroll
;                     for (int n = 0; n < 2; ++n) xb[cur ^ 1][bj][n] = *(const f32x4*)(Xin + (size_t)rn * DM + col0 + bj * HALF + n * 16); }
; #pragma unroll
;             for (int bj = 0; bj < 2; ++bj)
; #pragma unroll
;                 for (int n = 0; n < 2; ++n) { const int c = col0 + bj * HALF + n * 16;
;                     const f32x4 xv = xb[cur][bj][n] + acc[ai][bj][m][n]; *(f32x4*)(X + (size_t)r * DM + c) = xv;
;                     ss += (xv[0] * xv[0] + xv[1] * xv[1]) + (xv[2] * xv[2] + xv[3] * xv[3]);
;                     if (H) { const f32x4 hv = xv * gv[bj][n]; u32x2 w; w.x = cvt_pk_bf16(hv[0], hv[1]); w.y = cvt_pk_bf16(hv[2], hv[3]);
;                         *(u32x2*)(H + (size_t)r * DM + c) = w; } }
	ds_read_b128 v[146:149], v211 offset:49152
	ds_read_b128 v[150:153], v211 offset:50176
	ds_read_b128 v[154:157], v211 offset:51200
	ds_read_b128 v[158:161], v211 offset:52224
	ds_read_b128 v[162:165], v211 offset:53248
	ds_read_b128 v[166:169], v211 offset:54272
	ds_read_b128 v[170:173], v211 offset:55296
	ds_read_b128 v[184:187], v211 offset:56320
	global_load_lds_dwordx4 v[206:207], off
	v_lshl_add_u64 v[206:207], v[220:221], 0, s[6:7]
	s_mov_b32 m0, s59
	s_nop 0
	global_load_lds_dwordx4 v[206:207], off
	s_barrier
	s_waitcnt lgkmcnt(0)
	s_waitcnt lgkmcnt(0)
	v_mfma_f32_16x16x32_bf16 v[62:65], v[70:73], v[146:149], v[62:65]
	v_mfma_f32_16x16x32_bf16 v[58:61], v[82:85], v[146:149], v[58:61]
	v_mfma_f32_16x16x32_bf16 v[46:49], v[70:73], v[154:157], v[46:49]
	v_mfma_f32_16x16x32_bf16 v[42:45], v[82:85], v[154:157], v[42:45]
	v_mfma_f32_16x16x32_bf16 v[30:33], v[70:73], v[162:165], v[30:33]
	v_mfma_f32_16x16x32_bf16 v[26:29], v[82:85], v[162:165], v[26:29]
	v_mfma_f32_16x16x32_bf16 v[14:17], v[70:73], v[170:173], v[14:17]
	v_mfma_f32_16x16x32_bf16 v[10:13], v[82:85], v[170:173], v[10:13]
	v_mfma_f32_16x16x32_bf16 v[62:65], v[74:77], v[150:153], v[62:65]
	v_mfma_f32_16x16x32_bf16 v[58:61], v[86:89], v[150:153], v[58:61]
	v_mfma_f32_16x16x32_bf16 v[46:49], v[74:77], v[158:161], v[46:49]
	v_mfma_f32_16x16x32_bf16 v[42:45], v[86:89], v[158:161], v[42:45]
	v_mfma_f32_16x16x32_bf16 v[30:33], v[74:77], v[166:169], v[30:33]
	v_mfma_f32_16x16x32_bf16 v[26:29], v[86:89], v[166:169], v[26:29]
	v_mfma_f32_16x16x32_bf16 v[14:17], v[74:77], v[184:187], v[14:17]
	v_mfma_f32_16x16x32_bf16 v[10:13], v[86:89], v[184:187], v[10:13]
	s_barrier
	s_add_u32 s22, s36, 0x100080
	s_addc_u32 s23, s37, 0
	s_add_i32 s24, s24, s52
	v_lshl_add_u64 v[70:71], s[22:23], 0, v[0:1]
	s_mov_b32 m0, s24
	s_nop 0
	global_load_lds_dwordx4 v[70:71], off
	v_lshl_add_u64 v[70:71], s[22:23], 0, v[174:175]
	s_add_i32 m0, s24, 0x2000
	s_nop 0
	global_load_lds_dwordx4 v[70:71], off
	s_waitcnt vmcnt(6)
	s_barrier
	v_mfma_f32_16x16x32_bf16 v[54:57], v[194:197], v[146:149], v[54:57]
	v_mfma_f32_16x16x32_bf16 v[50:53], v[202:205], v[146:149], v[50:53]
	v_mfma_f32_16x16x32_bf16 v[38:41], v[194:197], v[154:157], v[38:41]
	v_mfma_f32_16x16x32_bf16 v[34:37], v[202:205], v[154:157], v[34:37]
	v_mfma_f32_16x16x32_bf16 v[22:25], v[194:197], v[162:165], v[22:25]
	v_mfma_f32_16x16x32_bf16 v[18:21], v[202:205], v[162:165], v[18:21]
	v_mfma_f32_16x16x32_bf16 v[6:9], v[194:197], v[170:173], v[6:9]
	v_mfma_f32_16x16x32_bf16 v[2:5], v[202:205], v[170:173], v[2:5]
	v_mfma_f32_16x16x32_bf16 v[54:57], v[198:201], v[150:153], v[54:57]
	v_mfma_f32_16x16x32_bf16 v[50:53], v[212:215], v[150:153], v[50:53]
	v_mfma_f32_16x16x32_bf16 v[38:41], v[198:201], v[158:161], v[38:41]
	v_mfma_f32_16x16x32_bf16 v[34:37], v[212:215], v[158:161], v[34:37]
	v_mfma_f32_16x16x32_bf16 v[22:25], v[198:201], v[166:169], v[22:25]
	v_mfma_f32_16x16x32_bf16 v[18:21], v[212:215], v[166:169], v[18:21]
	v_mfma_f32_16x16x32_bf16 v[6:9], v[198:201], v[184:187], v[6:9]
	v_mfma_f32_16x16x32_bf16 v[2:5], v[212:215], v[184:187], v[2:5]
	s_add_i32 s64, s64, 2
	s_add_u32 s62, s62, 0x100
	s_addc_u32 s63, s63, 0
	s_cmp_gt_u32 s64, 61
	s_mov_b64 s[22:23], s[26:27]
	s_barrier
	s_cbranch_scc0 .LBB0_359
	v_lshl_add_u32 v198, s44, 8, v208
	v_lshl_or_b32 v194, s45, 8, v210
	v_ashrrev_i32_e32 v199, 31, v198
	v_ashrrev_i32_e32 v195, 31, v194
	v_lshlrev_b64 v[204:205], 13, v[198:199]
	v_or_b32_e32 v202, 16, v198
	v_lshlrev_b64 v[196:197], 2, v[194:195]
	v_lshl_add_u64 v[146:147], s[0:1], 0, v[204:205]
	v_ashrrev_i32_e32 v203, 31, v202
	v_lshl_add_u64 v[70:71], s[4:5], 0, v[196:197]
	v_lshl_add_u64 v[146:147], v[146:147], 0, v[196:197]
	v_lshlrev_b64 v[200:201], 13, v[202:203]
	global_load_dwordx4 v[86:89], v[70:71], off
	global_load_dwordx4 v[82:85], v[70:71], off offset:64
	global_load_dwordx4 v[74:77], v[70:71], off offset:512
	s_nop 0
	global_load_dwordx4 v[70:73], v[70:71], off offset:576
	s_nop 0
	global_load_dwordx4 v[184:187], v[146:147], off
	global_load_dwordx4 v[170:173], v[146:147], off offset:64
	global_load_dwordx4 v[166:169], v[146:147], off offset:512
	global_load_dwordx4 v[162:165], v[146:147], off offset:576
	v_lshl_add_u64 v[146:147], s[0:1], 0, v[200:201]
	v_lshl_add_u64 v[146:147], v[146:147], 0, v[196:197]
	global_load_dwordx4 v[158:161], v[146:147], off
	global_load_dwordx4 v[154:157], v[146:147], off offset:64
	global_load_dwordx4 v[150:153], v[146:147], off offset:512
	s_nop 0
	global_load_dwordx4 v[146:149], v[146:147], off offset:576
	v_cndmask_b32_e64 v206, 0, 1, s[10:11]
	v_lshlrev_b64 v[212:213], 11, v[198:199]
	v_lshl_add_u64 v[204:205], s[48:49], 0, v[204:205]
	v_cmp_ne_u32_e64 s[44:45], 1, v206
	s_andn2_b64 vcc, exec, s[10:11]
	v_lshl_add_u64 v[206:207], v[204:205], 0, v[196:197]
	v_lshl_add_u64 v[204:205], v[212:213], 1, s[50:51]
	s_waitcnt vmcnt(0)
	v_pk_add_f32 v[144:145], v[144:145], v[186:187]
	v_pk_add_f32 v[142:143], v[142:143], v[184:185]
	global_store_dwordx4 v[206:207], v[142:145], off
	s_cbranch_vccnz .LBB0_362
	v_pk_mul_f32 v[184:185], v[88:89], v[144:145]
	v_pk_mul_f32 v[186:187], v[86:87], v[142:143]
	s_nop 0
	v_cvt_pk_bf16_f32 v186, v186, v187
	v_cvt_pk_bf16_f32 v187, v184, v185
	v_lshl_add_u64 v[184:185], v[194:195], 1, v[204:205]
	global_store_dwordx2 v[184:185], v[186:187], off

; #define PG8_STAGE(bufoff, gbase, voff) do { _Pragma("unroll") for (int _i = 0; _i < 2; ++_i) \
;         __builtin_amdgcn_global_load_lds((const unsigned*)((const char*)(gbase) + (voff)[_i]), (LAS unsigned*)(lds + (bufoff) + ldsw + _i * 8192), 16, 0, 0); } while (0)
; #define PG8_LDA(dst, b, h) do { _Pragma("unroll") for (int m = 0; m < 4; ++m) _Pragma("unroll") for (int k = 0; k < 2; ++k) dst[m][k] = *(const LAS bf16x8*)(lds + PG8_SA(b, h) + aoff + m * 2048 + k * 1024); } while (0)
; #define PG8_LDB(dst, b, h) do { _Pragma("unroll") for (int n = 0; n < 2; ++n) _Pragma("unroll") for (int k = 0; k < 2; ++k) dst[n][k] = *(const LAS bf16x8*)(lds + PG8_SB(b, h) + boff + n * 2048 + k * 1024); } while (0)
; #define PG8_MMA(ai, bj, At, Bt) do { __builtin_amdgcn_s_setprio(1); _Pragma("unroll") for (int m = 0; m < 4; ++m) _Pragma("unroll") for (int n = 0; n < 2; ++n) _Pragma("unroll") for (int k = 0; k < 2; ++k) \
;         acc[ai][bj][m][n] = __builtin_amdgcn_mfma_f32_16x16x32_bf16(Bt[n][k], At[m][k], acc[ai][bj][m][n], 0, 0, 0); __builtin_amdgcn_s_setprio(0); } while (0)
; #define PG8_WAIT_V(n) asm volatile("s_waitcnt vmcnt(" #n ")" ::: "memory")
; #define PG8_WAIT_L(n) asm volatile("s_waitcnt lgkmcnt(" #n ")" ::: "memory")
; #define PG8_BAR __builtin_amdgcn_s_barrier()
; #define PG8_SCHED __builtin_amdgcn_sched_barrier(0)
; template <class Epi>
; __device__ __forceinline__ void gemm_phase(LAS unsigned char* lds, const Gemm g, const StaticOrder& S, const Epi& E) {
;     ...
;             PG8_LDB(B0, 0, 0); PG8_SCHED; PG8_LDA(At, 0, 0); PG8_STAGE(PG8_SA(1, 1), a1 + hstepA, voffA);
;             PG8_WAIT_L(8); PG8_BAR; PG8_WAIT_L(0); PG8_MMA(0, 0, At, B0); PG8_BAR; PG8_SCHED;
;             PG8_LDB(B1, 0, 1); PG8_STAGE(PG8_SB(0, 0), b2, voffB);
;             PG8_BAR; PG8_WAIT_L(0); PG8_MMA(0, 1, At, B1); PG8_BAR;
;             PG8_LDA(At, 0, 1); PG8_STAGE(PG8_SA(0, 0), a2, voffA);
;             PG8_BAR; PG8_WAIT_L(0); PG8_MMA(1, 0, At, B0); PG8_BAR; PG8_SCHED;
;             PG8_STAGE(PG8_SB(0, 1), b2 + hstepB, voffB);
;             PG8_WAIT_V(6); PG8_BAR; PG8_MMA(1, 1, At, B1); PG8_BAR;
.LBB0_472:
	s_add_u32 s22, s4, s20
	s_addc_u32 s23, s5, s21
	s_add_u32 s22, s22, 0x100
	s_addc_u32 s23, s23, 0
	s_add_u32 s62, s17, s20
	s_addc_u32 s63, s58, s21
	s_add_i32 s64, 0, 0x10000
	v_add_u32_e32 v160, s64, v146
	ds_read_b128 v[148:151], v160
	ds_read_b128 v[152:155], v160 offset:1024
	ds_read_b128 v[156:159], v160 offset:2048
	ds_read_b128 v[160:163], v160 offset:3072
	s_cmpk_eq_i32 s20, 0x1f00
	s_cselect_b32 s25, s11, s23
	s_cselect_b32 s24, s59, s22
	s_cselect_b32 s23, s9, s63
	s_cselect_b32 s22, s60, s62
	v_lshl_add_u64 v[176:177], v[140:141], 0, s[20:21]
	s_add_i32 m0, s48, 0xc000
	ds_read_b128 v[164:167], v147
	ds_read_b128 v[168:171], v147 offset:1024
	ds_read_b128 v[172:175], v147 offset:2048
	ds_read_b128 v[184:187], v147 offset:3072
	ds_read_b128 v[188:191], v147 offset:4096
	ds_read_b128 v[192:195], v147 offset:5120
	ds_read_b128 v[196:199], v147 offset:6144
	ds_read_b128 v[200:203], v147 offset:7168
	global_load_lds_dwordx4 v[176:177], off
	v_lshl_add_u64 v[176:177], v[142:143], 0, s[20:21]
	s_add_i32 m0, s48, 0xe000
	s_nop 0
	global_load_lds_dwordx4 v[176:177], off
	s_waitcnt lgkmcnt(8)
	s_barrier
	s_waitcnt lgkmcnt(0)
	s_waitcnt lgkmcnt(0)
	v_mfma_f32_16x16x32_bf16 v[126:129], v[148:151], v[164:167], v[126:129]
	v_mfma_f32_16x16x32_bf16 v[122:125], v[156:159], v[164:167], v[122:125]
	v_mfma_f32_16x16x32_bf16 v[110:113], v[148:151], v[172:175], v[110:113]
	v_mfma_f32_16x16x32_bf16 v[106:109], v[156:159], v[172:175], v[106:109]
	v_mfma_f32_16x16x32_bf16 v[94:97], v[148:151], v[188:191], v[94:97]
	v_mfma_f32_16x16x32_bf16 v[90:93], v[156:159], v[188:191], v[90:93]
	v_mfma_f32_16x16x32_bf16 v[78:81], v[148:151], v[196:199], v[78:81]
	v_mfma_f32_16x16x32_bf16 v[74:77], v[156:159], v[196:199], v[74:77]
	v_mfma_f32_16x16x32_bf16 v[126:129], v[152:155], v[168:171], v[126:129]
	v_mfma_f32_16x16x32_bf16 v[122:125], v[160:163], v[168:171], v[122:125]
	v_mfma_f32_16x16x32_bf16 v[110:113], v[152:155], v[184:187], v[110:113]
	v_mfma_f32_16x16x32_bf16 v[106:109], v[160:163], v[184:187], v[106:109]
	v_mfma_f32_16x16x32_bf16 v[94:97], v[152:155], v[192:195], v[94:97]
	v_mfma_f32_16x16x32_bf16 v[90:93], v[160:163], v[192:195], v[90:93]
	v_mfma_f32_16x16x32_bf16 v[78:81], v[152:155], v[200:203], v[78:81]
	v_mfma_f32_16x16x32_bf16 v[74:77], v[160:163], v[200:203], v[74:77]
	s_barrier
	s_add_i32 s65, 0, 0x14000
	v_add_u32_e32 v176, s65, v146
	s_add_i32 s62, s64, s39
	ds_read_b128 v[204:207], v176
	ds_read_b128 v[208:211], v176 offset:1024
	ds_read_b128 v[212:215], v176 offset:2048
	ds_read_b128 v[216:219], v176 offset:3072
	v_lshl_add_u64 v[176:177], s[22:23], 0, v[0:1]
	s_mov_b32 m0, s62
	v_lshl_add_u64 v[220:221], s[22:23], 0, v[130:131]
	global_load_lds_dwordx4 v[176:177], off
	s_add_i32 m0, s62, 0x2000
	s_nop 0
	global_load_lds_dwordx4 v[220:221], off
	s_barrier
	s_waitcnt lgkmcnt(0)
	s_waitcnt lgkmcnt(0)
	v_mfma_f32_16x16x32_bf16 v[118:121], v[204:207], v[164:167], v[118:121]
	v_mfma_f32_16x16x32_bf16 v[114:117], v[212:215], v[164:167], v[114:117]
	v_mfma_f32_16x16x32_bf16 v[102:105], v[204:207], v[172:175], v[102:105]
	v_mfma_f32_16x16x32_bf16 v[98:101], v[212:215], v[172:175], v[98:101]
	v_mfma_f32_16x16x32_bf16 v[86:89], v[204:207], v[188:191], v[86:89]
	v_mfma_f32_16x16x32_bf16 v[82:85], v[212:215], v[188:191], v[82:85]
	v_mfma_f32_16x16x32_bf16 v[70:73], v[204:207], v[196:199], v[70:73]
	v_mfma_f32_16x16x32_bf16 v[66:69], v[212:215], v[196:199], v[66:69]
	v_mfma_f32_16x16x32_bf16 v[118:121], v[208:211], v[168:171], v[118:121]
	v_mfma_f32_16x16x32_bf16 v[114:117], v[216:219], v[168:171], v[114:117]
	v_mfma_f32_16x16x32_bf16 v[102:105], v[208:211], v[184:187], v[102:105]
	v_mfma_f32_16x16x32_bf16 v[98:101], v[216:219], v[184:187], v[98:101]
	v_mfma_f32_16x16x32_bf16 v[86:89], v[208:211], v[192:195], v[86:89]
	v_mfma_f32_16x16x32_bf16 v[82:85], v[216:219], v[192:195], v[82:85]
	v_mfma_f32_16x16x32_bf16 v[70:73], v[208:211], v[200:203], v[70:73]
	v_mfma_f32_16x16x32_bf16 v[66:69], v[216:219], v[200:203], v[66:69]
	s_mov_b32 m0, s48
	v_lshl_add_u64 v[222:223], s[24:25], 0, v[134:135]
	s_barrier
	ds_read_b128 v[164:167], v147 offset:16384
	ds_read_b128 v[168:171], v147 offset:17408
	ds_read_b128 v[172:175], v147 offset:18432
	ds_read_b128 v[184:187], v147 offset:19456
	ds_read_b128 v[188:191], v147 offset:20480
	ds_read_b128 v[192:195], v147 offset:21504
	ds_read_b128 v[196:199], v147 offset:22528
	ds_read_b128 v[200:203], v147 offset:23552
	global_load_lds_dwordx4 v[222:223], off
	v_lshl_add_u64 v[224:225], s[24:25], 0, v[132:133]
	s_mov_b32 m0, s49
	s_nop 0
	global_load_lds_dwordx4 v[224:225], off
	s_barrier
	s_waitcnt lgkmcnt(0)
	s_waitcnt lgkmcnt(0)
	v_mfma_f32_16x16x32_bf16 v[62:65], v[148:151], v[164:167], v[62:65]
	v_mfma_f32_16x16x32_bf16 v[58:61], v[156:159], v[164:167], v[58:61]
	v_mfma_f32_16x16x32_bf16 v[46:49], v[148:151], v[172:175], v[46:49]
	v_mfma_f32_16x16x32_bf16 v[42:45], v[156:159], v[172:175], v[42:45]
	v_mfma_f32_16x16x32_bf16 v[30:33], v[148:151], v[188:191], v[30:33]
	v_mfma_f32_16x16x32_bf16 v[26:29], v[156:159], v[188:191], v[26:29]
	v_mfma_f32_16x16x32_bf16 v[18:21], v[148:151], v[196:199], v[18:21]
	v_mfma_f32_16x16x32_bf16 v[10:13], v[156:159], v[196:199], v[10:13]
	v_mfma_f32_16x16x32_bf16 v[62:65], v[152:155], v[168:171], v[62:65]
	v_mfma_f32_16x16x32_bf16 v[58:61], v[160:163], v[168:171], v[58:61]
	v_mfma_f32_16x16x32_bf16 v[46:49], v[152:155], v[184:187], v[46:49]
	v_mfma_f32_16x16x32_bf16 v[42:45], v[160:163], v[184:187], v[42:45]
	v_mfma_f32_16x16x32_bf16 v[30:33], v[152:155], v[192:195], v[30:33]
	v_mfma_f32_16x16x32_bf16 v[26:29], v[160:163], v[192:195], v[26:29]
	v_mfma_f32_16x16x32_bf16 v[18:21], v[152:155], v[200:203], v[18:21]
	v_mfma_f32_16x16x32_bf16 v[10:13], v[160:163], v[200:203], v[10:13]
	s_barrier
; #define PG8_STAGE(bufoff, gbase, voff) do { _Pragma("unroll") for (int _i = 0; _i < 2; ++_i) \
;         __builtin_amdgcn_global_load_lds((const unsigned*)((const char*)(gbase) + (voff)[_i]), (LAS unsigned*)(lds + (bufoff) + ldsw + _i * 8192), 16, 0, 0); } while (0)
; #define PG8_LDA(dst, b, h) do { _Pragma("unroll") for (int m = 0; m < 4; ++m) _Pragma("unroll") for (int k = 0; k < 2; ++k) dst[m][k] = *(const LAS bf16x8*)(lds + PG8_SA(b, h) + aoff + m * 2048 + k * 1024); } while (0)
; #define PG8_LDB(dst, b, h) do { _Pragma("unroll") for (int n = 0; n < 2; ++n) _Pragma("unroll") for (int k = 0; k < 2; ++k) dst[n][k] = *(const LAS bf16x8*)(lds + PG8_SB(b, h) + boff + n * 2048 + k * 1024); } while (0)
; #define PG8_MMA(ai, bj, At, Bt) do { __builtin_amdgcn_s_setprio(1); _Pragma("unroll") for (int m = 0; m < 4; ++m) _Pragma("unroll") for (int n = 0; n < 2; ++n) _Pragma("unroll") for (int k = 0; k < 2; ++k) \
;         acc[ai][bj][m][n] = __builtin_amdgcn_mfma_f32_16x16x32_bf16(Bt[n][k], At[m][k], acc[ai][bj][m][n], 0, 0, 0); __builtin_amdgcn_s_setprio(0); } while (0)
; #define PG8_WAIT_V(n) asm volatile("s_waitcnt vmcnt(" #n ")" ::: "memory")
; #define PG8_WAIT_L(n) asm volatile("s_waitcnt lgkmcnt(" #n ")" ::: "memory")
; #define PG8_BAR __builtin_amdgcn_s_barrier()
; #define PG8_SCHED __builtin_amdgcn_sched_barrier(0)
; template <class Epi>
; __device__ __forceinline__ void gemm_phase(LAS unsigned char* lds, const Gemm g, const StaticOrder& S, const Epi& E) {
;     ...
;             PG8_WAIT_V(6); PG8_BAR; PG8_MMA(1, 1, At, B1); PG8_BAR;
;             PG8_LDB(B0, 1, 0); PG8_SCHED; PG8_LDA(At, 1, 0); PG8_STAGE(PG8_SA(0, 1), a2 + hstepA, voffA);
;             PG8_WAIT_L(8); PG8_BAR; PG8_WAIT_L(0); PG8_MMA(0, 0, At, B0); PG8_BAR; PG8_SCHED;
;             PG8_LDB(B1, 1, 1); PG8_STAGE(PG8_SB(1, 0), b3, voffB);
;             PG8_BAR; PG8_WAIT_L(0); PG8_MMA(0, 1, At, B1); PG8_BAR;
;             PG8_LDA(At, 1, 1); PG8_STAGE(PG8_SA(1, 0), a3, voffA);
;             PG8_BAR; PG8_WAIT_L(0); PG8_MMA(1, 0, At, B0); PG8_BAR; PG8_SCHED;
	s_add_u32 s62, s22, 0x100000
	s_addc_u32 s63, s23, 0
	s_add_i32 s64, s65, s39
	v_lshl_add_u64 v[148:149], s[62:63], 0, v[0:1]
	s_mov_b32 m0, s64
	s_nop 0
	global_load_lds_dwordx4 v[148:149], off
	v_lshl_add_u64 v[148:149], s[62:63], 0, v[130:131]
	s_add_i32 m0, s64, 0x2000
	s_nop 0
	global_load_lds_dwordx4 v[148:149], off
	s_waitcnt vmcnt(6)
	s_barrier
	v_mfma_f32_16x16x32_bf16 v[54:57], v[204:207], v[164:167], v[54:57]
	v_mfma_f32_16x16x32_bf16 v[50:53], v[212:215], v[164:167], v[50:53]
	v_mfma_f32_16x16x32_bf16 v[38:41], v[204:207], v[172:175], v[38:41]
	v_mfma_f32_16x16x32_bf16 v[34:37], v[212:215], v[172:175], v[34:37]
	v_mfma_f32_16x16x32_bf16 v[22:25], v[204:207], v[188:191], v[22:25]
	v_mfma_f32_16x16x32_bf16 v[14:17], v[212:215], v[188:191], v[14:17]
	v_mfma_f32_16x16x32_bf16 v[6:9], v[204:207], v[196:199], v[6:9]
	v_mfma_f32_16x16x32_bf16 v[2:5], v[212:215], v[196:199], v[2:5]
	v_mfma_f32_16x16x32_bf16 v[54:57], v[208:211], v[168:171], v[54:57]
	v_mfma_f32_16x16x32_bf16 v[50:53], v[216:219], v[168:171], v[50:53]
	v_mfma_f32_16x16x32_bf16 v[38:41], v[208:211], v[184:187], v[38:41]
	v_mfma_f32_16x16x32_bf16 v[34:37], v[216:219], v[184:187], v[34:37]
	v_mfma_f32_16x16x32_bf16 v[22:25], v[208:211], v[192:195], v[22:25]
	v_mfma_f32_16x16x32_bf16 v[14:17], v[216:219], v[192:195], v[14:17]
	v_mfma_f32_16x16x32_bf16 v[6:9], v[208:211], v[200:203], v[6:9]
	v_mfma_f32_16x16x32_bf16 v[2:5], v[216:219], v[200:203], v[2:5]
	s_add_i32 s62, 0, 0x18000
	v_add_u32_e32 v160, s62, v146
	s_barrier
	ds_read_b128 v[148:151], v160
	ds_read_b128 v[152:155], v160 offset:1024
	ds_read_b128 v[156:159], v160 offset:2048
	ds_read_b128 v[160:163], v160 offset:3072
	s_add_u32 s24, s24, 0x100000
	s_addc_u32 s25, s25, 0
	s_mov_b32 m0, s50
	v_lshl_add_u64 v[204:205], s[24:25], 0, v[134:135]
	ds_read_b128 v[164:167], v147 offset:32768
	ds_read_b128 v[168:171], v147 offset:33792
	ds_read_b128 v[172:175], v147 offset:34816
	ds_read_b128 v[184:187], v147 offset:35840
	ds_read_b128 v[188:191], v147 offset:36864
	ds_read_b128 v[192:195], v147 offset:37888
	ds_read_b128 v[196:199], v147 offset:38912
	ds_read_b128 v[200:203], v147 offset:39936
	global_load_lds_dwordx4 v[204:205], off
	v_lshl_add_u64 v[204:205], s[24:25], 0, v[132:133]
	s_mov_b32 m0, s51
	s_nop 0
	global_load_lds_dwordx4 v[204:205], off
	s_waitcnt lgkmcnt(8)
	s_barrier
	s_waitcnt lgkmcnt(0)
	s_waitcnt lgkmcnt(0)
	v_mfma_f32_16x16x32_bf16 v[126:129], v[148:151], v[164:167], v[126:129]
	v_mfma_f32_16x16x32_bf16 v[122:125], v[156:159], v[164:167], v[122:125]
	v_mfma_f32_16x16x32_bf16 v[110:113], v[148:151], v[172:175], v[110:113]
	v_mfma_f32_16x16x32_bf16 v[106:109], v[156:159], v[172:175], v[106:109]
	v_mfma_f32_16x16x32_bf16 v[94:97], v[148:151], v[188:191], v[94:97]
	v_mfma_f32_16x16x32_bf16 v[90:93], v[156:159], v[188:191], v[90:93]
	v_mfma_f32_16x16x32_bf16 v[78:81], v[148:151], v[196:199], v[78:81]
	v_mfma_f32_16x16x32_bf16 v[74:77], v[156:159], v[196:199], v[74:77]
	v_mfma_f32_16x16x32_bf16 v[126:129], v[152:155], v[168:171], v[126:129]
	v_mfma_f32_16x16x32_bf16 v[122:125], v[160:163], v[168:171], v[122:125]
	v_mfma_f32_16x16x32_bf16 v[110:113], v[152:155], v[184:187], v[110:113]
	v_mfma_f32_16x16x32_bf16 v[106:109], v[160:163], v[184:187], v[106:109]
	v_mfma_f32_16x16x32_bf16 v[94:97], v[152:155], v[192:195], v[94:97]
	v_mfma_f32_16x16x32_bf16 v[90:93], v[160:163], v[192:195], v[90:93]
	v_mfma_f32_16x16x32_bf16 v[78:81], v[152:155], v[200:203], v[78:81]
	v_mfma_f32_16x16x32_bf16 v[74:77], v[160:163], v[200:203], v[74:77]
	s_barrier
	s_add_i32 s24, 0, 0x1c000
	s_add_i32 s25, s62, s39
	v_add_u32_e32 v216, s24, v146
	v_lshl_add_u64 v[176:177], v[176:177], 0, s[6:7]
	s_mov_b32 m0, s25
	ds_read_b128 v[204:207], v216
	ds_read_b128 v[208:211], v216 offset:1024
	ds_read_b128 v[212:215], v216 offset:2048
	ds_read_b128 v[216:219], v216 offset:3072
	global_load_lds_dwordx4 v[176:177], off
	v_lshl_add_u64 v[176:177], v[220:221], 0, s[6:7]
	s_add_i32 m0, s25, 0x2000
	s_nop 0
	global_load_lds_dwordx4 v[176:177], off
	s_barrier
	s_waitcnt lgkmcnt(0)
	s_waitcnt lgkmcnt(0)
	v_mfma_f32_16x16x32_bf16 v[118:121], v[204:207], v[164:167], v[118:121]
	v_mfma_f32_16x16x32_bf16 v[114:117], v[212:215], v[164:167], v[114:117]
	v_mfma_f32_16x16x32_bf16 v[102:105], v[204:207], v[172:175], v[102:105]
	v_mfma_f32_16x16x32_bf16 v[98:101], v[212:215], v[172:175], v[98:101]
	v_mfma_f32_16x16x32_bf16 v[86:89], v[204:207], v[188:191], v[86:89]
	v_mfma_f32_16x16x32_bf16 v[82:85], v[212:215], v[188:191], v[82:85]
	v_mfma_f32_16x16x32_bf16 v[70:73], v[204:207], v[196:199], v[70:73]
	v_mfma_f32_16x16x32_bf16 v[66:69], v[212:215], v[196:199], v[66:69]
	v_mfma_f32_16x16x32_bf16 v[118:121], v[208:211], v[168:171], v[118:121]
	v_mfma_f32_16x16x32_bf16 v[114:117], v[216:219], v[168:171], v[114:117]
	v_mfma_f32_16x16x32_bf16 v[102:105], v[208:211], v[184:187], v[102:105]
	v_mfma_f32_16x16x32_bf16 v[98:101], v[216:219], v[184:187], v[98:101]
	v_mfma_f32_16x16x32_bf16 v[86:89], v[208:211], v[192:195], v[86:89]
	v_mfma_f32_16x16x32_bf16 v[82:85], v[216:219], v[192:195], v[82:85]
	v_mfma_f32_16x16x32_bf16 v[70:73], v[208:211], v[200:203], v[70:73]
	v_mfma_f32_16x16x32_bf16 v[66:69], v[216:219], v[200:203], v[66:69]
	s_mov_b32 m0, s54
	v_lshl_add_u64 v[176:177], v[222:223], 0, s[6:7]
	s_barrier
	ds_read_b128 v[164:167], v147 offset:49152
	ds_read_b128 v[168:171], v147 offset:50176
	ds_read_b128 v[172:175], v147 offset:51200
	ds_read_b128 v[184:187], v147 offset:52224
	ds_read_b128 v[188:191], v147 offset:53248
	ds_read_b128 v[192:195], v147 offset:54272
	ds_read_b128 v[196:199], v147 offset:55296
	ds_read_b128 v[200:203], v147 offset:56320
	global_load_lds_dwordx4 v[176:177], off
	v_lshl_add_u64 v[176:177], v[224:225], 0, s[6:7]
	s_mov_b32 m0, s55
	s_nop 0
	global_load_lds_dwordx4 v[176:177], off
	s_barrier
; #define PG8_STAGE(bufoff, gbase, voff) do { _Pragma("unroll") for (int _i = 0; _i < 2; ++_i) \
;         __builtin_amdgcn_global_load_lds((const unsigned*)((const char*)(gbase) + (voff)[_i]), (LAS unsigned*)(lds + (bufoff) + ldsw + _i * 8192), 16, 0, 0); } while (0)
; #define PG8_MMA(ai, bj, At, Bt) do { __builtin_amdgcn_s_setprio(1); _Pragma("unroll") for (int m = 0; m < 4; ++m) _Pragma("unroll") for (int n = 0; n < 2; ++n) _Pragma("unroll") for (int k = 0; k < 2; ++k) \
;         acc[ai][bj][m][n] = __builtin_amdgcn_mfma_f32_16x16x32_bf16(Bt[n][k], At[m][k], acc[ai][bj][m][n], 0, 0, 0); __builtin_amdgcn_s_setprio(0); } while (0)
; #define PG8_WAIT_V(n) asm volatile("s_waitcnt vmcnt(" #n ")" ::: "memory")
; #define PG8_WAIT_L(n) asm volatile("s_waitcnt lgkmcnt(" #n ")" ::: "memory")
; #define PG8_BAR __builtin_amdgcn_s_barrier()
; #define PG8_SCHED __builtin_amdgcn_sched_barrier(0)
; template <class Epi>
; __device__ __forceinline__ void gemm_phase(LAS unsigned char* lds, const Gemm g, const StaticOrder& S, const Epi& E) {
;     ...
;             PG8_BAR; PG8_WAIT_L(0); PG8_MMA(1, 0, At, B0); PG8_BAR; PG8_SCHED;
;             PG8_STAGE(PG8_SB(1, 1), b3 + hstepB, voffB);
;             PG8_WAIT_V(6); PG8_BAR; PG8_MMA(1, 1, At, B1); PG8_BAR;
;         }
;         if constexpr (!Epi::AFTER_DRAIN) E(acc, cur, wr, wc, fr, fq, pre);
;         if (!has_next) break;
; #pragma unroll
;         for (int a = 0; a < 2; ++a)
; #pragma unroll
;             for (int b = 0; b < 2; ++b)
; #pragma unroll
;                 for (int m = 0; m < 4; ++m)
; #pragma unroll
;                     for (int n = 0; n < 2; ++n) acc[a][b][m][n] = (f32x4){0.f, 0.f, 0.f, 0.f};
;         cur = nxt; cA = nA; cB = nB; ++ui;
	s_waitcnt lgkmcnt(0)
	s_waitcnt lgkmcnt(0)
	v_mfma_f32_16x16x32_bf16 v[62:65], v[148:151], v[164:167], v[62:65]
	v_mfma_f32_16x16x32_bf16 v[58:61], v[156:159], v[164:167], v[58:61]
	v_mfma_f32_16x16x32_bf16 v[46:49], v[148:151], v[172:175], v[46:49]
	v_mfma_f32_16x16x32_bf16 v[42:45], v[156:159], v[172:175], v[42:45]
	v_mfma_f32_16x16x32_bf16 v[30:33], v[148:151], v[188:191], v[30:33]
	v_mfma_f32_16x16x32_bf16 v[26:29], v[156:159], v[188:191], v[26:29]
	v_mfma_f32_16x16x32_bf16 v[18:21], v[148:151], v[196:199], v[18:21]
	v_mfma_f32_16x16x32_bf16 v[10:13], v[156:159], v[196:199], v[10:13]
	v_mfma_f32_16x16x32_bf16 v[62:65], v[152:155], v[168:171], v[62:65]
	v_mfma_f32_16x16x32_bf16 v[58:61], v[160:163], v[168:171], v[58:61]
	v_mfma_f32_16x16x32_bf16 v[46:49], v[152:155], v[184:187], v[46:49]
	v_mfma_f32_16x16x32_bf16 v[42:45], v[160:163], v[184:187], v[42:45]
	v_mfma_f32_16x16x32_bf16 v[30:33], v[152:155], v[192:195], v[30:33]
	v_mfma_f32_16x16x32_bf16 v[26:29], v[160:163], v[192:195], v[26:29]
	v_mfma_f32_16x16x32_bf16 v[18:21], v[152:155], v[200:203], v[18:21]
	v_mfma_f32_16x16x32_bf16 v[10:13], v[160:163], v[200:203], v[10:13]
	s_barrier
	s_add_u32 s22, s22, 0x100080
	s_addc_u32 s23, s23, 0
	s_add_i32 s24, s24, s39
	v_lshl_add_u64 v[148:149], s[22:23], 0, v[0:1]
	s_mov_b32 m0, s24
	s_nop 0
	global_load_lds_dwordx4 v[148:149], off
	v_lshl_add_u64 v[148:149], s[22:23], 0, v[130:131]
	s_add_i32 m0, s24, 0x2000
	s_nop 0
	global_load_lds_dwordx4 v[148:149], off
	s_waitcnt vmcnt(6)
	s_barrier
	v_mfma_f32_16x16x32_bf16 v[54:57], v[204:207], v[164:167], v[54:57]
	v_mfma_f32_16x16x32_bf16 v[50:53], v[212:215], v[164:167], v[50:53]
	v_mfma_f32_16x16x32_bf16 v[38:41], v[204:207], v[172:175], v[38:41]
	v_mfma_f32_16x16x32_bf16 v[34:37], v[212:215], v[172:175], v[34:37]
	v_mfma_f32_16x16x32_bf16 v[22:25], v[204:207], v[188:191], v[22:25]
	v_mfma_f32_16x16x32_bf16 v[14:17], v[212:215], v[188:191], v[14:17]
	v_mfma_f32_16x16x32_bf16 v[6:9], v[204:207], v[196:199], v[6:9]
	v_mfma_f32_16x16x32_bf16 v[2:5], v[212:215], v[196:199], v[2:5]
	v_mfma_f32_16x16x32_bf16 v[54:57], v[208:211], v[168:171], v[54:57]
	v_mfma_f32_16x16x32_bf16 v[50:53], v[216:219], v[168:171], v[50:53]
	v_mfma_f32_16x16x32_bf16 v[38:41], v[208:211], v[184:187], v[38:41]
	v_mfma_f32_16x16x32_bf16 v[34:37], v[216:219], v[184:187], v[34:37]
	v_mfma_f32_16x16x32_bf16 v[22:25], v[208:211], v[192:195], v[22:25]
	v_mfma_f32_16x16x32_bf16 v[14:17], v[216:219], v[192:195], v[14:17]
	v_mfma_f32_16x16x32_bf16 v[6:9], v[208:211], v[200:203], v[6:9]
	v_mfma_f32_16x16x32_bf16 v[2:5], v[216:219], v[200:203], v[2:5]
	s_add_i32 s61, s61, 2
	s_add_u32 s20, s20, 0x100
	s_addc_u32 s21, s21, 0
	s_cmp_gt_u32 s61, 61
	s_barrier
	s_cbranch_scc0 .LBB0_472
	s_add_u32 s20, s17, 0xffffff00
	s_addc_u32 s21, s58, -1
	s_andn2_b64 vcc, exec, s[42:43]
	s_cbranch_vccnz .LBB0_463
	v_mov_b32_e32 v2, 0
	s_mov_b32 s57, s8
	s_mov_b32 s26, s10
	s_mov_b64 s[4:5], s[18:19]
	s_mov_b32 s56, s16
	v_mov_b32_e32 v3, v2
	v_mov_b32_e32 v4, v2
	v_mov_b32_e32 v5, v2
	v_mov_b32_e32 v6, v2
	v_mov_b32_e32 v7, v2
	v_mov_b32_e32 v8, v2
	v_mov_b32_e32 v9, v2
	v_mov_b32_e32 v14, v2
	v_mov_b32_e32 v15, v2
	v_mov_b32_e32 v16, v2
	v_mov_b32_e32 v17, v2
	v_mov_b32_e32 v22, v2
	v_mov_b32_e32 v23, v2
	v_mov_b32_e32 v24, v2
	v_mov_b32_e32 v25, v2
	v_mov_b32_e32 v34, v2
	v_mov_b32_e32 v35, v2
	v_mov_b32_e32 v36, v2
	v_mov_b32_e32 v37, v2
	v_mov_b32_e32 v38, v2
	v_mov_b32_e32 v39, v2
	v_mov_b32_e32 v40, v2
	v_mov_b32_e32 v41, v2
	v_mov_b32_e32 v50, v2
	v_mov_b32_e32 v51, v2
	v_mov_b32_e32 v52, v2
	v_mov_b32_e32 v53, v2
	v_mov_b32_e32 v54, v2
	v_mov_b32_e32 v55, v2
	v_mov_b32_e32 v56, v2
	v_mov_b32_e32 v57, v2
	v_mov_b32_e32 v10, v2
	v_mov_b32_e32 v11, v2
	v_mov_b32_e32 v12, v2
	v_mov_b32_e32 v13, v2
	v_mov_b32_e32 v18, v2
	v_mov_b32_e32 v19, v2
	v_mov_b32_e32 v20, v2
	v_mov_b32_e32 v21, v2
	v_mov_b32_e32 v26, v2
	v_mov_b32_e32 v27, v2
	v_mov_b32_e32 v28, v2
	v_mov_b32_e32 v29, v2
	v_mov_b32_e32 v30, v2
	v_mov_b32_e32 v31, v2
	v_mov_b32_e32 v32, v2
	v_mov_b32_e32 v33, v2
	v_mov_b32_e32 v42, v2
	v_mov_b32_e32 v43, v2
	v_mov_b32_e32 v44, v2
	v_mov_b32_e32 v45, v2
	v_mov_b32_e32 v46, v2
	v_mov_b32_e32 v47, v2
	v_mov_b32_e32 v48, v2
	v_mov_b32_e32 v49, v2
	v_mov_b32_e32 v58, v2
	v_mov_b32_e32 v59, v2
	v_mov_b32_e32 v60, v2
	v_mov_b32_e32 v61, v2
	v_mov_b32_e32 v62, v2
	v_mov_b32_e32 v63, v2
	v_mov_b32_e32 v64, v2
	v_mov_b32_e32 v65, v2
	v_mov_b32_e32 v66, v2
	v_mov_b32_e32 v67, v2
	v_mov_b32_e32 v68, v2
	v_mov_b32_e32 v69, v2
	v_mov_b32_e32 v70, v2
	v_mov_b32_e32 v71, v2
	v_mov_b32_e32 v72, v2
	v_mov_b32_e32 v73, v2
	v_mov_b32_e32 v82, v2
	v_mov_b32_e32 v83, v2
	v_mov_b32_e32 v84, v2
	v_mov_b32_e32 v85, v2
	v_mov_b32_e32 v86, v2
	v_mov_b32_e32 v87, v2
	v_mov_b32_e32 v88, v2
	v_mov_b32_e32 v89, v2
	v_mov_b32_e32 v98, v2
	v_mov_b32_e32 v99, v2
	v_mov_b32_e32 v100, v2
	v_mov_b32_e32 v101, v2
	v_mov_b32_e32 v102, v2
	v_mov_b32_e32 v103, v2
	v_mov_b32_e32 v104, v2
	v_mov_b32_e32 v105, v2
	v_mov_b32_e32 v114, v2
	v_mov_b32_e32 v115, v2
	v_mov_b32_e32 v116, v2
	v_mov_b32_e32 v117, v2
	v_mov_b32_e32 v118, v2
	v_mov_b32_e32 v119, v2
	v_mov_b32_e32 v120, v2
	v_mov_b32_e32 v121, v2
	v_mov_b32_e32 v74, v2
	v_mov_b32_e32 v75, v2
	v_mov_b32_e32 v76, v2
	v_mov_b32_e32 v77, v2
	v_mov_b32_e32 v78, v2
	v_mov_b32_e32 v79, v2
	v_mov_b32_e32 v80, v2
	v_mov_b32_e32 v81, v2
	v_mov_b32_e32 v90, v2
	v_mov_b32_e32 v91, v2
	v_mov_b32_e32 v92, v2
	v_mov_b32_e32 v93, v2
	v_mov_b32_e32 v94, v2
	v_mov_b32_e32 v95, v2
	v_mov_b32_e32 v96, v2
	v_mov_b32_e32 v97, v2
	v_mov_b32_e32 v106, v2
	v_mov_b32_e32 v107, v2
	v_mov_b32_e32 v108, v2
	v_mov_b32_e32 v109, v2
	v_mov_b32_e32 v110, v2
	v_mov_b32_e32 v111, v2
	v_mov_b32_e32 v112, v2
	v_mov_b32_e32 v113, v2
	v_mov_b32_e32 v122, v2
	v_mov_b32_e32 v123, v2
	v_mov_b32_e32 v124, v2
	v_mov_b32_e32 v125, v2
	v_mov_b32_e32 v126, v2
	v_mov_b32_e32 v127, v2
	v_mov_b32_e32 v128, v2
	v_mov_b32_e32 v129, v2
	s_andn2_b64 vcc, exec, s[40:41]
	s_cbranch_vccnz .LBB0_464

; #define PG8_STAGE(bufoff, gbase, voff) do { _Pragma("unroll") for (int _i = 0; _i < 2; ++_i) \
;         __builtin_amdgcn_global_load_lds((const unsigned*)((const char*)(gbase) + (voff)[_i]), (LAS unsigned*)(lds + (bufoff) + ldsw + _i * 8192), 16, 0, 0); } while (0)
; #define PG8_LDA(dst, b, h) do { _Pragma("unroll") for (int m = 0; m < 4; ++m) _Pragma("unroll") for (int k = 0; k < 2; ++k) dst[m][k] = *(const LAS bf16x8*)(lds + PG8_SA(b, h) + aoff + m * 2048 + k * 1024); } while (0)
; #define PG8_LDB(dst, b, h) do { _Pragma("unroll") for (int n = 0; n < 2; ++n) _Pragma("unroll") for (int k = 0; k < 2; ++k) dst[n][k] = *(const LAS bf16x8*)(lds + PG8_SB(b, h) + boff + n * 2048 + k * 1024); } while (0)
; #define PG8_MMA(ai, bj, At, Bt) do { __builtin_amdgcn_s_setprio(1); _Pragma("unroll") for (int m = 0; m < 4; ++m) _Pragma("unroll") for (int n = 0; n < 2; ++n) _Pragma("unroll") for (int k = 0; k < 2; ++k) \
;         acc[ai][bj][m][n] = __builtin_amdgcn_mfma_f32_16x16x32_bf16(Bt[n][k], At[m][k], acc[ai][bj][m][n], 0, 0, 0); __builtin_amdgcn_s_setprio(0); } while (0)
; #define PG8_WAIT_L(n) asm volatile("s_waitcnt lgkmcnt(" #n ")" ::: "memory")
; #define PG8_BAR __builtin_amdgcn_s_barrier()
; #define PG8_SCHED __builtin_amdgcn_sched_barrier(0)
; template <class Epi>
; __device__ __forceinline__ void gemm_phase(LAS unsigned char* lds, const Gemm g, const StaticOrder& S, const Epi& E) {
;     ...
;             const bool last = (t == nt - 2);
;             const char* a1 = cA + (size_t)(t + 1) * kstepA;
;             const char* a2 = last ? nA : cA + (size_t)(t + 2) * kstepA; const char* b2 = last ? nB : cB + (size_t)(t + 2) * kstep;
;             const char* a3 = a2 + kstepA; const char* b3 = b2 + kstep;
;             PG8_LDB(B0, 0, 0); PG8_SCHED; PG8_LDA(At, 0, 0); PG8_STAGE(PG8_SA(1, 1), a1 + hstepA, voffA);
;             PG8_WAIT_L(8); PG8_BAR; PG8_WAIT_L(0); PG8_MMA(0, 0, At, B0); PG8_BAR; PG8_SCHED;
;             PG8_LDB(B1, 0, 1); PG8_STAGE(PG8_SB(0, 0), b2, voffB);
;             PG8_BAR; PG8_WAIT_L(0); PG8_MMA(0, 1, At, B1); PG8_BAR;
;             PG8_LDA(At, 0, 1); PG8_STAGE(PG8_SA(0, 0), a2, voffA);
;             PG8_BAR; PG8_WAIT_L(0); PG8_MMA(1, 0, At, B0); PG8_BAR; PG8_SCHED;
.LBB0_603:
	s_add_u32 s8, s0, 0x100
	s_addc_u32 s9, s1, 0
	s_add_i32 s60, 0, 0x10000
	v_add_u32_e32 v102, s60, v229
	ds_read_b128 v[34:37], v102
	ds_read_b128 v[38:41], v102 offset:1024
	ds_read_b128 v[98:101], v102 offset:2048
	ds_read_b128 v[102:105], v102 offset:3072
	s_cmp_eq_u32 s59, 12
	s_cselect_b32 s11, s35, s9
	s_cselect_b32 s10, s36, s8
	s_cselect_b32 s5, s37, s58
	s_cselect_b32 s4, s51, s53
	v_lshl_add_u64 v[184:185], s[0:1], 0, v[194:195]
	s_add_i32 m0, s20, 0xc000
	ds_read_b128 v[106:109], v231
	ds_read_b128 v[118:121], v231 offset:1024
	ds_read_b128 v[130:133], v231 offset:2048
	ds_read_b128 v[142:145], v231 offset:3072
	ds_read_b128 v[154:157], v231 offset:4096
	ds_read_b128 v[158:161], v231 offset:5120
	ds_read_b128 v[170:173], v231 offset:6144
	ds_read_b128 v[174:177], v231 offset:7168
	global_load_lds_dwordx4 v[184:185], off
	v_lshl_add_u64 v[184:185], s[0:1], 0, v[196:197]
	s_add_i32 m0, s20, 0xe000
	s_nop 0
	global_load_lds_dwordx4 v[184:185], off
	s_waitcnt lgkmcnt(8)
	s_barrier
	s_waitcnt lgkmcnt(0)
	s_waitcnt lgkmcnt(0)
	v_mfma_f32_16x16x32_bf16 v[166:169], v[34:37], v[106:109], v[166:169]
	v_mfma_f32_16x16x32_bf16 v[162:165], v[98:101], v[106:109], v[162:165]
	v_mfma_f32_16x16x32_bf16 v[150:153], v[34:37], v[130:133], v[150:153]
	v_mfma_f32_16x16x32_bf16 v[146:149], v[98:101], v[130:133], v[146:149]
	v_mfma_f32_16x16x32_bf16 v[138:141], v[34:37], v[154:157], v[138:141]
	v_mfma_f32_16x16x32_bf16 v[134:137], v[98:101], v[154:157], v[134:137]
	v_mfma_f32_16x16x32_bf16 v[126:129], v[34:37], v[170:173], v[126:129]
	v_mfma_f32_16x16x32_bf16 v[122:125], v[98:101], v[170:173], v[122:125]
	v_mfma_f32_16x16x32_bf16 v[166:169], v[38:41], v[118:121], v[166:169]
	v_mfma_f32_16x16x32_bf16 v[162:165], v[102:105], v[118:121], v[162:165]
	v_mfma_f32_16x16x32_bf16 v[150:153], v[38:41], v[142:145], v[150:153]
	v_mfma_f32_16x16x32_bf16 v[146:149], v[102:105], v[142:145], v[146:149]
	v_mfma_f32_16x16x32_bf16 v[138:141], v[38:41], v[158:161], v[138:141]
	v_mfma_f32_16x16x32_bf16 v[134:137], v[102:105], v[158:161], v[134:137]
	v_mfma_f32_16x16x32_bf16 v[126:129], v[38:41], v[174:177], v[126:129]
	v_mfma_f32_16x16x32_bf16 v[122:125], v[102:105], v[174:177], v[122:125]
	s_barrier
	s_add_i32 s61, 0, 0x14000
	v_add_u32_e32 v184, s61, v229
	s_add_i32 s0, s60, s19
	ds_read_b128 v[198:201], v184
	ds_read_b128 v[202:205], v184 offset:1024
	ds_read_b128 v[206:209], v184 offset:2048
	ds_read_b128 v[210:213], v184 offset:3072
	v_lshl_add_u64 v[184:185], s[4:5], 0, v[0:1]
	s_mov_b32 m0, s0
	v_lshl_add_u64 v[186:187], s[4:5], 0, v[188:189]
	global_load_lds_dwordx4 v[184:185], off
	s_add_i32 m0, s0, 0x2000
	s_nop 0
	global_load_lds_dwordx4 v[186:187], off
	s_barrier
	s_waitcnt lgkmcnt(0)
	s_waitcnt lgkmcnt(0)
	v_mfma_f32_16x16x32_bf16 v[70:73], v[198:201], v[106:109], v[70:73]
	v_mfma_f32_16x16x32_bf16 v[66:69], v[206:209], v[106:109], v[66:69]
	v_mfma_f32_16x16x32_bf16 v[62:65], v[198:201], v[130:133], v[62:65]
	v_mfma_f32_16x16x32_bf16 v[58:61], v[206:209], v[130:133], v[58:61]
	v_mfma_f32_16x16x32_bf16 v[54:57], v[198:201], v[154:157], v[54:57]
	v_mfma_f32_16x16x32_bf16 v[50:53], v[206:209], v[154:157], v[50:53]
	v_mfma_f32_16x16x32_bf16 v[46:49], v[198:201], v[170:173], v[46:49]
	v_mfma_f32_16x16x32_bf16 v[42:45], v[206:209], v[170:173], v[42:45]
	v_mfma_f32_16x16x32_bf16 v[70:73], v[202:205], v[118:121], v[70:73]
	v_mfma_f32_16x16x32_bf16 v[66:69], v[210:213], v[118:121], v[66:69]
	v_mfma_f32_16x16x32_bf16 v[62:65], v[202:205], v[142:145], v[62:65]
	v_mfma_f32_16x16x32_bf16 v[58:61], v[210:213], v[142:145], v[58:61]
	v_mfma_f32_16x16x32_bf16 v[54:57], v[202:205], v[158:161], v[54:57]
	v_mfma_f32_16x16x32_bf16 v[50:53], v[210:213], v[158:161], v[50:53]
	v_mfma_f32_16x16x32_bf16 v[46:49], v[202:205], v[174:177], v[46:49]
	v_mfma_f32_16x16x32_bf16 v[42:45], v[210:213], v[174:177], v[42:45]
	s_mov_b32 m0, s20
	v_lshl_add_u64 v[214:215], s[10:11], 0, v[192:193]
	s_barrier
	ds_read_b128 v[106:109], v231 offset:16384
	ds_read_b128 v[118:121], v231 offset:17408
	ds_read_b128 v[130:133], v231 offset:18432
	ds_read_b128 v[142:145], v231 offset:19456
	ds_read_b128 v[154:157], v231 offset:20480
	ds_read_b128 v[158:161], v231 offset:21504
	ds_read_b128 v[170:173], v231 offset:22528
	ds_read_b128 v[174:177], v231 offset:23552
	global_load_lds_dwordx4 v[214:215], off
	v_lshl_add_u64 v[216:217], s[10:11], 0, v[190:191]
	s_mov_b32 m0, s21
	s_nop 0
	global_load_lds_dwordx4 v[216:217], off
	s_barrier
	s_waitcnt lgkmcnt(0)
	s_waitcnt lgkmcnt(0)
	v_mfma_f32_16x16x32_bf16 v[114:117], v[34:37], v[106:109], v[114:117]
	v_mfma_f32_16x16x32_bf16 v[110:113], v[98:101], v[106:109], v[110:113]
	v_mfma_f32_16x16x32_bf16 v[94:97], v[34:37], v[130:133], v[94:97]
	v_mfma_f32_16x16x32_bf16 v[90:93], v[98:101], v[130:133], v[90:93]
	v_mfma_f32_16x16x32_bf16 v[86:89], v[34:37], v[154:157], v[86:89]
	v_mfma_f32_16x16x32_bf16 v[82:85], v[98:101], v[154:157], v[82:85]
	v_mfma_f32_16x16x32_bf16 v[34:37], v[34:37], v[170:173], v[78:81]
	v_mfma_f32_16x16x32_bf16 v[114:117], v[38:41], v[118:121], v[114:117]
	v_mfma_f32_16x16x32_bf16 v[110:113], v[102:105], v[118:121], v[110:113]
	v_mfma_f32_16x16x32_bf16 v[94:97], v[38:41], v[142:145], v[94:97]
	v_mfma_f32_16x16x32_bf16 v[90:93], v[102:105], v[142:145], v[90:93]
	v_mfma_f32_16x16x32_bf16 v[86:89], v[38:41], v[158:161], v[86:89]
	v_mfma_f32_16x16x32_bf16 v[82:85], v[102:105], v[158:161], v[82:85]
	v_mfma_f32_16x16x32_bf16 v[34:37], v[38:41], v[174:177], v[34:37]
	v_mfma_f32_16x16x32_bf16 v[38:41], v[98:101], v[170:173], v[74:77]
	v_mfma_f32_16x16x32_bf16 v[38:41], v[102:105], v[174:177], v[38:41]
	s_barrier
; #define PG8_STAGE(bufoff, gbase, voff) do { _Pragma("unroll") for (int _i = 0; _i < 2; ++_i) \
;         __builtin_amdgcn_global_load_lds((const unsigned*)((const char*)(gbase) + (voff)[_i]), (LAS unsigned*)(lds + (bufoff) + ldsw + _i * 8192), 16, 0, 0); } while (0)
; #define PG8_LDA(dst, b, h) do { _Pragma("unroll") for (int m = 0; m < 4; ++m) _Pragma("unroll") for (int k = 0; k < 2; ++k) dst[m][k] = *(const LAS bf16x8*)(lds + PG8_SA(b, h) + aoff + m * 2048 + k * 1024); } while (0)
; #define PG8_LDB(dst, b, h) do { _Pragma("unroll") for (int n = 0; n < 2; ++n) _Pragma("unroll") for (int k = 0; k < 2; ++k) dst[n][k] = *(const LAS bf16x8*)(lds + PG8_SB(b, h) + boff + n * 2048 + k * 1024); } while (0)
; #define PG8_MMA(ai, bj, At, Bt) do { __builtin_amdgcn_s_setprio(1); _Pragma("unroll") for (int m = 0; m < 4; ++m) _Pragma("unroll") for (int n = 0; n < 2; ++n) _Pragma("unroll") for (int k = 0; k < 2; ++k) \
;         acc[ai][bj][m][n] = __builtin_amdgcn_mfma_f32_16x16x32_bf16(Bt[n][k], At[m][k], acc[ai][bj][m][n], 0, 0, 0); __builtin_amdgcn_s_setprio(0); } while (0)
; #define PG8_WAIT_V(n) asm volatile("s_waitcnt vmcnt(" #n ")" ::: "memory")
; #define PG8_WAIT_L(n) asm volatile("s_waitcnt lgkmcnt(" #n ")" ::: "memory")
; #define PG8_BAR __builtin_amdgcn_s_barrier()
; #define PG8_SCHED __builtin_amdgcn_sched_barrier(0)
; template <class Epi>
; __device__ __forceinline__ void gemm_phase(LAS unsigned char* lds, const Gemm g, const StaticOrder& S, const Epi& E) {
;     ...
;             PG8_STAGE(PG8_SB(0, 1), b2 + hstepB, voffB);
;             PG8_WAIT_V(6); PG8_BAR; PG8_MMA(1, 1, At, B1); PG8_BAR;
;             PG8_LDB(B0, 1, 0); PG8_SCHED; PG8_LDA(At, 1, 0); PG8_STAGE(PG8_SA(0, 1), a2 + hstepA, voffA);
;             PG8_WAIT_L(8); PG8_BAR; PG8_WAIT_L(0); PG8_MMA(0, 0, At, B0); PG8_BAR; PG8_SCHED;
;             PG8_LDB(B1, 1, 1); PG8_STAGE(PG8_SB(1, 0), b3, voffB);
;             PG8_BAR; PG8_WAIT_L(0); PG8_MMA(0, 1, At, B1); PG8_BAR;
;             PG8_LDA(At, 1, 1); PG8_STAGE(PG8_SA(1, 0), a3, voffA);
;             PG8_BAR; PG8_WAIT_L(0); PG8_MMA(1, 0, At, B0); PG8_BAR; PG8_SCHED;
	s_add_u32 s0, s4, 0x40000
	s_addc_u32 s1, s5, 0
	s_add_i32 s60, s61, s19
	v_lshl_add_u64 v[74:75], s[0:1], 0, v[0:1]
	s_mov_b32 m0, s60
	s_nop 0
	global_load_lds_dwordx4 v[74:75], off
	v_lshl_add_u64 v[74:75], s[0:1], 0, v[188:189]
	s_add_i32 m0, s60, 0x2000
	s_nop 0
	global_load_lds_dwordx4 v[74:75], off
	s_waitcnt vmcnt(6)
	s_barrier
	v_mfma_f32_16x16x32_bf16 v[30:33], v[198:201], v[106:109], v[30:33]
	v_mfma_f32_16x16x32_bf16 v[26:29], v[206:209], v[106:109], v[26:29]
	v_mfma_f32_16x16x32_bf16 v[22:25], v[198:201], v[130:133], v[22:25]
	v_mfma_f32_16x16x32_bf16 v[18:21], v[206:209], v[130:133], v[18:21]
	v_mfma_f32_16x16x32_bf16 v[14:17], v[198:201], v[154:157], v[14:17]
	v_mfma_f32_16x16x32_bf16 v[10:13], v[206:209], v[154:157], v[10:13]
	v_mfma_f32_16x16x32_bf16 v[6:9], v[198:201], v[170:173], v[6:9]
	v_mfma_f32_16x16x32_bf16 v[2:5], v[206:209], v[170:173], v[2:5]
	v_mfma_f32_16x16x32_bf16 v[30:33], v[202:205], v[118:121], v[30:33]
	v_mfma_f32_16x16x32_bf16 v[26:29], v[210:213], v[118:121], v[26:29]
	v_mfma_f32_16x16x32_bf16 v[22:25], v[202:205], v[142:145], v[22:25]
	v_mfma_f32_16x16x32_bf16 v[18:21], v[210:213], v[142:145], v[18:21]
	v_mfma_f32_16x16x32_bf16 v[14:17], v[202:205], v[158:161], v[14:17]
	v_mfma_f32_16x16x32_bf16 v[10:13], v[210:213], v[158:161], v[10:13]
	v_mfma_f32_16x16x32_bf16 v[6:9], v[202:205], v[174:177], v[6:9]
	v_mfma_f32_16x16x32_bf16 v[2:5], v[210:213], v[174:177], v[2:5]
	s_add_i32 s60, 0, 0x18000
	v_add_u32_e32 v102, s60, v229
	s_barrier
	ds_read_b128 v[74:77], v102
	ds_read_b128 v[78:81], v102 offset:1024
	ds_read_b128 v[98:101], v102 offset:2048
	ds_read_b128 v[102:105], v102 offset:3072
	s_add_u32 s0, s10, 0x100000
	s_addc_u32 s1, s11, 0
	s_mov_b32 m0, s22
	v_lshl_add_u64 v[198:199], s[0:1], 0, v[192:193]
	ds_read_b128 v[106:109], v231 offset:32768
	ds_read_b128 v[118:121], v231 offset:33792
	ds_read_b128 v[130:133], v231 offset:34816
	ds_read_b128 v[142:145], v231 offset:35840
	ds_read_b128 v[154:157], v231 offset:36864
	ds_read_b128 v[158:161], v231 offset:37888
	ds_read_b128 v[170:173], v231 offset:38912
	ds_read_b128 v[174:177], v231 offset:39936
	global_load_lds_dwordx4 v[198:199], off
	v_lshl_add_u64 v[198:199], s[0:1], 0, v[190:191]
	s_mov_b32 m0, s23
	s_nop 0
	global_load_lds_dwordx4 v[198:199], off
	s_waitcnt lgkmcnt(8)
	s_barrier
	s_waitcnt lgkmcnt(0)
	s_waitcnt lgkmcnt(0)
	v_mfma_f32_16x16x32_bf16 v[166:169], v[74:77], v[106:109], v[166:169]
	v_mfma_f32_16x16x32_bf16 v[162:165], v[98:101], v[106:109], v[162:165]
	v_mfma_f32_16x16x32_bf16 v[150:153], v[74:77], v[130:133], v[150:153]
	v_mfma_f32_16x16x32_bf16 v[146:149], v[98:101], v[130:133], v[146:149]
	v_mfma_f32_16x16x32_bf16 v[138:141], v[74:77], v[154:157], v[138:141]
	v_mfma_f32_16x16x32_bf16 v[134:137], v[98:101], v[154:157], v[134:137]
	v_mfma_f32_16x16x32_bf16 v[126:129], v[74:77], v[170:173], v[126:129]
	v_mfma_f32_16x16x32_bf16 v[122:125], v[98:101], v[170:173], v[122:125]
	v_mfma_f32_16x16x32_bf16 v[166:169], v[78:81], v[118:121], v[166:169]
	v_mfma_f32_16x16x32_bf16 v[162:165], v[102:105], v[118:121], v[162:165]
	v_mfma_f32_16x16x32_bf16 v[150:153], v[78:81], v[142:145], v[150:153]
	v_mfma_f32_16x16x32_bf16 v[146:149], v[102:105], v[142:145], v[146:149]
	v_mfma_f32_16x16x32_bf16 v[138:141], v[78:81], v[158:161], v[138:141]
	v_mfma_f32_16x16x32_bf16 v[134:137], v[102:105], v[158:161], v[134:137]
	v_mfma_f32_16x16x32_bf16 v[126:129], v[78:81], v[174:177], v[126:129]
	v_mfma_f32_16x16x32_bf16 v[122:125], v[102:105], v[174:177], v[122:125]
	s_barrier
	s_add_i32 s10, 0, 0x1c000
	s_add_i32 s0, s60, s19
	v_add_u32_e32 v210, s10, v229
	v_lshl_add_u64 v[184:185], v[184:185], 0, s[6:7]
	s_mov_b32 m0, s0
	ds_read_b128 v[198:201], v210
	ds_read_b128 v[202:205], v210 offset:1024
	ds_read_b128 v[206:209], v210 offset:2048
	ds_read_b128 v[210:213], v210 offset:3072
	global_load_lds_dwordx4 v[184:185], off
	v_lshl_add_u64 v[184:185], v[186:187], 0, s[6:7]
	s_add_i32 m0, s0, 0x2000
	s_nop 0
	global_load_lds_dwordx4 v[184:185], off
	s_barrier
	s_waitcnt lgkmcnt(0)
	s_waitcnt lgkmcnt(0)
	v_mfma_f32_16x16x32_bf16 v[70:73], v[198:201], v[106:109], v[70:73]
	v_mfma_f32_16x16x32_bf16 v[66:69], v[206:209], v[106:109], v[66:69]
	v_mfma_f32_16x16x32_bf16 v[62:65], v[198:201], v[130:133], v[62:65]
	v_mfma_f32_16x16x32_bf16 v[58:61], v[206:209], v[130:133], v[58:61]
	v_mfma_f32_16x16x32_bf16 v[54:57], v[198:201], v[154:157], v[54:57]
	v_mfma_f32_16x16x32_bf16 v[50:53], v[206:209], v[154:157], v[50:53]
	v_mfma_f32_16x16x32_bf16 v[46:49], v[198:201], v[170:173], v[46:49]
	v_mfma_f32_16x16x32_bf16 v[42:45], v[206:209], v[170:173], v[42:45]
	v_mfma_f32_16x16x32_bf16 v[70:73], v[202:205], v[118:121], v[70:73]
	v_mfma_f32_16x16x32_bf16 v[66:69], v[210:213], v[118:121], v[66:69]
	v_mfma_f32_16x16x32_bf16 v[62:65], v[202:205], v[142:145], v[62:65]
	v_mfma_f32_16x16x32_bf16 v[58:61], v[210:213], v[142:145], v[58:61]
	v_mfma_f32_16x16x32_bf16 v[54:57], v[202:205], v[158:161], v[54:57]
	v_mfma_f32_16x16x32_bf16 v[50:53], v[210:213], v[158:161], v[50:53]
	v_mfma_f32_16x16x32_bf16 v[46:49], v[202:205], v[174:177], v[46:49]
	v_mfma_f32_16x16x32_bf16 v[42:45], v[210:213], v[174:177], v[42:45]
	s_mov_b32 m0, s24
	v_lshl_add_u64 v[184:185], v[214:215], 0, s[6:7]
	s_barrier
	ds_read_b128 v[106:109], v231 offset:49152
	ds_read_b128 v[118:121], v231 offset:50176
	ds_read_b128 v[130:133], v231 offset:51200
	ds_read_b128 v[142:145], v231 offset:52224
	ds_read_b128 v[154:157], v231 offset:53248
	ds_read_b128 v[158:161], v231 offset:54272
	ds_read_b128 v[170:173], v231 offset:55296
	ds_read_b128 v[174:177], v231 offset:56320
	global_load_lds_dwordx4 v[184:185], off
	v_lshl_add_u64 v[184:185], v[216:217], 0, s[6:7]
	s_mov_b32 m0, s25
	s_nop 0
	global_load_lds_dwordx4 v[184:185], off
	s_barrier
; #define PG8_STAGE(bufoff, gbase, voff) do { _Pragma("unroll") for (int _i = 0; _i < 2; ++_i) \
;         __builtin_amdgcn_global_load_lds((const unsigned*)((const char*)(gbase) + (voff)[_i]), (LAS unsigned*)(lds + (bufoff) + ldsw + _i * 8192), 16, 0, 0); } while (0)
; #define PG8_MMA(ai, bj, At, Bt) do { __builtin_amdgcn_s_setprio(1); _Pragma("unroll") for (int m = 0; m < 4; ++m) _Pragma("unroll") for (int n = 0; n < 2; ++n) _Pragma("unroll") for (int k = 0; k < 2; ++k) \
;         acc[ai][bj][m][n] = __builtin_amdgcn_mfma_f32_16x16x32_bf16(Bt[n][k], At[m][k], acc[ai][bj][m][n], 0, 0, 0); __builtin_amdgcn_s_setprio(0); } while (0)
; #define PG8_WAIT_V(n) asm volatile("s_waitcnt vmcnt(" #n ")" ::: "memory")
; #define PG8_WAIT_L(n) asm volatile("s_waitcnt lgkmcnt(" #n ")" ::: "memory")
; #define PG8_BAR __builtin_amdgcn_s_barrier()
; #define PG8_SCHED __builtin_amdgcn_sched_barrier(0)
; template <class Epi>
; __device__ __forceinline__ void gemm_phase(LAS unsigned char* lds, const Gemm g, const StaticOrder& S, const Epi& E) {
;     ...
;             PG8_BAR; PG8_WAIT_L(0); PG8_MMA(1, 0, At, B0); PG8_BAR; PG8_SCHED;
;             PG8_STAGE(PG8_SB(1, 1), b3 + hstepB, voffB);
;             PG8_WAIT_V(6); PG8_BAR; PG8_MMA(1, 1, At, B1); PG8_BAR;
;         }
;         if constexpr (!Epi::AFTER_DRAIN) E(acc, cur, wr, wc, fr, fq, pre);
;     __device__ __forceinline__ void operator()(const f32x4 (&acc)[2][2][4][2], const Unit& u, int wr, int wc, int fr, int fq, const Pre&) const {
;         const int row0 = u.pm * BM + wr * 64 + fr, col0 = u.pn * BM + wc * 32 + 8 * fq;
;         f32x4 sc[2][2];
; #pragma unroll
;         for (int bj = 0; bj < 2; ++bj) { sc[bj][0] = *(const f32x4*)(scale + col0 + bj * HALF); sc[bj][1] = *(const f32x4*)(scale + col0 + bj * HALF + 4); }
; #pragma unroll
;         for (int bj = 0; bj < 2; ++bj) { const int c = col0 + bj * HALF;
;             u32x4 zv[8];
; #pragma unroll
;             for (int g8 = 0; g8 < 8; ++g8) zv[g8] = *(const u32x4*)(Z + (size_t)(row0 + (g8 >> 2) * HALF + (g8 & 3) * 16) * DE2 + c);
	s_waitcnt lgkmcnt(0)
	s_waitcnt lgkmcnt(0)
	v_mfma_f32_16x16x32_bf16 v[114:117], v[74:77], v[106:109], v[114:117]
	v_mfma_f32_16x16x32_bf16 v[94:97], v[74:77], v[130:133], v[94:97]
	v_mfma_f32_16x16x32_bf16 v[86:89], v[74:77], v[154:157], v[86:89]
	v_mfma_f32_16x16x32_bf16 v[34:37], v[74:77], v[170:173], v[34:37]
	v_mfma_f32_16x16x32_bf16 v[114:117], v[78:81], v[118:121], v[114:117]
	v_mfma_f32_16x16x32_bf16 v[110:113], v[98:101], v[106:109], v[110:113]
	v_mfma_f32_16x16x32_bf16 v[94:97], v[78:81], v[142:145], v[94:97]
	v_mfma_f32_16x16x32_bf16 v[90:93], v[98:101], v[130:133], v[90:93]
	v_mfma_f32_16x16x32_bf16 v[86:89], v[78:81], v[158:161], v[86:89]
	v_mfma_f32_16x16x32_bf16 v[82:85], v[98:101], v[154:157], v[82:85]
	v_mfma_f32_16x16x32_bf16 v[78:81], v[78:81], v[174:177], v[34:37]
	v_mfma_f32_16x16x32_bf16 v[34:37], v[98:101], v[170:173], v[38:41]
	v_mfma_f32_16x16x32_bf16 v[110:113], v[102:105], v[118:121], v[110:113]
	v_mfma_f32_16x16x32_bf16 v[90:93], v[102:105], v[142:145], v[90:93]
	v_mfma_f32_16x16x32_bf16 v[82:85], v[102:105], v[158:161], v[82:85]
	v_mfma_f32_16x16x32_bf16 v[74:77], v[102:105], v[174:177], v[34:37]
	s_barrier
	s_add_u32 s0, s4, 0x40080
	s_addc_u32 s1, s5, 0
	s_add_i32 s4, s10, s19
	v_lshl_add_u64 v[34:35], s[0:1], 0, v[0:1]
	s_mov_b32 m0, s4
	s_nop 0
	global_load_lds_dwordx4 v[34:35], off
	v_lshl_add_u64 v[34:35], s[0:1], 0, v[188:189]
	s_add_i32 m0, s4, 0x2000
	s_nop 0
	global_load_lds_dwordx4 v[34:35], off
	s_waitcnt vmcnt(6)
	s_barrier
	v_mfma_f32_16x16x32_bf16 v[30:33], v[198:201], v[106:109], v[30:33]
	v_mfma_f32_16x16x32_bf16 v[26:29], v[206:209], v[106:109], v[26:29]
	v_mfma_f32_16x16x32_bf16 v[22:25], v[198:201], v[130:133], v[22:25]
	v_mfma_f32_16x16x32_bf16 v[18:21], v[206:209], v[130:133], v[18:21]
	v_mfma_f32_16x16x32_bf16 v[14:17], v[198:201], v[154:157], v[14:17]
	v_mfma_f32_16x16x32_bf16 v[10:13], v[206:209], v[154:157], v[10:13]
	v_mfma_f32_16x16x32_bf16 v[6:9], v[198:201], v[170:173], v[6:9]
	v_mfma_f32_16x16x32_bf16 v[2:5], v[206:209], v[170:173], v[2:5]
	v_mfma_f32_16x16x32_bf16 v[30:33], v[202:205], v[118:121], v[30:33]
	v_mfma_f32_16x16x32_bf16 v[26:29], v[210:213], v[118:121], v[26:29]
	v_mfma_f32_16x16x32_bf16 v[22:25], v[202:205], v[142:145], v[22:25]
	v_mfma_f32_16x16x32_bf16 v[18:21], v[210:213], v[142:145], v[18:21]
	v_mfma_f32_16x16x32_bf16 v[14:17], v[202:205], v[158:161], v[14:17]
	v_mfma_f32_16x16x32_bf16 v[10:13], v[210:213], v[158:161], v[10:13]
	v_mfma_f32_16x16x32_bf16 v[6:9], v[202:205], v[174:177], v[6:9]
	v_mfma_f32_16x16x32_bf16 v[2:5], v[210:213], v[174:177], v[2:5]
	s_add_i32 s59, s59, 2
	s_add_u32 s53, s53, 0x100
	s_addc_u32 s58, s58, 0
	s_cmp_gt_u32 s59, 13
	s_mov_b64 s[0:1], s[8:9]
	s_barrier
	s_cbranch_scc0 .LBB0_603
	v_lshl_or_b32 v200, s34, 8, v230
	v_ashrrev_i32_e32 v201, 31, v200
	v_lshl_add_u32 v226, s27, 8, v228
	v_lshlrev_b64 v[216:217], 1, v[200:201]
	v_ashrrev_i32_e32 v227, 31, v226
	v_lshl_add_u64 v[106:107], s[46:47], 0, v[216:217]
	v_lshlrev_b64 v[204:205], 14, v[226:227]
	v_lshl_add_u64 v[38:39], v[200:201], 2, s[48:49]
	v_lshl_add_u64 v[108:109], v[106:107], 0, v[204:205]
	global_load_dwordx4 v[98:101], v[38:39], off offset:16
	global_load_dwordx4 v[102:105], v[38:39], off
	global_load_dwordx4 v[34:37], v[38:39], off offset:528
	s_nop 0
	global_load_dwordx4 v[38:41], v[38:39], off offset:512
	v_or_b32_e32 v224, 16, v226
	global_load_dwordx4 v[174:177], v[108:109], off
	v_ashrrev_i32_e32 v225, 31, v224
	v_or_b32_e32 v222, 32, v226
	v_lshlrev_b64 v[198:199], 14, v[224:225]
	v_ashrrev_i32_e32 v223, 31, v222
	v_or_b32_e32 v220, 48, v226
	v_lshl_add_u64 v[108:109], v[106:107], 0, v[198:199]
	v_lshlrev_b64 v[202:203], 14, v[222:223]
	v_ashrrev_i32_e32 v221, 31, v220
	v_add_u32_e32 v218, 0x80, v226
	global_load_dwordx4 v[170:173], v[108:109], off
	v_lshl_add_u64 v[108:109], v[106:107], 0, v[202:203]
	v_lshlrev_b64 v[206:207], 14, v[220:221]
	v_ashrrev_i32_e32 v219, 31, v218
	global_load_dwordx4 v[158:161], v[108:109], off
	v_lshl_add_u64 v[108:109], v[106:107], 0, v[206:207]
	v_lshlrev_b64 v[208:209], 14, v[218:219]
	global_load_dwordx4 v[154:157], v[108:109], off
	v_lshl_add_u64 v[108:109], v[106:107], 0, v[208:209]
	global_load_dwordx4 v[142:145], v[108:109], off
	v_add_u32_e32 v108, 0x90, v226
	v_ashrrev_i32_e32 v109, 31, v108
	v_lshlrev_b64 v[210:211], 14, v[108:109]
	v_lshl_add_u64 v[108:109], v[106:107], 0, v[210:211]
	global_load_dwordx4 v[130:133], v[108:109], off
	v_add_u32_e32 v108, 0xa0, v226
	v_ashrrev_i32_e32 v109, 31, v108
	v_lshlrev_b64 v[212:213], 14, v[108:109]
	v_lshl_add_u64 v[108:109], v[106:107], 0, v[212:213]
	global_load_dwordx4 v[118:121], v[108:109], off
	v_add_u32_e32 v108, 0xb0, v226
	v_ashrrev_i32_e32 v109, 31, v108
	v_lshlrev_b64 v[214:215], 14, v[108:109]
	v_lshl_add_u64 v[106:107], v[106:107], 0, v[214:215]
	global_load_dwordx4 v[106:109], v[106:107], off
	s_mov_b64 s[0:1], 0x120000
	s_mov_b32 s27, s52
	s_mov_b32 s34, s50
	s_mov_b64 s[8:9], s[56:57]
	s_waitcnt vmcnt(0)
; __device__ __forceinline__ unsigned cvt_pk_bf16(float lo, float hi) { unsigned r; asm volatile("v_cvt_pk_bf16_f32 %0, %1, %2" : "=v"(r) : "v"(lo), "v"(hi)); return r; }
; __device__ __forceinline__ float bf_lo(unsigned w) { return __uint_as_float(w << 16); }
; __device__ __forceinline__ float bf_hi(unsigned w) { return __uint_as_float(w & 0xffff0000u); }
; __device__ __forceinline__ float silu_f(float z) { return z * fast_rcp(1.0f + __builtin_amdgcn_exp2f(z * -1.44269504f)); }
;     __device__ __forceinline__ void operator()(const f32x4 (&acc)[2][2][4][2], const Unit& u, int wr, int wc, int fr, int fq, const Pre&) const {
;     ...
; #pragma unroll
;             for (int ai = 0; ai < 2; ++ai)
; #pragma unroll
;                 for (int m = 0; m < 4; ++m) { const int r = row0 + ai * HALF + m * 16;
;                     const u32x4 zw = zv[ai * 4 + m];
;                     const f32x4 a0 = acc[ai][bj][m][0] * sc[bj][0], a1 = acc[ai][bj][m][1] * sc[bj][1];
;                     u32x4 w;
;                     w.x = cvt_pk_bf16(a0[0] * silu_f(bf_lo(zw.x)), a0[1] * silu_f(bf_hi(zw.x)));
;                     w.y = cvt_pk_bf16(a0[2] * silu_f(bf_lo(zw.y)), a0[3] * silu_f(bf_hi(zw.y)));
;                     w.z = cvt_pk_bf16(a1[0] * silu_f(bf_lo(zw.z)), a1[1] * silu_f(bf_hi(zw.z)));
;                     w.w = cvt_pk_bf16(a1[2] * silu_f(bf_lo(zw.w)), a1[3] * silu_f(bf_hi(zw.w)));
;                     *(u32x4*)(O + (size_t)r * DE + c) = w; } }
	v_pk_mul_f32 v[146:147], v[146:147], v[98:99]
	v_pk_mul_f32 v[184:185], v[166:167], v[102:103]
	v_pk_mul_f32 v[166:167], v[164:165], v[100:101]
	v_pk_mul_f32 v[164:165], v[162:163], v[98:99]
	v_pk_mul_f32 v[168:169], v[168:169], v[104:105]
	v_lshlrev_b32_e32 v162, 16, v174
	v_mul_f32_e32 v163, 0xbfb8aa3b, v162
	v_exp_f32_e32 v163, v163
	v_pk_mul_f32 v[150:151], v[150:151], v[102:103]
	v_pk_mul_f32 v[152:153], v[152:153], v[104:105]
	v_pk_mul_f32 v[148:149], v[148:149], v[100:101]
	v_add_f32_e32 v163, 1.0, v163
	v_rcp_f32_e32 v163, v163
	v_pk_mul_f32 v[138:139], v[138:139], v[102:103]
	v_pk_mul_f32 v[140:141], v[140:141], v[104:105]
	v_pk_mul_f32 v[134:135], v[134:135], v[98:99]
	v_mul_f32_e32 v162, v163, v162
	v_and_b32_e32 v163, 0xffff0000, v174
	v_mul_f32_e32 v174, 0xbfb8aa3b, v163
	v_exp_f32_e32 v174, v174
	v_mul_f32_e32 v162, v184, v162
	v_pk_mul_f32 v[136:137], v[136:137], v[100:101]
	v_pk_mul_f32 v[126:127], v[126:127], v[102:103]
	v_add_f32_e32 v174, 1.0, v174
	v_rcp_f32_e32 v174, v174
	v_pk_mul_f32 v[128:129], v[128:129], v[104:105]
	v_pk_mul_f32 v[122:123], v[122:123], v[98:99]
	v_pk_mul_f32 v[124:125], v[124:125], v[100:101]
	v_mul_f32_e32 v163, v174, v163
	v_mul_f32_e32 v163, v185, v163
	v_cvt_pk_bf16_f32 v162, v162, v163
	v_lshlrev_b32_e32 v163, 16, v175
	v_mul_f32_e32 v174, 0xbfb8aa3b, v163
	v_exp_f32_e32 v174, v174
	v_pk_mul_f32 v[114:115], v[114:115], v[102:103]
	v_pk_mul_f32 v[116:117], v[116:117], v[104:105]
	v_pk_mul_f32 v[110:111], v[110:111], v[98:99]
	v_add_f32_e32 v174, 1.0, v174
	v_rcp_f32_e32 v174, v174
	v_pk_mul_f32 v[112:113], v[112:113], v[100:101]
	v_pk_mul_f32 v[94:95], v[94:95], v[102:103]
	v_pk_mul_f32 v[96:97], v[96:97], v[104:105]
	v_mul_f32_e32 v163, v174, v163
	v_mul_f32_e32 v163, v168, v163
	v_and_b32_e32 v168, 0xffff0000, v175
	v_mul_f32_e32 v174, 0xbfb8aa3b, v168
	v_exp_f32_e32 v174, v174
	v_pk_mul_f32 v[90:91], v[90:91], v[98:99]
	v_pk_mul_f32 v[92:93], v[92:93], v[100:101]
	v_pk_mul_f32 v[86:87], v[86:87], v[102:103]
	v_add_f32_e32 v174, 1.0, v174
	v_rcp_f32_e32 v174, v174
	v_pk_mul_f32 v[88:89], v[88:89], v[104:105]
	v_pk_mul_f32 v[82:83], v[82:83], v[98:99]
	v_pk_mul_f32 v[84:85], v[84:85], v[100:101]
	v_mul_f32_e32 v168, v174, v168
	v_mul_f32_e32 v168, v169, v168
	v_cvt_pk_bf16_f32 v163, v163, v168
	v_lshlrev_b32_e32 v168, 16, v176
	v_mul_f32_e32 v169, 0xbfb8aa3b, v168
	v_exp_f32_e32 v169, v169
	v_pk_mul_f32 v[78:79], v[78:79], v[102:103]
	v_pk_mul_f32 v[80:81], v[80:81], v[104:105]
	v_pk_mul_f32 v[74:75], v[74:75], v[98:99]
	v_add_f32_e32 v169, 1.0, v169
	v_rcp_f32_e32 v169, v169
	v_pk_mul_f32 v[76:77], v[76:77], v[100:101]
	v_pk_mul_f32 v[70:71], v[70:71], v[38:39]
	v_pk_mul_f32 v[72:73], v[72:73], v[40:41]
	v_mul_f32_e32 v168, v169, v168
	v_mul_f32_e32 v164, v164, v168
	v_and_b32_e32 v168, 0xffff0000, v176
	v_mul_f32_e32 v169, 0xbfb8aa3b, v168
	v_exp_f32_e32 v169, v169
	v_pk_mul_f32 v[66:67], v[66:67], v[34:35]
	v_pk_mul_f32 v[68:69], v[68:69], v[36:37]
	v_pk_mul_f32 v[62:63], v[62:63], v[38:39]
	v_add_f32_e32 v169, 1.0, v169
	v_rcp_f32_e32 v169, v169
	v_pk_mul_f32 v[64:65], v[64:65], v[40:41]
	v_pk_mul_f32 v[58:59], v[58:59], v[34:35]
	v_pk_mul_f32 v[60:61], v[60:61], v[36:37]
	v_mul_f32_e32 v168, v169, v168
	v_mul_f32_e32 v165, v165, v168
	v_cvt_pk_bf16_f32 v164, v164, v165
	v_lshlrev_b32_e32 v165, 16, v177
	v_mul_f32_e32 v168, 0xbfb8aa3b, v165
	v_exp_f32_e32 v168, v168
	v_pk_mul_f32 v[54:55], v[54:55], v[38:39]
	v_pk_mul_f32 v[56:57], v[56:57], v[40:41]
	v_pk_mul_f32 v[50:51], v[50:51], v[34:35]
	v_add_f32_e32 v168, 1.0, v168
	v_rcp_f32_e32 v168, v168
	v_pk_mul_f32 v[52:53], v[52:53], v[36:37]
	v_pk_mul_f32 v[46:47], v[46:47], v[38:39]
	v_pk_mul_f32 v[48:49], v[48:49], v[40:41]
	v_mul_f32_e32 v165, v168, v165
	v_mul_f32_e32 v165, v166, v165
	v_and_b32_e32 v166, 0xffff0000, v177
	v_mul_f32_e32 v168, 0xbfb8aa3b, v166
	v_exp_f32_e32 v168, v168
	v_pk_mul_f32 v[42:43], v[42:43], v[34:35]
	v_pk_mul_f32 v[44:45], v[44:45], v[36:37]
	v_pk_mul_f32 v[30:31], v[30:31], v[38:39]
	v_add_f32_e32 v168, 1.0, v168
	v_rcp_f32_e32 v168, v168
	v_pk_mul_f32 v[32:33], v[32:33], v[40:41]
	v_pk_mul_f32 v[26:27], v[26:27], v[34:35]
	v_pk_mul_f32 v[28:29], v[28:29], v[36:37]
	v_mul_f32_e32 v166, v168, v166
	v_mul_f32_e32 v166, v167, v166
	v_cvt_pk_bf16_f32 v165, v165, v166
	v_lshlrev_b64 v[166:167], 13, v[226:227]
	v_lshl_add_u64 v[166:167], s[44:45], 0, v[166:167]
	v_lshl_add_u64 v[166:167], v[166:167], 0, v[216:217]
	global_store_dwordx4 v[166:167], v[162:165], off
	v_pk_mul_f32 v[22:23], v[22:23], v[38:39]
	v_pk_mul_f32 v[24:25], v[24:25], v[40:41]
	v_lshlrev_b32_e32 v162, 16, v170
	v_mul_f32_e32 v163, 0xbfb8aa3b, v162
	v_exp_f32_e32 v163, v163
	v_pk_mul_f32 v[18:19], v[18:19], v[34:35]
	v_pk_mul_f32 v[20:21], v[20:21], v[36:37]
	v_pk_mul_f32 v[14:15], v[14:15], v[38:39]
	v_add_f32_e32 v163, 1.0, v163
	v_rcp_f32_e32 v163, v163
	v_pk_mul_f32 v[16:17], v[16:17], v[40:41]
	v_pk_mul_f32 v[10:11], v[10:11], v[34:35]
	v_pk_mul_f32 v[12:13], v[12:13], v[36:37]
	v_mul_f32_e32 v162, v163, v162
	v_mul_f32_e32 v150, v150, v162
	v_and_b32_e32 v162, 0xffff0000, v170
	v_mul_f32_e32 v163, 0xbfb8aa3b, v162
	v_exp_f32_e32 v163, v163
	v_pk_mul_f32 v[6:7], v[6:7], v[38:39]
	v_pk_mul_f32 v[8:9], v[8:9], v[40:41]
	v_pk_mul_f32 v[2:3], v[2:3], v[34:35]
	v_add_f32_e32 v163, 1.0, v163
	v_rcp_f32_e32 v163, v163
	v_pk_mul_f32 v[4:5], v[4:5], v[36:37]
	v_mul_f32_e32 v162, v163, v162
	v_mul_f32_e32 v151, v151, v162
	v_cvt_pk_bf16_f32 v150, v150, v151
	v_lshlrev_b32_e32 v151, 16, v171
	v_mul_f32_e32 v162, 0xbfb8aa3b, v151
	v_exp_f32_e32 v162, v162
	s_nop 0
	v_add_f32_e32 v162, 1.0, v162
	v_rcp_f32_e32 v162, v162
	s_nop 0
; __device__ __forceinline__ unsigned cvt_pk_bf16(float lo, float hi) { unsigned r; asm volatile("v_cvt_pk_bf16_f32 %0, %1, %2" : "=v"(r) : "v"(lo), "v"(hi)); return r; }
; __device__ __forceinline__ float bf_lo(unsigned w) { return __uint_as_float(w << 16); }
; __device__ __forceinline__ float bf_hi(unsigned w) { return __uint_as_float(w & 0xffff0000u); }
; __device__ __forceinline__ float silu_f(float z) { return z * fast_rcp(1.0f + __builtin_amdgcn_exp2f(z * -1.44269504f)); }
;     __device__ __forceinline__ void operator()(const f32x4 (&acc)[2][2][4][2], const Unit& u, int wr, int wc, int fr, int fq, const Pre&) const {
;     ...
; #pragma unroll
;             for (int ai = 0; ai < 2; ++ai)
; #pragma unroll
;                 for (int m = 0; m < 4; ++m) { const int r = row0 + ai * HALF + m * 16;
;                     const u32x4 zw = zv[ai * 4 + m];
;                     const f32x4 a0 = acc[ai][bj][m][0] * sc[bj][0], a1 = acc[ai][bj][m][1] * sc[bj][1];
;                     u32x4 w;
;                     w.x = cvt_pk_bf16(a0[0] * silu_f(bf_lo(zw.x)), a0[1] * silu_f(bf_hi(zw.x)));
;                     w.y = cvt_pk_bf16(a0[2] * silu_f(bf_lo(zw.y)), a0[3] * silu_f(bf_hi(zw.y)));
;                     w.z = cvt_pk_bf16(a1[0] * silu_f(bf_lo(zw.z)), a1[1] * silu_f(bf_hi(zw.z)));
;                     w.w = cvt_pk_bf16(a1[2] * silu_f(bf_lo(zw.w)), a1[3] * silu_f(bf_hi(zw.w)));
;                     *(u32x4*)(O + (size_t)r * DE + c) = w; } }
	v_mul_f32_e32 v151, v162, v151
	v_mul_f32_e32 v151, v152, v151
	v_and_b32_e32 v152, 0xffff0000, v171
	v_mul_f32_e32 v162, 0xbfb8aa3b, v152
	v_exp_f32_e32 v162, v162
	s_nop 0
	v_add_f32_e32 v162, 1.0, v162
	v_rcp_f32_e32 v162, v162
	s_nop 0
	v_mul_f32_e32 v152, v162, v152
	v_mul_f32_e32 v152, v153, v152
	v_cvt_pk_bf16_f32 v151, v151, v152
	v_lshlrev_b32_e32 v152, 16, v172
	v_mul_f32_e32 v153, 0xbfb8aa3b, v152
	v_exp_f32_e32 v153, v153
	s_nop 0
	v_add_f32_e32 v153, 1.0, v153
	v_rcp_f32_e32 v153, v153
	s_nop 0
	v_mul_f32_e32 v152, v153, v152
	v_mul_f32_e32 v146, v146, v152
	v_and_b32_e32 v152, 0xffff0000, v172
	v_mul_f32_e32 v153, 0xbfb8aa3b, v152
	v_exp_f32_e32 v153, v153
	s_nop 0
	v_add_f32_e32 v153, 1.0, v153
	v_rcp_f32_e32 v153, v153
	s_nop 0
	v_mul_f32_e32 v152, v153, v152
	v_mul_f32_e32 v147, v147, v152
	v_cvt_pk_bf16_f32 v152, v146, v147
	v_lshlrev_b32_e32 v146, 16, v173
	v_mul_f32_e32 v147, 0xbfb8aa3b, v146
	v_exp_f32_e32 v147, v147
	s_nop 0
	v_add_f32_e32 v147, 1.0, v147
	v_rcp_f32_e32 v147, v147
	s_nop 0
	v_mul_f32_e32 v146, v147, v146
	v_and_b32_e32 v147, 0xffff0000, v173
	v_mul_f32_e32 v146, v148, v146
	v_mul_f32_e32 v148, 0xbfb8aa3b, v147
	v_exp_f32_e32 v148, v148
	s_nop 0
	v_add_f32_e32 v148, 1.0, v148
	v_rcp_f32_e32 v148, v148
	s_nop 0
	v_mul_f32_e32 v147, v148, v147
	v_lshlrev_b32_e32 v148, 16, v158
	v_mul_f32_e32 v147, v149, v147
	v_mul_f32_e32 v149, 0xbfb8aa3b, v148
	v_exp_f32_e32 v149, v149
	v_cvt_pk_bf16_f32 v153, v146, v147
	v_lshlrev_b64 v[146:147], 13, v[224:225]
	v_lshl_add_u64 v[146:147], s[44:45], 0, v[146:147]
	v_add_f32_e32 v149, 1.0, v149
	v_rcp_f32_e32 v149, v149
	v_lshl_add_u64 v[146:147], v[146:147], 0, v[216:217]
	global_store_dwordx4 v[146:147], v[150:153], off
	v_mul_f32_e32 v148, v149, v148
	v_mul_f32_e32 v138, v138, v148
	v_and_b32_e32 v148, 0xffff0000, v158
	v_mul_f32_e32 v149, 0xbfb8aa3b, v148
	v_exp_f32_e32 v149, v149
	s_nop 0
	v_add_f32_e32 v149, 1.0, v149
	v_rcp_f32_e32 v149, v149
	s_nop 0
	v_mul_f32_e32 v148, v149, v148
	v_mul_f32_e32 v139, v139, v148
	v_cvt_pk_bf16_f32 v138, v138, v139
	v_lshlrev_b32_e32 v139, 16, v159
	v_mul_f32_e32 v148, 0xbfb8aa3b, v139
	v_exp_f32_e32 v148, v148
	s_nop 0
	v_add_f32_e32 v148, 1.0, v148
	v_rcp_f32_e32 v148, v148
	s_nop 0
	v_mul_f32_e32 v139, v148, v139
	v_mul_f32_e32 v139, v140, v139
	v_and_b32_e32 v140, 0xffff0000, v159
	v_mul_f32_e32 v148, 0xbfb8aa3b, v140
	v_exp_f32_e32 v148, v148
	s_nop 0
	v_add_f32_e32 v148, 1.0, v148
	v_rcp_f32_e32 v148, v148
	s_nop 0
	v_mul_f32_e32 v140, v148, v140
	v_mul_f32_e32 v140, v141, v140
	v_cvt_pk_bf16_f32 v139, v139, v140
	v_lshlrev_b32_e32 v140, 16, v160
	v_mul_f32_e32 v141, 0xbfb8aa3b, v140
	v_exp_f32_e32 v141, v141
	s_nop 0
	v_add_f32_e32 v141, 1.0, v141
	v_rcp_f32_e32 v141, v141
	s_nop 0
	v_mul_f32_e32 v140, v141, v140
	v_mul_f32_e32 v134, v134, v140
	v_and_b32_e32 v140, 0xffff0000, v160
	v_mul_f32_e32 v141, 0xbfb8aa3b, v140
	v_exp_f32_e32 v141, v141
	s_nop 0
	v_add_f32_e32 v141, 1.0, v141
	v_rcp_f32_e32 v141, v141
	s_nop 0
	v_mul_f32_e32 v140, v141, v140
	v_mul_f32_e32 v135, v135, v140
	v_cvt_pk_bf16_f32 v140, v134, v135
	v_lshlrev_b32_e32 v134, 16, v161
	v_mul_f32_e32 v135, 0xbfb8aa3b, v134
	v_exp_f32_e32 v135, v135
	s_nop 0
	v_add_f32_e32 v135, 1.0, v135
	v_rcp_f32_e32 v135, v135
	s_nop 0
	v_mul_f32_e32 v134, v135, v134
	v_and_b32_e32 v135, 0xffff0000, v161
	v_mul_f32_e32 v134, v136, v134
	v_mul_f32_e32 v136, 0xbfb8aa3b, v135
	v_exp_f32_e32 v136, v136
	s_nop 0
	v_add_f32_e32 v136, 1.0, v136
	v_rcp_f32_e32 v136, v136
	s_nop 0
	v_mul_f32_e32 v135, v136, v135
	v_lshlrev_b32_e32 v136, 16, v154
	v_mul_f32_e32 v135, v137, v135
	v_mul_f32_e32 v137, 0xbfb8aa3b, v136
	v_exp_f32_e32 v137, v137
	v_cvt_pk_bf16_f32 v141, v134, v135
	v_lshlrev_b64 v[134:135], 13, v[222:223]
	v_lshl_add_u64 v[134:135], s[44:45], 0, v[134:135]
	v_add_f32_e32 v137, 1.0, v137
	v_rcp_f32_e32 v137, v137
	v_lshl_add_u64 v[134:135], v[134:135], 0, v[216:217]
	global_store_dwordx4 v[134:135], v[138:141], off
	v_mul_f32_e32 v136, v137, v136
	v_mul_f32_e32 v126, v126, v136
	v_and_b32_e32 v136, 0xffff0000, v154
	v_mul_f32_e32 v137, 0xbfb8aa3b, v136
	v_exp_f32_e32 v137, v137
	s_nop 0
	v_add_f32_e32 v137, 1.0, v137
	v_rcp_f32_e32 v137, v137
	s_nop 0
	v_mul_f32_e32 v136, v137, v136
	v_mul_f32_e32 v127, v127, v136
	v_cvt_pk_bf16_f32 v126, v126, v127
	v_lshlrev_b32_e32 v127, 16, v155
	v_mul_f32_e32 v136, 0xbfb8aa3b, v127
	v_exp_f32_e32 v136, v136
	s_nop 0
	v_add_f32_e32 v136, 1.0, v136
	v_rcp_f32_e32 v136, v136
	s_nop 0
	v_mul_f32_e32 v127, v136, v127
	v_mul_f32_e32 v127, v128, v127
	v_and_b32_e32 v128, 0xffff0000, v155
	v_mul_f32_e32 v136, 0xbfb8aa3b, v128
	v_exp_f32_e32 v136, v136
	s_nop 0
	v_add_f32_e32 v136, 1.0, v136
	v_rcp_f32_e32 v136, v136
	s_nop 0
	v_mul_f32_e32 v128, v136, v128
	v_mul_f32_e32 v128, v129, v128
	v_cvt_pk_bf16_f32 v127, v127, v128
	v_lshlrev_b32_e32 v128, 16, v156
	v_mul_f32_e32 v129, 0xbfb8aa3b, v128
	v_exp_f32_e32 v129, v129
	s_nop 0
	v_add_f32_e32 v129, 1.0, v129
	v_rcp_f32_e32 v129, v129
	s_nop 0
	v_mul_f32_e32 v128, v129, v128
	v_mul_f32_e32 v122, v122, v128
	v_and_b32_e32 v128, 0xffff0000, v156
	v_mul_f32_e32 v129, 0xbfb8aa3b, v128
	v_exp_f32_e32 v129, v129
	s_nop 0
	v_add_f32_e32 v129, 1.0, v129
	v_rcp_f32_e32 v129, v129
	s_nop 0
	v_mul_f32_e32 v128, v129, v128
	v_mul_f32_e32 v123, v123, v128
	v_cvt_pk_bf16_f32 v128, v122, v123
	v_lshlrev_b32_e32 v122, 16, v157
	v_mul_f32_e32 v123, 0xbfb8aa3b, v122
	v_exp_f32_e32 v123, v123
	s_nop 0
	v_add_f32_e32 v123, 1.0, v123
	v_rcp_f32_e32 v123, v123
	s_nop 0
	v_mul_f32_e32 v122, v123, v122
	v_and_b32_e32 v123, 0xffff0000, v157
	v_mul_f32_e32 v122, v124, v122
	v_mul_f32_e32 v124, 0xbfb8aa3b, v123
; __device__ __forceinline__ unsigned cvt_pk_bf16(float lo, float hi) { unsigned r; asm volatile("v_cvt_pk_bf16_f32 %0, %1, %2" : "=v"(r) : "v"(lo), "v"(hi)); return r; }
; __device__ __forceinline__ float bf_lo(unsigned w) { return __uint_as_float(w << 16); }
; __device__ __forceinline__ float bf_hi(unsigned w) { return __uint_as_float(w & 0xffff0000u); }
; __device__ __forceinline__ float silu_f(float z) { return z * fast_rcp(1.0f + __builtin_amdgcn_exp2f(z * -1.44269504f)); }
;     __device__ __forceinline__ void operator()(const f32x4 (&acc)[2][2][4][2], const Unit& u, int wr, int wc, int fr, int fq, const Pre&) const {
;     ...
; #pragma unroll
;             for (int ai = 0; ai < 2; ++ai)
; #pragma unroll
;                 for (int m = 0; m < 4; ++m) { const int r = row0 + ai * HALF + m * 16;
;                     const u32x4 zw = zv[ai * 4 + m];
;                     const f32x4 a0 = acc[ai][bj][m][0] * sc[bj][0], a1 = acc[ai][bj][m][1] * sc[bj][1];
;                     u32x4 w;
;                     w.x = cvt_pk_bf16(a0[0] * silu_f(bf_lo(zw.x)), a0[1] * silu_f(bf_hi(zw.x)));
;                     w.y = cvt_pk_bf16(a0[2] * silu_f(bf_lo(zw.y)), a0[3] * silu_f(bf_hi(zw.y)));
;                     w.z = cvt_pk_bf16(a1[0] * silu_f(bf_lo(zw.z)), a1[1] * silu_f(bf_hi(zw.z)));
;                     w.w = cvt_pk_bf16(a1[2] * silu_f(bf_lo(zw.w)), a1[3] * silu_f(bf_hi(zw.w)));
;                     *(u32x4*)(O + (size_t)r * DE + c) = w; } }
	v_exp_f32_e32 v124, v124
	s_nop 0
	v_add_f32_e32 v124, 1.0, v124
	v_rcp_f32_e32 v124, v124
	s_nop 0
	v_mul_f32_e32 v123, v124, v123
	v_lshlrev_b32_e32 v124, 16, v142
	v_mul_f32_e32 v123, v125, v123
	v_mul_f32_e32 v125, 0xbfb8aa3b, v124
	v_exp_f32_e32 v125, v125
	v_cvt_pk_bf16_f32 v129, v122, v123
	v_lshlrev_b64 v[122:123], 13, v[220:221]
	v_lshl_add_u64 v[122:123], s[44:45], 0, v[122:123]
	v_add_f32_e32 v125, 1.0, v125
	v_rcp_f32_e32 v125, v125
	v_lshl_add_u64 v[122:123], v[122:123], 0, v[216:217]
	global_store_dwordx4 v[122:123], v[126:129], off
	v_mul_f32_e32 v124, v125, v124
	v_mul_f32_e32 v114, v114, v124
	v_and_b32_e32 v124, 0xffff0000, v142
	v_mul_f32_e32 v125, 0xbfb8aa3b, v124
	v_exp_f32_e32 v125, v125
	s_nop 0
	v_add_f32_e32 v125, 1.0, v125
	v_rcp_f32_e32 v125, v125
	s_nop 0
	v_mul_f32_e32 v124, v125, v124
	v_mul_f32_e32 v115, v115, v124
	v_cvt_pk_bf16_f32 v114, v114, v115
	v_lshlrev_b32_e32 v115, 16, v143
	v_mul_f32_e32 v124, 0xbfb8aa3b, v115
	v_exp_f32_e32 v124, v124
	s_nop 0
	v_add_f32_e32 v124, 1.0, v124
	v_rcp_f32_e32 v124, v124
	s_nop 0
	v_mul_f32_e32 v115, v124, v115
	v_mul_f32_e32 v115, v116, v115
	v_and_b32_e32 v116, 0xffff0000, v143
	v_mul_f32_e32 v124, 0xbfb8aa3b, v116
	v_exp_f32_e32 v124, v124
	s_nop 0
	v_add_f32_e32 v124, 1.0, v124
	v_rcp_f32_e32 v124, v124
	s_nop 0
	v_mul_f32_e32 v116, v124, v116
	v_mul_f32_e32 v116, v117, v116
	v_cvt_pk_bf16_f32 v115, v115, v116
	v_lshlrev_b32_e32 v116, 16, v144
	v_mul_f32_e32 v117, 0xbfb8aa3b, v116
	v_exp_f32_e32 v117, v117
	s_nop 0
	v_add_f32_e32 v117, 1.0, v117
	v_rcp_f32_e32 v117, v117
	s_nop 0
	v_mul_f32_e32 v116, v117, v116
	v_mul_f32_e32 v110, v110, v116
	v_and_b32_e32 v116, 0xffff0000, v144
	v_mul_f32_e32 v117, 0xbfb8aa3b, v116
	v_exp_f32_e32 v117, v117
	s_nop 0
	v_add_f32_e32 v117, 1.0, v117
	v_rcp_f32_e32 v117, v117
	s_nop 0
	v_mul_f32_e32 v116, v117, v116
	v_mul_f32_e32 v111, v111, v116
	v_cvt_pk_bf16_f32 v116, v110, v111
	v_lshlrev_b32_e32 v110, 16, v145
	v_mul_f32_e32 v111, 0xbfb8aa3b, v110
	v_exp_f32_e32 v111, v111
	s_nop 0
	v_add_f32_e32 v111, 1.0, v111
	v_rcp_f32_e32 v111, v111
	s_nop 0
	v_mul_f32_e32 v110, v111, v110
	v_and_b32_e32 v111, 0xffff0000, v145
	v_mul_f32_e32 v110, v112, v110
	v_mul_f32_e32 v112, 0xbfb8aa3b, v111
	v_exp_f32_e32 v112, v112
	s_nop 0
	v_add_f32_e32 v112, 1.0, v112
	v_rcp_f32_e32 v112, v112
	s_nop 0
	v_mul_f32_e32 v111, v112, v111
	v_mul_f32_e32 v111, v113, v111
	v_cvt_pk_bf16_f32 v117, v110, v111
	v_lshlrev_b64 v[110:111], 13, v[218:219]
	v_lshl_add_u64 v[110:111], s[44:45], 0, v[110:111]
	v_lshl_add_u64 v[112:113], v[110:111], 0, v[216:217]
	v_lshlrev_b32_e32 v110, 16, v130
	v_mul_f32_e32 v111, 0xbfb8aa3b, v110
	v_exp_f32_e32 v111, v111
	global_store_dwordx4 v[112:113], v[114:117], off
	v_add_f32_e32 v111, 1.0, v111
	v_rcp_f32_e32 v111, v111
	s_nop 0
	v_mul_f32_e32 v110, v111, v110
	v_mul_f32_e32 v94, v94, v110
	v_and_b32_e32 v110, 0xffff0000, v130
	v_mul_f32_e32 v111, 0xbfb8aa3b, v110
	v_exp_f32_e32 v111, v111
	s_nop 0
	v_add_f32_e32 v111, 1.0, v111
	v_rcp_f32_e32 v111, v111
	s_nop 0
	v_mul_f32_e32 v110, v111, v110
	v_mul_f32_e32 v95, v95, v110
	v_cvt_pk_bf16_f32 v94, v94, v95
	v_lshlrev_b32_e32 v95, 16, v131
	v_mul_f32_e32 v110, 0xbfb8aa3b, v95
	v_exp_f32_e32 v110, v110
	s_nop 0
	v_add_f32_e32 v110, 1.0, v110
	v_rcp_f32_e32 v110, v110
	s_nop 0
	v_mul_f32_e32 v95, v110, v95
	v_mul_f32_e32 v95, v96, v95
	v_and_b32_e32 v96, 0xffff0000, v131
	v_mul_f32_e32 v110, 0xbfb8aa3b, v96
	v_exp_f32_e32 v110, v110
	s_nop 0
	v_add_f32_e32 v110, 1.0, v110
	v_rcp_f32_e32 v110, v110
	s_nop 0
	v_mul_f32_e32 v96, v110, v96
	v_mul_f32_e32 v96, v97, v96
	v_cvt_pk_bf16_f32 v95, v95, v96
	v_lshlrev_b32_e32 v96, 16, v132
	v_mul_f32_e32 v97, 0xbfb8aa3b, v96
	v_exp_f32_e32 v97, v97
	v_lshl_add_u64 v[110:111], v[166:167], 0, s[0:1]
	s_mov_b64 s[0:1], 0x140000
	v_lshl_add_u64 v[114:115], v[166:167], 0, s[0:1]
	v_add_f32_e32 v97, 1.0, v97
	v_rcp_f32_e32 v97, v97
	s_mov_b64 s[0:1], 0x160000
	v_mul_f32_e32 v96, v97, v96
	v_mul_f32_e32 v90, v90, v96
	v_and_b32_e32 v96, 0xffff0000, v132
	v_mul_f32_e32 v97, 0xbfb8aa3b, v96
	v_exp_f32_e32 v97, v97
	s_nop 0
	v_add_f32_e32 v97, 1.0, v97
	v_rcp_f32_e32 v97, v97
	s_nop 0
	v_mul_f32_e32 v96, v97, v96
	v_mul_f32_e32 v91, v91, v96
	v_cvt_pk_bf16_f32 v96, v90, v91
	v_lshlrev_b32_e32 v90, 16, v133
	v_mul_f32_e32 v91, 0xbfb8aa3b, v90
	v_exp_f32_e32 v91, v91
	s_nop 0
	v_add_f32_e32 v91, 1.0, v91
	v_rcp_f32_e32 v91, v91
	s_nop 0
	v_mul_f32_e32 v90, v91, v90
	v_and_b32_e32 v91, 0xffff0000, v133
	v_mul_f32_e32 v90, v92, v90
	v_mul_f32_e32 v92, 0xbfb8aa3b, v91
	v_exp_f32_e32 v92, v92
	s_nop 0
	v_add_f32_e32 v92, 1.0, v92
	v_rcp_f32_e32 v92, v92
	s_nop 0
	v_mul_f32_e32 v91, v92, v91
	v_mul_f32_e32 v91, v93, v91
	v_cvt_pk_bf16_f32 v97, v90, v91
	v_add_co_u32_e32 v90, vcc, s41, v166
	s_nop 1
	v_addc_co_u32_e32 v91, vcc, 0, v167, vcc
	global_store_dwordx4 v[90:91], v[94:97], off
	v_lshlrev_b32_e32 v90, 16, v118
	v_mul_f32_e32 v91, 0xbfb8aa3b, v90
	v_exp_f32_e32 v91, v91
	s_nop 0
	v_add_f32_e32 v91, 1.0, v91
	v_rcp_f32_e32 v91, v91
	s_nop 0
	v_mul_f32_e32 v90, v91, v90
	v_mul_f32_e32 v86, v86, v90
	v_and_b32_e32 v90, 0xffff0000, v118
	v_mul_f32_e32 v91, 0xbfb8aa3b, v90
	v_exp_f32_e32 v91, v91
	s_nop 0
	v_add_f32_e32 v91, 1.0, v91
	v_rcp_f32_e32 v91, v91
	s_nop 0
	v_mul_f32_e32 v90, v91, v90
	v_mul_f32_e32 v87, v87, v90
	v_cvt_pk_bf16_f32 v86, v86, v87
	v_lshlrev_b32_e32 v87, 16, v119
	v_mul_f32_e32 v90, 0xbfb8aa3b, v87
	v_exp_f32_e32 v90, v90
	s_nop 0
	v_add_f32_e32 v90, 1.0, v90
	v_rcp_f32_e32 v90, v90
	s_nop 0
	v_mul_f32_e32 v87, v90, v87
	v_mul_f32_e32 v87, v88, v87
	v_and_b32_e32 v88, 0xffff0000, v119
	v_mul_f32_e32 v90, 0xbfb8aa3b, v88
; __device__ __forceinline__ unsigned cvt_pk_bf16(float lo, float hi) { unsigned r; asm volatile("v_cvt_pk_bf16_f32 %0, %1, %2" : "=v"(r) : "v"(lo), "v"(hi)); return r; }
; __device__ __forceinline__ float bf_lo(unsigned w) { return __uint_as_float(w << 16); }
; __device__ __forceinline__ float bf_hi(unsigned w) { return __uint_as_float(w & 0xffff0000u); }
; __device__ __forceinline__ float silu_f(float z) { return z * fast_rcp(1.0f + __builtin_amdgcn_exp2f(z * -1.44269504f)); }
;     __device__ __forceinline__ void operator()(const f32x4 (&acc)[2][2][4][2], const Unit& u, int wr, int wc, int fr, int fq, const Pre&) const {
;     ...
;             for (int g8 = 0; g8 < 8; ++g8) zv[g8] = *(const u32x4*)(Z + (size_t)(row0 + (g8 >> 2) * HALF + (g8 & 3) * 16) * DE2 + c);
; #pragma unroll
;             for (int ai = 0; ai < 2; ++ai)
; #pragma unroll
;                 for (int m = 0; m < 4; ++m) { const int r = row0 + ai * HALF + m * 16;
;                     const u32x4 zw = zv[ai * 4 + m];
;                     const f32x4 a0 = acc[ai][bj][m][0] * sc[bj][0], a1 = acc[ai][bj][m][1] * sc[bj][1];
;                     u32x4 w;
;                     w.x = cvt_pk_bf16(a0[0] * silu_f(bf_lo(zw.x)), a0[1] * silu_f(bf_hi(zw.x)));
;                     w.y = cvt_pk_bf16(a0[2] * silu_f(bf_lo(zw.y)), a0[3] * silu_f(bf_hi(zw.y)));
;                     w.z = cvt_pk_bf16(a1[0] * silu_f(bf_lo(zw.z)), a1[1] * silu_f(bf_hi(zw.z)));
;                     w.w = cvt_pk_bf16(a1[2] * silu_f(bf_lo(zw.w)), a1[3] * silu_f(bf_hi(zw.w)));
;                     *(u32x4*)(O + (size_t)r * DE + c) = w; } }
	v_exp_f32_e32 v90, v90
	s_nop 0
	v_add_f32_e32 v90, 1.0, v90
	v_rcp_f32_e32 v90, v90
	s_nop 0
	v_mul_f32_e32 v88, v90, v88
	v_mul_f32_e32 v88, v89, v88
	v_cvt_pk_bf16_f32 v87, v87, v88
	v_lshlrev_b32_e32 v88, 16, v120
	v_mul_f32_e32 v89, 0xbfb8aa3b, v88
	v_exp_f32_e32 v89, v89
	s_nop 0
	v_add_f32_e32 v89, 1.0, v89
	v_rcp_f32_e32 v89, v89
	s_nop 0
	v_mul_f32_e32 v88, v89, v88
	v_mul_f32_e32 v82, v82, v88
	v_and_b32_e32 v88, 0xffff0000, v120
	v_mul_f32_e32 v89, 0xbfb8aa3b, v88
	v_exp_f32_e32 v89, v89
	s_nop 0
	v_add_f32_e32 v89, 1.0, v89
	v_rcp_f32_e32 v89, v89
	s_nop 0
	v_mul_f32_e32 v88, v89, v88
	v_mul_f32_e32 v83, v83, v88
	v_cvt_pk_bf16_f32 v88, v82, v83
	v_lshlrev_b32_e32 v82, 16, v121
	v_mul_f32_e32 v83, 0xbfb8aa3b, v82
	v_exp_f32_e32 v83, v83
	s_nop 0
	v_add_f32_e32 v83, 1.0, v83
	v_rcp_f32_e32 v83, v83
	s_nop 0
	v_mul_f32_e32 v82, v83, v82
	v_and_b32_e32 v83, 0xffff0000, v121
	v_mul_f32_e32 v82, v84, v82
	v_mul_f32_e32 v84, 0xbfb8aa3b, v83
	v_exp_f32_e32 v84, v84
	s_nop 0
	v_add_f32_e32 v84, 1.0, v84
	v_rcp_f32_e32 v84, v84
	s_nop 0
	v_mul_f32_e32 v83, v84, v83
	v_mul_f32_e32 v83, v85, v83
	v_cvt_pk_bf16_f32 v89, v82, v83
	v_add_co_u32_e32 v82, vcc, s65, v166
	s_nop 1
	v_addc_co_u32_e32 v83, vcc, 0, v167, vcc
	global_store_dwordx4 v[82:83], v[86:89], off
	v_lshlrev_b32_e32 v82, 16, v106
	v_mul_f32_e32 v83, 0xbfb8aa3b, v82
	v_exp_f32_e32 v83, v83
	s_nop 0
	v_add_f32_e32 v83, 1.0, v83
	v_rcp_f32_e32 v83, v83
	s_nop 0
	v_mul_f32_e32 v82, v83, v82
	v_mul_f32_e32 v78, v78, v82
	v_and_b32_e32 v82, 0xffff0000, v106
	v_mul_f32_e32 v83, 0xbfb8aa3b, v82
	v_exp_f32_e32 v83, v83
	s_nop 0
	v_add_f32_e32 v83, 1.0, v83
	v_rcp_f32_e32 v83, v83
	s_nop 0
	v_mul_f32_e32 v82, v83, v82
	v_mul_f32_e32 v79, v79, v82
	v_cvt_pk_bf16_f32 v78, v78, v79
	v_lshlrev_b32_e32 v79, 16, v107
	v_mul_f32_e32 v82, 0xbfb8aa3b, v79
	v_exp_f32_e32 v82, v82
	s_nop 0
	v_add_f32_e32 v82, 1.0, v82
	v_rcp_f32_e32 v82, v82
	s_nop 0
	v_mul_f32_e32 v79, v82, v79
	v_mul_f32_e32 v79, v80, v79
	v_and_b32_e32 v80, 0xffff0000, v107
	v_mul_f32_e32 v82, 0xbfb8aa3b, v80
	v_exp_f32_e32 v82, v82
	v_lshl_add_u64 v[106:107], v[166:167], 0, s[0:1]
	s_mov_b64 s[0:1], s[54:55]
	v_add_f32_e32 v82, 1.0, v82
	v_rcp_f32_e32 v82, v82
	s_nop 0
	v_mul_f32_e32 v80, v82, v80
	v_mul_f32_e32 v80, v81, v80
	v_cvt_pk_bf16_f32 v79, v79, v80
	v_lshlrev_b32_e32 v80, 16, v108
	v_mul_f32_e32 v81, 0xbfb8aa3b, v80
	v_exp_f32_e32 v81, v81
	s_nop 0
	v_add_f32_e32 v81, 1.0, v81
	v_rcp_f32_e32 v81, v81
	s_nop 0
	v_mul_f32_e32 v80, v81, v80
	v_mul_f32_e32 v74, v74, v80
	v_and_b32_e32 v80, 0xffff0000, v108
	v_mul_f32_e32 v81, 0xbfb8aa3b, v80
	v_exp_f32_e32 v81, v81
	s_nop 0
	v_add_f32_e32 v81, 1.0, v81
	v_rcp_f32_e32 v81, v81
	s_nop 0
	v_mul_f32_e32 v80, v81, v80
	v_mul_f32_e32 v75, v75, v80
	v_cvt_pk_bf16_f32 v80, v74, v75
	v_lshlrev_b32_e32 v74, 16, v109
	v_mul_f32_e32 v75, 0xbfb8aa3b, v74
	v_exp_f32_e32 v75, v75
	s_nop 0
	v_add_f32_e32 v75, 1.0, v75
	v_rcp_f32_e32 v75, v75
	s_nop 0
	v_mul_f32_e32 v74, v75, v74
	v_and_b32_e32 v75, 0xffff0000, v109
	v_mul_f32_e32 v74, v76, v74
	v_mul_f32_e32 v76, 0xbfb8aa3b, v75
	v_exp_f32_e32 v76, v76
	s_nop 0
	v_add_f32_e32 v76, 1.0, v76
	v_rcp_f32_e32 v76, v76
	s_nop 0
	v_mul_f32_e32 v75, v76, v75
	v_mul_f32_e32 v75, v77, v75
	v_cvt_pk_bf16_f32 v81, v74, v75
	v_add_co_u32_e32 v74, vcc, s70, v166
	v_lshl_add_u64 v[76:77], s[46:47], 0, v[204:205]
	s_nop 0
	v_addc_co_u32_e32 v75, vcc, 0, v167, vcc
	global_store_dwordx4 v[74:75], v[78:81], off
	v_or_b32_e32 v74, 0x80, v200
	v_ashrrev_i32_e32 v75, 31, v74
	v_lshlrev_b64 v[74:75], 1, v[74:75]
	v_lshl_add_u64 v[76:77], v[76:77], 0, v[74:75]
	global_load_dwordx4 v[102:105], v[76:77], off
	v_lshl_add_u64 v[76:77], s[46:47], 0, v[198:199]
	v_lshl_add_u64 v[76:77], v[76:77], 0, v[74:75]
	global_load_dwordx4 v[98:101], v[76:77], off
	v_lshl_add_u64 v[76:77], s[46:47], 0, v[202:203]
	v_lshl_add_u64 v[76:77], v[76:77], 0, v[74:75]
	global_load_dwordx4 v[94:97], v[76:77], off
	v_lshl_add_u64 v[76:77], s[46:47], 0, v[206:207]
	v_lshl_add_u64 v[76:77], v[76:77], 0, v[74:75]
	global_load_dwordx4 v[90:93], v[76:77], off
	v_lshl_add_u64 v[76:77], s[46:47], 0, v[208:209]
	v_lshl_add_u64 v[76:77], v[76:77], 0, v[74:75]
	global_load_dwordx4 v[86:89], v[76:77], off
	v_lshl_add_u64 v[76:77], s[46:47], 0, v[210:211]
	v_lshl_add_u64 v[76:77], v[76:77], 0, v[74:75]
	global_load_dwordx4 v[82:85], v[76:77], off
	v_lshl_add_u64 v[76:77], s[46:47], 0, v[212:213]
	v_lshl_add_u64 v[76:77], v[76:77], 0, v[74:75]
	global_load_dwordx4 v[78:81], v[76:77], off
	v_lshl_add_u64 v[76:77], s[46:47], 0, v[214:215]
	v_lshl_add_u64 v[74:75], v[76:77], 0, v[74:75]
	global_load_dwordx4 v[74:77], v[74:75], off
	s_and_b64 vcc, exec, s[42:43]
	s_waitcnt vmcnt(0)
; __device__ __forceinline__ unsigned cvt_pk_bf16(float lo, float hi) { unsigned r; asm volatile("v_cvt_pk_bf16_f32 %0, %1, %2" : "=v"(r) : "v"(lo), "v"(hi)); return r; }
; __device__ __forceinline__ float bf_lo(unsigned w) { return __uint_as_float(w << 16); }
; __device__ __forceinline__ float bf_hi(unsigned w) { return __uint_as_float(w & 0xffff0000u); }
; __device__ __forceinline__ float silu_f(float z) { return z * fast_rcp(1.0f + __builtin_amdgcn_exp2f(z * -1.44269504f)); }
;     __device__ __forceinline__ void operator()(const f32x4 (&acc)[2][2][4][2], const Unit& u, int wr, int wc, int fr, int fq, const Pre&) const {
;     ...
;             for (int ai = 0; ai < 2; ++ai)
; #pragma unroll
;                 for (int m = 0; m < 4; ++m) { const int r = row0 + ai * HALF + m * 16;
;                     const u32x4 zw = zv[ai * 4 + m];
;                     const f32x4 a0 = acc[ai][bj][m][0] * sc[bj][0], a1 = acc[ai][bj][m][1] * sc[bj][1];
;                     u32x4 w;
;                     w.x = cvt_pk_bf16(a0[0] * silu_f(bf_lo(zw.x)), a0[1] * silu_f(bf_hi(zw.x)));
;                     w.y = cvt_pk_bf16(a0[2] * silu_f(bf_lo(zw.y)), a0[3] * silu_f(bf_hi(zw.y)));
;                     w.z = cvt_pk_bf16(a1[0] * silu_f(bf_lo(zw.z)), a1[1] * silu_f(bf_hi(zw.z)));
;                     w.w = cvt_pk_bf16(a1[2] * silu_f(bf_lo(zw.w)), a1[3] * silu_f(bf_hi(zw.w)));
;                     *(u32x4*)(O + (size_t)r * DE + c) = w; } }
	v_lshlrev_b32_e32 v108, 16, v102
	v_mul_f32_e32 v109, 0xbfb8aa3b, v108
	v_exp_f32_e32 v109, v109
	v_and_b32_e32 v102, 0xffff0000, v102
	v_add_f32_e32 v109, 1.0, v109
	v_rcp_f32_e32 v109, v109
	s_nop 0
	v_mul_f32_e32 v108, v109, v108
	v_mul_f32_e32 v70, v70, v108
	v_mul_f32_e32 v108, 0xbfb8aa3b, v102
	v_exp_f32_e32 v108, v108
	s_nop 0
	v_add_f32_e32 v108, 1.0, v108
	v_rcp_f32_e32 v108, v108
	s_nop 0
	v_mul_f32_e32 v102, v108, v102
	v_mul_f32_e32 v71, v71, v102
	v_cvt_pk_bf16_f32 v70, v70, v71
	v_lshlrev_b32_e32 v71, 16, v103
	v_mul_f32_e32 v102, 0xbfb8aa3b, v71
	v_exp_f32_e32 v102, v102
	s_nop 0
	v_add_f32_e32 v102, 1.0, v102
	v_rcp_f32_e32 v102, v102
	s_nop 0
	v_mul_f32_e32 v71, v102, v71
	v_mul_f32_e32 v71, v72, v71
	v_and_b32_e32 v72, 0xffff0000, v103
	v_mul_f32_e32 v102, 0xbfb8aa3b, v72
	v_exp_f32_e32 v102, v102
	s_nop 0
	v_add_f32_e32 v102, 1.0, v102
	v_rcp_f32_e32 v102, v102
	s_nop 0
	v_mul_f32_e32 v72, v102, v72
	v_mul_f32_e32 v72, v73, v72
	v_cvt_pk_bf16_f32 v71, v71, v72
	v_lshlrev_b32_e32 v72, 16, v104
	v_mul_f32_e32 v73, 0xbfb8aa3b, v72
	v_exp_f32_e32 v73, v73
	s_nop 0
	v_add_f32_e32 v73, 1.0, v73
	v_rcp_f32_e32 v73, v73
	s_nop 0
	v_mul_f32_e32 v72, v73, v72
	v_mul_f32_e32 v66, v66, v72
	v_and_b32_e32 v72, 0xffff0000, v104
	v_mul_f32_e32 v73, 0xbfb8aa3b, v72
	v_exp_f32_e32 v73, v73
	s_nop 0
	v_add_f32_e32 v73, 1.0, v73
	v_rcp_f32_e32 v73, v73
	s_nop 0
	v_mul_f32_e32 v72, v73, v72
	v_mul_f32_e32 v67, v67, v72
	v_cvt_pk_bf16_f32 v72, v66, v67
	v_lshlrev_b32_e32 v66, 16, v105
	v_mul_f32_e32 v67, 0xbfb8aa3b, v66
	v_exp_f32_e32 v67, v67
	s_nop 0
	v_add_f32_e32 v67, 1.0, v67
	v_rcp_f32_e32 v67, v67
	s_nop 0
	v_mul_f32_e32 v66, v67, v66
	v_and_b32_e32 v67, 0xffff0000, v105
	v_mul_f32_e32 v66, v68, v66
	v_mul_f32_e32 v68, 0xbfb8aa3b, v67
	v_exp_f32_e32 v68, v68
	s_nop 0
	v_add_f32_e32 v68, 1.0, v68
	v_rcp_f32_e32 v68, v68
	s_nop 0
	v_mul_f32_e32 v67, v68, v67
	v_mul_f32_e32 v67, v69, v67
	v_cvt_pk_bf16_f32 v73, v66, v67
	v_lshlrev_b32_e32 v66, 16, v98
	v_mul_f32_e32 v67, 0xbfb8aa3b, v66
	v_exp_f32_e32 v67, v67
	global_store_dwordx4 v[166:167], v[70:73], off offset:256
	v_add_f32_e32 v67, 1.0, v67
	v_rcp_f32_e32 v67, v67
	s_nop 0
	v_mul_f32_e32 v66, v67, v66
	v_mul_f32_e32 v62, v62, v66
	v_and_b32_e32 v66, 0xffff0000, v98
	v_mul_f32_e32 v67, 0xbfb8aa3b, v66
	v_exp_f32_e32 v67, v67
	s_nop 0
	v_add_f32_e32 v67, 1.0, v67
	v_rcp_f32_e32 v67, v67
	s_nop 0
	v_mul_f32_e32 v66, v67, v66
	v_mul_f32_e32 v63, v63, v66
	v_cvt_pk_bf16_f32 v62, v62, v63
	v_lshlrev_b32_e32 v63, 16, v99
	v_mul_f32_e32 v66, 0xbfb8aa3b, v63
	v_exp_f32_e32 v66, v66
	s_nop 0
	v_add_f32_e32 v66, 1.0, v66
	v_rcp_f32_e32 v66, v66
	s_nop 0
	v_mul_f32_e32 v63, v66, v63
	v_mul_f32_e32 v63, v64, v63
	v_and_b32_e32 v64, 0xffff0000, v99
	v_mul_f32_e32 v66, 0xbfb8aa3b, v64
	v_exp_f32_e32 v66, v66
	s_nop 0
	v_add_f32_e32 v66, 1.0, v66
	v_rcp_f32_e32 v66, v66
	s_nop 0
	v_mul_f32_e32 v64, v66, v64
	v_mul_f32_e32 v64, v65, v64
	v_cvt_pk_bf16_f32 v63, v63, v64
	v_lshlrev_b32_e32 v64, 16, v100
	v_mul_f32_e32 v65, 0xbfb8aa3b, v64
	v_exp_f32_e32 v65, v65
	s_nop 0
	v_add_f32_e32 v65, 1.0, v65
	v_rcp_f32_e32 v65, v65
	s_nop 0
	v_mul_f32_e32 v64, v65, v64
	v_mul_f32_e32 v58, v58, v64
	v_and_b32_e32 v64, 0xffff0000, v100
	v_mul_f32_e32 v65, 0xbfb8aa3b, v64
	v_exp_f32_e32 v65, v65
	s_nop 0
	v_add_f32_e32 v65, 1.0, v65
	v_rcp_f32_e32 v65, v65
	s_nop 0
	v_mul_f32_e32 v64, v65, v64
	v_mul_f32_e32 v59, v59, v64
	v_cvt_pk_bf16_f32 v64, v58, v59
	v_lshlrev_b32_e32 v58, 16, v101
	v_mul_f32_e32 v59, 0xbfb8aa3b, v58
	v_exp_f32_e32 v59, v59
	s_nop 0
	v_add_f32_e32 v59, 1.0, v59
	v_rcp_f32_e32 v59, v59
	s_nop 0
	v_mul_f32_e32 v58, v59, v58
	v_and_b32_e32 v59, 0xffff0000, v101
	v_mul_f32_e32 v58, v60, v58
	v_mul_f32_e32 v60, 0xbfb8aa3b, v59
	v_exp_f32_e32 v60, v60
	s_nop 0
	v_add_f32_e32 v60, 1.0, v60
	v_rcp_f32_e32 v60, v60
	s_nop 0
	v_mul_f32_e32 v59, v60, v59
	v_mul_f32_e32 v59, v61, v59
	v_cvt_pk_bf16_f32 v65, v58, v59
	v_lshlrev_b32_e32 v58, 16, v94
	v_mul_f32_e32 v59, 0xbfb8aa3b, v58
	v_exp_f32_e32 v59, v59
	global_store_dwordx4 v[146:147], v[62:65], off offset:256
	v_add_f32_e32 v59, 1.0, v59
	v_rcp_f32_e32 v59, v59
	s_nop 0
	v_mul_f32_e32 v58, v59, v58
	v_mul_f32_e32 v54, v54, v58
	v_and_b32_e32 v58, 0xffff0000, v94
	v_mul_f32_e32 v59, 0xbfb8aa3b, v58
	v_exp_f32_e32 v59, v59
	s_nop 0
	v_add_f32_e32 v59, 1.0, v59
	v_rcp_f32_e32 v59, v59
	s_nop 0
	v_mul_f32_e32 v58, v59, v58
	v_mul_f32_e32 v55, v55, v58
	v_cvt_pk_bf16_f32 v54, v54, v55
	v_lshlrev_b32_e32 v55, 16, v95
	v_mul_f32_e32 v58, 0xbfb8aa3b, v55
	v_exp_f32_e32 v58, v58
	s_nop 0
	v_add_f32_e32 v58, 1.0, v58
	v_rcp_f32_e32 v58, v58
	s_nop 0
	v_mul_f32_e32 v55, v58, v55
	v_mul_f32_e32 v55, v56, v55
	v_and_b32_e32 v56, 0xffff0000, v95
	v_mul_f32_e32 v58, 0xbfb8aa3b, v56
	v_exp_f32_e32 v58, v58
	s_nop 0
	v_add_f32_e32 v58, 1.0, v58
	v_rcp_f32_e32 v58, v58
	s_nop 0
	v_mul_f32_e32 v56, v58, v56
	v_mul_f32_e32 v56, v57, v56
	v_cvt_pk_bf16_f32 v55, v55, v56
	v_lshlrev_b32_e32 v56, 16, v96
	v_mul_f32_e32 v57, 0xbfb8aa3b, v56
	v_exp_f32_e32 v57, v57
	s_nop 0
	v_add_f32_e32 v57, 1.0, v57
	v_rcp_f32_e32 v57, v57
	s_nop 0
	v_mul_f32_e32 v56, v57, v56
	v_mul_f32_e32 v50, v50, v56
	v_and_b32_e32 v56, 0xffff0000, v96
	v_mul_f32_e32 v57, 0xbfb8aa3b, v56
	v_exp_f32_e32 v57, v57
	s_nop 0
	v_add_f32_e32 v57, 1.0, v57
	v_rcp_f32_e32 v57, v57
	s_nop 0
	v_mul_f32_e32 v56, v57, v56
	v_mul_f32_e32 v51, v51, v56
	v_cvt_pk_bf16_f32 v56, v50, v51
	v_lshlrev_b32_e32 v50, 16, v97
	v_mul_f32_e32 v51, 0xbfb8aa3b, v50
	v_exp_f32_e32 v51, v51
	s_nop 0
	v_add_f32_e32 v51, 1.0, v51
	v_rcp_f32_e32 v51, v51
	s_nop 0
	v_mul_f32_e32 v50, v51, v50
	v_and_b32_e32 v51, 0xffff0000, v97
; __device__ __forceinline__ unsigned cvt_pk_bf16(float lo, float hi) { unsigned r; asm volatile("v_cvt_pk_bf16_f32 %0, %1, %2" : "=v"(r) : "v"(lo), "v"(hi)); return r; }
; __device__ __forceinline__ float bf_lo(unsigned w) { return __uint_as_float(w << 16); }
; __device__ __forceinline__ float bf_hi(unsigned w) { return __uint_as_float(w & 0xffff0000u); }
; __device__ __forceinline__ float silu_f(float z) { return z * fast_rcp(1.0f + __builtin_amdgcn_exp2f(z * -1.44269504f)); }
;     __device__ __forceinline__ void operator()(const f32x4 (&acc)[2][2][4][2], const Unit& u, int wr, int wc, int fr, int fq, const Pre&) const {
;     ...
;             for (int ai = 0; ai < 2; ++ai)
; #pragma unroll
;                 for (int m = 0; m < 4; ++m) { const int r = row0 + ai * HALF + m * 16;
;                     const u32x4 zw = zv[ai * 4 + m];
;                     const f32x4 a0 = acc[ai][bj][m][0] * sc[bj][0], a1 = acc[ai][bj][m][1] * sc[bj][1];
;                     u32x4 w;
;                     w.x = cvt_pk_bf16(a0[0] * silu_f(bf_lo(zw.x)), a0[1] * silu_f(bf_hi(zw.x)));
;                     w.y = cvt_pk_bf16(a0[2] * silu_f(bf_lo(zw.y)), a0[3] * silu_f(bf_hi(zw.y)));
;                     w.z = cvt_pk_bf16(a1[0] * silu_f(bf_lo(zw.z)), a1[1] * silu_f(bf_hi(zw.z)));
;                     w.w = cvt_pk_bf16(a1[2] * silu_f(bf_lo(zw.w)), a1[3] * silu_f(bf_hi(zw.w)));
;                     *(u32x4*)(O + (size_t)r * DE + c) = w; } }
	v_mul_f32_e32 v50, v52, v50
	v_mul_f32_e32 v52, 0xbfb8aa3b, v51
	v_exp_f32_e32 v52, v52
	s_nop 0
	v_add_f32_e32 v52, 1.0, v52
	v_rcp_f32_e32 v52, v52
	s_nop 0
	v_mul_f32_e32 v51, v52, v51
	v_mul_f32_e32 v51, v53, v51
	v_cvt_pk_bf16_f32 v57, v50, v51
	v_lshlrev_b32_e32 v50, 16, v90
	v_mul_f32_e32 v51, 0xbfb8aa3b, v50
	v_exp_f32_e32 v51, v51
	global_store_dwordx4 v[134:135], v[54:57], off offset:256
	v_add_f32_e32 v51, 1.0, v51
	v_rcp_f32_e32 v51, v51
	s_nop 0
	v_mul_f32_e32 v50, v51, v50
	v_mul_f32_e32 v46, v46, v50
	v_and_b32_e32 v50, 0xffff0000, v90
	v_mul_f32_e32 v51, 0xbfb8aa3b, v50
	v_exp_f32_e32 v51, v51
	s_nop 0
	v_add_f32_e32 v51, 1.0, v51
	v_rcp_f32_e32 v51, v51
	s_nop 0
	v_mul_f32_e32 v50, v51, v50
	v_mul_f32_e32 v47, v47, v50
	v_cvt_pk_bf16_f32 v46, v46, v47
	v_lshlrev_b32_e32 v47, 16, v91
	v_mul_f32_e32 v50, 0xbfb8aa3b, v47
	v_exp_f32_e32 v50, v50
	s_nop 0
	v_add_f32_e32 v50, 1.0, v50
	v_rcp_f32_e32 v50, v50
	s_nop 0
	v_mul_f32_e32 v47, v50, v47
	v_mul_f32_e32 v47, v48, v47
	v_and_b32_e32 v48, 0xffff0000, v91
	v_mul_f32_e32 v50, 0xbfb8aa3b, v48
	v_exp_f32_e32 v50, v50
	s_nop 0
	v_add_f32_e32 v50, 1.0, v50
	v_rcp_f32_e32 v50, v50
	s_nop 0
	v_mul_f32_e32 v48, v50, v48
	v_mul_f32_e32 v48, v49, v48
	v_cvt_pk_bf16_f32 v47, v47, v48
	v_lshlrev_b32_e32 v48, 16, v92
	v_mul_f32_e32 v49, 0xbfb8aa3b, v48
	v_exp_f32_e32 v49, v49
	s_nop 0
	v_add_f32_e32 v49, 1.0, v49
	v_rcp_f32_e32 v49, v49
	s_nop 0
	v_mul_f32_e32 v48, v49, v48
	v_mul_f32_e32 v42, v42, v48
	v_and_b32_e32 v48, 0xffff0000, v92
	v_mul_f32_e32 v49, 0xbfb8aa3b, v48
	v_exp_f32_e32 v49, v49
	s_nop 0
	v_add_f32_e32 v49, 1.0, v49
	v_rcp_f32_e32 v49, v49
	s_nop 0
	v_mul_f32_e32 v48, v49, v48
	v_mul_f32_e32 v43, v43, v48
	v_cvt_pk_bf16_f32 v48, v42, v43
	v_lshlrev_b32_e32 v42, 16, v93
	v_mul_f32_e32 v43, 0xbfb8aa3b, v42
	v_exp_f32_e32 v43, v43
	s_nop 0
	v_add_f32_e32 v43, 1.0, v43
	v_rcp_f32_e32 v43, v43
	s_nop 0
	v_mul_f32_e32 v42, v43, v42
	v_and_b32_e32 v43, 0xffff0000, v93
	v_mul_f32_e32 v42, v44, v42
	v_mul_f32_e32 v44, 0xbfb8aa3b, v43
	v_exp_f32_e32 v44, v44
	s_nop 0
	v_add_f32_e32 v44, 1.0, v44
	v_rcp_f32_e32 v44, v44
	s_nop 0
	v_mul_f32_e32 v43, v44, v43
	v_mul_f32_e32 v43, v45, v43
	v_cvt_pk_bf16_f32 v49, v42, v43
	v_lshlrev_b32_e32 v42, 16, v86
	v_mul_f32_e32 v43, 0xbfb8aa3b, v42
	v_exp_f32_e32 v43, v43
	global_store_dwordx4 v[122:123], v[46:49], off offset:256
	v_add_f32_e32 v43, 1.0, v43
	v_rcp_f32_e32 v43, v43
	s_nop 0
	v_mul_f32_e32 v42, v43, v42
	v_mul_f32_e32 v30, v30, v42
	v_and_b32_e32 v42, 0xffff0000, v86
	v_mul_f32_e32 v43, 0xbfb8aa3b, v42
	v_exp_f32_e32 v43, v43
	s_nop 0
	v_add_f32_e32 v43, 1.0, v43
	v_rcp_f32_e32 v43, v43
	s_nop 0
	v_mul_f32_e32 v42, v43, v42
	v_mul_f32_e32 v31, v31, v42
	v_cvt_pk_bf16_f32 v30, v30, v31
	v_lshlrev_b32_e32 v31, 16, v87
	v_mul_f32_e32 v42, 0xbfb8aa3b, v31
	v_exp_f32_e32 v42, v42
	s_nop 0
	v_add_f32_e32 v42, 1.0, v42
	v_rcp_f32_e32 v42, v42
	s_nop 0
	v_mul_f32_e32 v31, v42, v31
	v_mul_f32_e32 v31, v32, v31
	v_and_b32_e32 v32, 0xffff0000, v87
	v_mul_f32_e32 v42, 0xbfb8aa3b, v32
	v_exp_f32_e32 v42, v42
	s_nop 0
	v_add_f32_e32 v42, 1.0, v42
	v_rcp_f32_e32 v42, v42
	s_nop 0
	v_mul_f32_e32 v32, v42, v32
	v_mul_f32_e32 v32, v33, v32
	v_cvt_pk_bf16_f32 v31, v31, v32
	v_lshlrev_b32_e32 v32, 16, v88
	v_mul_f32_e32 v33, 0xbfb8aa3b, v32
	v_exp_f32_e32 v33, v33
	s_nop 0
	v_add_f32_e32 v33, 1.0, v33
	v_rcp_f32_e32 v33, v33
	s_nop 0
	v_mul_f32_e32 v32, v33, v32
	v_mul_f32_e32 v26, v26, v32
	v_and_b32_e32 v32, 0xffff0000, v88
	v_mul_f32_e32 v33, 0xbfb8aa3b, v32
	v_exp_f32_e32 v33, v33
	s_nop 0
	v_add_f32_e32 v33, 1.0, v33
	v_rcp_f32_e32 v33, v33
	s_nop 0
	v_mul_f32_e32 v32, v33, v32
	v_mul_f32_e32 v27, v27, v32
	v_cvt_pk_bf16_f32 v32, v26, v27
	v_lshlrev_b32_e32 v26, 16, v89
	v_mul_f32_e32 v27, 0xbfb8aa3b, v26
	v_exp_f32_e32 v27, v27
	s_nop 0
	v_add_f32_e32 v27, 1.0, v27
	v_rcp_f32_e32 v27, v27
	s_nop 0
	v_mul_f32_e32 v26, v27, v26
	v_and_b32_e32 v27, 0xffff0000, v89
	v_mul_f32_e32 v26, v28, v26
	v_mul_f32_e32 v28, 0xbfb8aa3b, v27
	v_exp_f32_e32 v28, v28
	s_nop 0
	v_add_f32_e32 v28, 1.0, v28
	v_rcp_f32_e32 v28, v28
	s_nop 0
	v_mul_f32_e32 v27, v28, v27
	v_mul_f32_e32 v27, v29, v27
	v_cvt_pk_bf16_f32 v33, v26, v27
	v_lshlrev_b32_e32 v26, 16, v82
	v_mul_f32_e32 v27, 0xbfb8aa3b, v26
	v_exp_f32_e32 v27, v27
	global_store_dwordx4 v[112:113], v[30:33], off offset:256
	v_add_f32_e32 v27, 1.0, v27
	v_rcp_f32_e32 v27, v27
	s_nop 0
	v_mul_f32_e32 v26, v27, v26
	v_mul_f32_e32 v22, v22, v26
	v_and_b32_e32 v26, 0xffff0000, v82
	v_mul_f32_e32 v27, 0xbfb8aa3b, v26
	v_exp_f32_e32 v27, v27
	s_nop 0
	v_add_f32_e32 v27, 1.0, v27
	v_rcp_f32_e32 v27, v27
	s_nop 0
	v_mul_f32_e32 v26, v27, v26
	v_mul_f32_e32 v23, v23, v26
	v_cvt_pk_bf16_f32 v22, v22, v23
	v_lshlrev_b32_e32 v23, 16, v83
	v_mul_f32_e32 v26, 0xbfb8aa3b, v23
	v_exp_f32_e32 v26, v26
	s_nop 0
	v_add_f32_e32 v26, 1.0, v26
	v_rcp_f32_e32 v26, v26
	s_nop 0
	v_mul_f32_e32 v23, v26, v23
	v_mul_f32_e32 v23, v24, v23
	v_and_b32_e32 v24, 0xffff0000, v83
	v_mul_f32_e32 v26, 0xbfb8aa3b, v24
	v_exp_f32_e32 v26, v26
	s_nop 0
	v_add_f32_e32 v26, 1.0, v26
	v_rcp_f32_e32 v26, v26
; __device__ __forceinline__ unsigned cvt_pk_bf16(float lo, float hi) { unsigned r; asm volatile("v_cvt_pk_bf16_f32 %0, %1, %2" : "=v"(r) : "v"(lo), "v"(hi)); return r; }
; __device__ __forceinline__ float bf_lo(unsigned w) { return __uint_as_float(w << 16); }
; __device__ __forceinline__ float bf_hi(unsigned w) { return __uint_as_float(w & 0xffff0000u); }
; __device__ __forceinline__ float silu_f(float z) { return z * fast_rcp(1.0f + __builtin_amdgcn_exp2f(z * -1.44269504f)); }
; #define PG8_WAIT_V(n) asm volatile("s_waitcnt vmcnt(" #n ")" ::: "memory")
; #define PG8_BAR __builtin_amdgcn_s_barrier()
; template <class Epi>
; __device__ __forceinline__ void gemm_phase(LAS unsigned char* lds, const Gemm g, const StaticOrder& S, const Epi& E) {
;     ...
;         if (!has_next) break;
; #pragma unroll
;         for (int a = 0; a < 2; ++a)
; #pragma unroll
;             for (int b = 0; b < 2; ++b)
; #pragma unroll
;                 for (int m = 0; m < 4; ++m)
; #pragma unroll
;                     for (int n = 0; n < 2; ++n) acc[a][b][m][n] = (f32x4){0.f, 0.f, 0.f, 0.f};
;         cur = nxt; cA = nA; cB = nB; ++ui;
;         pre = E.pre(cur, wr, fr);
;     }
;     PG8_WAIT_V(0);
;     if (wr == 0) PG8_BAR;
;     PG8_BAR;
;     __device__ __forceinline__ void operator()(const f32x4 (&acc)[2][2][4][2], const Unit& u, int wr, int wc, int fr, int fq, const Pre&) const {
;     ...
;             for (int ai = 0; ai < 2; ++ai)
; #pragma unroll
;                 for (int m = 0; m < 4; ++m) { const int r = row0 + ai * HALF + m * 16;
;                     const u32x4 zw = zv[ai * 4 + m];
;                     const f32x4 a0 = acc[ai][bj][m][0] * sc[bj][0], a1 = acc[ai][bj][m][1] * sc[bj][1];
;                     u32x4 w;
;                     w.x = cvt_pk_bf16(a0[0] * silu_f(bf_lo(zw.x)), a0[1] * silu_f(bf_hi(zw.x)));
;                     w.y = cvt_pk_bf16(a0[2] * silu_f(bf_lo(zw.y)), a0[3] * silu_f(bf_hi(zw.y)));
;                     w.z = cvt_pk_bf16(a1[0] * silu_f(bf_lo(zw.z)), a1[1] * silu_f(bf_hi(zw.z)));
;                     w.w = cvt_pk_bf16(a1[2] * silu_f(bf_lo(zw.w)), a1[3] * silu_f(bf_hi(zw.w)));
;                     *(u32x4*)(O + (size_t)r * DE + c) = w; } }
	s_nop 0
	v_mul_f32_e32 v24, v26, v24
	v_mul_f32_e32 v24, v25, v24
	v_cvt_pk_bf16_f32 v23, v23, v24
	v_lshlrev_b32_e32 v24, 16, v84
	v_mul_f32_e32 v25, 0xbfb8aa3b, v24
	v_exp_f32_e32 v25, v25
	s_nop 0
	v_add_f32_e32 v25, 1.0, v25
	v_rcp_f32_e32 v25, v25
	s_nop 0
	v_mul_f32_e32 v24, v25, v24
	v_mul_f32_e32 v18, v18, v24
	v_and_b32_e32 v24, 0xffff0000, v84
	v_mul_f32_e32 v25, 0xbfb8aa3b, v24
	v_exp_f32_e32 v25, v25
	s_nop 0
	v_add_f32_e32 v25, 1.0, v25
	v_rcp_f32_e32 v25, v25
	s_nop 0
	v_mul_f32_e32 v24, v25, v24
	v_mul_f32_e32 v19, v19, v24
	v_cvt_pk_bf16_f32 v24, v18, v19
	v_lshlrev_b32_e32 v18, 16, v85
	v_mul_f32_e32 v19, 0xbfb8aa3b, v18
	v_exp_f32_e32 v19, v19
	s_nop 0
	v_add_f32_e32 v19, 1.0, v19
	v_rcp_f32_e32 v19, v19
	s_nop 0
	v_mul_f32_e32 v18, v19, v18
	v_and_b32_e32 v19, 0xffff0000, v85
	v_mul_f32_e32 v18, v20, v18
	v_mul_f32_e32 v20, 0xbfb8aa3b, v19
	v_exp_f32_e32 v20, v20
	s_nop 0
	v_add_f32_e32 v20, 1.0, v20
	v_rcp_f32_e32 v20, v20
	s_nop 0
	v_mul_f32_e32 v19, v20, v19
	v_mul_f32_e32 v19, v21, v19
	v_cvt_pk_bf16_f32 v25, v18, v19
	v_lshlrev_b32_e32 v18, 16, v78
	v_mul_f32_e32 v19, 0xbfb8aa3b, v18
	v_exp_f32_e32 v19, v19
	global_store_dwordx4 v[110:111], v[22:25], off offset:256
	v_add_f32_e32 v19, 1.0, v19
	v_rcp_f32_e32 v19, v19
	s_nop 0
	v_mul_f32_e32 v18, v19, v18
	v_mul_f32_e32 v14, v14, v18
	v_and_b32_e32 v18, 0xffff0000, v78
	v_mul_f32_e32 v19, 0xbfb8aa3b, v18
	v_exp_f32_e32 v19, v19
	s_nop 0
	v_add_f32_e32 v19, 1.0, v19
	v_rcp_f32_e32 v19, v19
	s_nop 0
	v_mul_f32_e32 v18, v19, v18
	v_mul_f32_e32 v15, v15, v18
	v_cvt_pk_bf16_f32 v14, v14, v15
	v_lshlrev_b32_e32 v15, 16, v79
	v_mul_f32_e32 v18, 0xbfb8aa3b, v15
	v_exp_f32_e32 v18, v18
	s_nop 0
	v_add_f32_e32 v18, 1.0, v18
	v_rcp_f32_e32 v18, v18
	s_nop 0
	v_mul_f32_e32 v15, v18, v15
	v_mul_f32_e32 v15, v16, v15
	v_and_b32_e32 v16, 0xffff0000, v79
	v_mul_f32_e32 v18, 0xbfb8aa3b, v16
	v_exp_f32_e32 v18, v18
	s_nop 0
	v_add_f32_e32 v18, 1.0, v18
	v_rcp_f32_e32 v18, v18
	s_nop 0
	v_mul_f32_e32 v16, v18, v16
	v_mul_f32_e32 v16, v17, v16
	v_cvt_pk_bf16_f32 v15, v15, v16
	v_lshlrev_b32_e32 v16, 16, v80
	v_mul_f32_e32 v17, 0xbfb8aa3b, v16
	v_exp_f32_e32 v17, v17
	s_nop 0
	v_add_f32_e32 v17, 1.0, v17
	v_rcp_f32_e32 v17, v17
	s_nop 0
	v_mul_f32_e32 v16, v17, v16
	v_mul_f32_e32 v10, v10, v16
	v_and_b32_e32 v16, 0xffff0000, v80
	v_mul_f32_e32 v17, 0xbfb8aa3b, v16
	v_exp_f32_e32 v17, v17
	s_nop 0
	v_add_f32_e32 v17, 1.0, v17
	v_rcp_f32_e32 v17, v17
	s_nop 0
	v_mul_f32_e32 v16, v17, v16
	v_mul_f32_e32 v11, v11, v16
	v_cvt_pk_bf16_f32 v16, v10, v11
	v_lshlrev_b32_e32 v10, 16, v81
	v_mul_f32_e32 v11, 0xbfb8aa3b, v10
	v_exp_f32_e32 v11, v11
	s_nop 0
	v_add_f32_e32 v11, 1.0, v11
	v_rcp_f32_e32 v11, v11
	s_nop 0
	v_mul_f32_e32 v10, v11, v10
	v_and_b32_e32 v11, 0xffff0000, v81
	v_mul_f32_e32 v10, v12, v10
	v_mul_f32_e32 v12, 0xbfb8aa3b, v11
	v_exp_f32_e32 v12, v12
	s_nop 0
	v_add_f32_e32 v12, 1.0, v12
	v_rcp_f32_e32 v12, v12
	s_nop 0
	v_mul_f32_e32 v11, v12, v11
	v_mul_f32_e32 v11, v13, v11
	v_cvt_pk_bf16_f32 v17, v10, v11
	v_lshlrev_b32_e32 v10, 16, v74
	v_mul_f32_e32 v11, 0xbfb8aa3b, v10
	v_exp_f32_e32 v11, v11
	global_store_dwordx4 v[114:115], v[14:17], off offset:256
	v_add_f32_e32 v11, 1.0, v11
	v_rcp_f32_e32 v11, v11
	s_nop 0
	v_mul_f32_e32 v10, v11, v10
	v_mul_f32_e32 v6, v6, v10
	v_and_b32_e32 v10, 0xffff0000, v74
	v_mul_f32_e32 v11, 0xbfb8aa3b, v10
	v_exp_f32_e32 v11, v11
	s_nop 0
	v_add_f32_e32 v11, 1.0, v11
	v_rcp_f32_e32 v11, v11
	s_nop 0
	v_mul_f32_e32 v10, v11, v10
	v_mul_f32_e32 v7, v7, v10
	v_cvt_pk_bf16_f32 v6, v6, v7
	v_lshlrev_b32_e32 v7, 16, v75
	v_mul_f32_e32 v10, 0xbfb8aa3b, v7
	v_exp_f32_e32 v10, v10
	s_nop 0
	v_add_f32_e32 v10, 1.0, v10
	v_rcp_f32_e32 v10, v10
	s_nop 0
	v_mul_f32_e32 v7, v10, v7
	v_mul_f32_e32 v7, v8, v7
	v_and_b32_e32 v8, 0xffff0000, v75
	v_mul_f32_e32 v10, 0xbfb8aa3b, v8
	v_exp_f32_e32 v10, v10
	s_nop 0
	v_add_f32_e32 v10, 1.0, v10
	v_rcp_f32_e32 v10, v10
	s_nop 0
	v_mul_f32_e32 v8, v10, v8
	v_mul_f32_e32 v8, v9, v8
	v_cvt_pk_bf16_f32 v7, v7, v8
	v_lshlrev_b32_e32 v8, 16, v76
	v_mul_f32_e32 v9, 0xbfb8aa3b, v8
	v_exp_f32_e32 v9, v9
	s_nop 0
	v_add_f32_e32 v9, 1.0, v9
	v_rcp_f32_e32 v9, v9
	s_nop 0
	v_mul_f32_e32 v8, v9, v8
	v_mul_f32_e32 v2, v2, v8
	v_and_b32_e32 v8, 0xffff0000, v76
	v_mul_f32_e32 v9, 0xbfb8aa3b, v8
	v_exp_f32_e32 v9, v9
	s_nop 0
	v_add_f32_e32 v9, 1.0, v9
	v_rcp_f32_e32 v9, v9
	s_nop 0
	v_mul_f32_e32 v8, v9, v8
	v_mul_f32_e32 v3, v3, v8
	v_cvt_pk_bf16_f32 v8, v2, v3
	v_lshlrev_b32_e32 v2, 16, v77
	v_mul_f32_e32 v3, 0xbfb8aa3b, v2
	v_exp_f32_e32 v3, v3
	s_nop 0
	v_add_f32_e32 v3, 1.0, v3
	v_rcp_f32_e32 v3, v3
	s_nop 0
	v_mul_f32_e32 v2, v3, v2
	v_and_b32_e32 v3, 0xffff0000, v77
	v_mul_f32_e32 v2, v4, v2
	v_mul_f32_e32 v4, 0xbfb8aa3b, v3
	v_exp_f32_e32 v4, v4
	s_nop 0
	v_add_f32_e32 v4, 1.0, v4
	v_rcp_f32_e32 v4, v4
	s_nop 0
	v_mul_f32_e32 v3, v4, v3
	v_mul_f32_e32 v3, v5, v3
	v_cvt_pk_bf16_f32 v9, v2, v3
	global_store_dwordx4 v[106:107], v[6:9], off offset:256
	s_cbranch_vccz .LBB0_596
	s_waitcnt vmcnt(0)
	s_cmpk_gt_u32 s14, 0xff
	s_mov_b64 s[36:37], s[96:97]
	s_cbranch_scc1 .LBB0_607
	s_barrier

; #define PG8_STAGE(bufoff, gbase, voff) do { _Pragma("unroll") for (int _i = 0; _i < 2; ++_i) \
;         __builtin_amdgcn_global_load_lds((const unsigned*)((const char*)(gbase) + (voff)[_i]), (LAS unsigned*)(lds + (bufoff) + ldsw + _i * 8192), 16, 0, 0); } while (0)
; #define PG8_LDA(dst, b, h) do { _Pragma("unroll") for (int m = 0; m < 4; ++m) _Pragma("unroll") for (int k = 0; k < 2; ++k) dst[m][k] = *(const LAS bf16x8*)(lds + PG8_SA(b, h) + aoff + m * 2048 + k * 1024); } while (0)
; #define PG8_LDB(dst, b, h) do { _Pragma("unroll") for (int n = 0; n < 2; ++n) _Pragma("unroll") for (int k = 0; k < 2; ++k) dst[n][k] = *(const LAS bf16x8*)(lds + PG8_SB(b, h) + boff + n * 2048 + k * 1024); } while (0)
; #define PG8_MMA(ai, bj, At, Bt) do { __builtin_amdgcn_s_setprio(1); _Pragma("unroll") for (int m = 0; m < 4; ++m) _Pragma("unroll") for (int n = 0; n < 2; ++n) _Pragma("unroll") for (int k = 0; k < 2; ++k) \
;         acc[ai][bj][m][n] = __builtin_amdgcn_mfma_f32_16x16x32_bf16(Bt[n][k], At[m][k], acc[ai][bj][m][n], 0, 0, 0); __builtin_amdgcn_s_setprio(0); } while (0)
; #define PG8_WAIT_L(n) asm volatile("s_waitcnt lgkmcnt(" #n ")" ::: "memory")
; #define PG8_BAR __builtin_amdgcn_s_barrier()
; #define PG8_SCHED __builtin_amdgcn_sched_barrier(0)
; template <class Epi>
; __device__ __forceinline__ void gemm_phase(LAS unsigned char* lds, const Gemm g, const StaticOrder& S, const Epi& E) {
;     ...
;             const bool last = (t == nt - 2);
;             const char* a1 = cA + (size_t)(t + 1) * kstepA;
;             const char* a2 = last ? nA : cA + (size_t)(t + 2) * kstepA; const char* b2 = last ? nB : cB + (size_t)(t + 2) * kstep;
;             const char* a3 = a2 + kstepA; const char* b3 = b2 + kstep;
;             PG8_LDB(B0, 0, 0); PG8_SCHED; PG8_LDA(At, 0, 0); PG8_STAGE(PG8_SA(1, 1), a1 + hstepA, voffA);
;             PG8_WAIT_L(8); PG8_BAR; PG8_WAIT_L(0); PG8_MMA(0, 0, At, B0); PG8_BAR; PG8_SCHED;
;             PG8_LDB(B1, 0, 1); PG8_STAGE(PG8_SB(0, 0), b2, voffB);
;             PG8_BAR; PG8_WAIT_L(0); PG8_MMA(0, 1, At, B1); PG8_BAR;
;             PG8_LDA(At, 0, 1); PG8_STAGE(PG8_SA(0, 0), a2, voffA);
;             PG8_BAR; PG8_WAIT_L(0); PG8_MMA(1, 0, At, B0); PG8_BAR; PG8_SCHED;
.LBB0_796:
	s_add_u32 s4, s8, 0x103400
	s_addc_u32 s5, s9, 0
	s_cmp_eq_u32 s57, 60
	s_cselect_b32 s16, s38, s4
	s_cselect_b32 s17, s37, s5
	s_cselect_b32 s4, s49, s51
	s_cselect_b32 s5, s39, s56
	s_add_u32 s14, s16, 0x104400
	s_addc_u32 s15, s17, 0
	s_add_i32 s58, 0, 0x10000
	v_add_u32_e32 v102, s58, v245
	ds_read_b128 v[26:29], v102
	ds_read_b128 v[30:33], v102 offset:1024
	ds_read_b128 v[98:101], v102 offset:2048
	ds_read_b128 v[102:105], v102 offset:3072
	v_lshl_add_u64 v[184:185], s[8:9], 0, v[196:197]
	s_add_i32 m0, s22, 0xc000
	ds_read_b128 v[130:133], v247
	ds_read_b128 v[142:145], v247 offset:1024
	ds_read_b128 v[146:149], v247 offset:2048
	ds_read_b128 v[150:153], v247 offset:3072
	ds_read_b128 v[154:157], v247 offset:4096
	ds_read_b128 v[166:169], v247 offset:5120
	ds_read_b128 v[170:173], v247 offset:6144
	ds_read_b128 v[174:177], v247 offset:7168
	global_load_lds_dwordx4 v[184:185], off
	v_lshl_add_u64 v[184:185], s[8:9], 0, v[198:199]
	s_add_i32 m0, s22, 0xe000
	s_nop 0
	global_load_lds_dwordx4 v[184:185], off
	s_waitcnt lgkmcnt(8)
	s_barrier
	s_waitcnt lgkmcnt(0)
	s_waitcnt lgkmcnt(0)
	v_mfma_f32_16x16x32_bf16 v[162:165], v[26:29], v[130:133], v[162:165]
	v_mfma_f32_16x16x32_bf16 v[158:161], v[98:101], v[130:133], v[158:161]
	v_mfma_f32_16x16x32_bf16 v[138:141], v[26:29], v[146:149], v[138:141]
	v_mfma_f32_16x16x32_bf16 v[134:137], v[98:101], v[146:149], v[134:137]
	v_mfma_f32_16x16x32_bf16 v[126:129], v[26:29], v[154:157], v[126:129]
	v_mfma_f32_16x16x32_bf16 v[122:125], v[98:101], v[154:157], v[122:125]
	v_mfma_f32_16x16x32_bf16 v[118:121], v[26:29], v[170:173], v[118:121]
	v_mfma_f32_16x16x32_bf16 v[114:117], v[98:101], v[170:173], v[114:117]
	v_mfma_f32_16x16x32_bf16 v[162:165], v[30:33], v[142:145], v[162:165]
	v_mfma_f32_16x16x32_bf16 v[158:161], v[102:105], v[142:145], v[158:161]
	v_mfma_f32_16x16x32_bf16 v[138:141], v[30:33], v[150:153], v[138:141]
	v_mfma_f32_16x16x32_bf16 v[134:137], v[102:105], v[150:153], v[134:137]
	v_mfma_f32_16x16x32_bf16 v[126:129], v[30:33], v[166:169], v[126:129]
	v_mfma_f32_16x16x32_bf16 v[122:125], v[102:105], v[166:169], v[122:125]
	v_mfma_f32_16x16x32_bf16 v[118:121], v[30:33], v[174:177], v[118:121]
	v_mfma_f32_16x16x32_bf16 v[114:117], v[102:105], v[174:177], v[114:117]
	s_barrier
	s_add_i32 s60, 0, 0x14000
	s_add_i32 s58, s58, s21
	v_add_u32_e32 v208, s60, v245
	v_lshl_add_u64 v[212:213], s[4:5], 0, v[0:1]
	s_mov_b32 m0, s58
	ds_read_b128 v[184:187], v208
	ds_read_b128 v[200:203], v208 offset:1024
	ds_read_b128 v[204:207], v208 offset:2048
	ds_read_b128 v[208:211], v208 offset:3072
	global_load_lds_dwordx4 v[212:213], off
	v_lshl_add_u64 v[214:215], s[4:5], 0, v[188:189]
	s_add_i32 m0, s58, 0x2000
	s_nop 0
	global_load_lds_dwordx4 v[214:215], off
	s_barrier
	s_waitcnt lgkmcnt(0)
	s_waitcnt lgkmcnt(0)
	v_mfma_f32_16x16x32_bf16 v[70:73], v[184:187], v[130:133], v[70:73]
	v_mfma_f32_16x16x32_bf16 v[66:69], v[204:207], v[130:133], v[66:69]
	v_mfma_f32_16x16x32_bf16 v[62:65], v[184:187], v[146:149], v[62:65]
	v_mfma_f32_16x16x32_bf16 v[58:61], v[204:207], v[146:149], v[58:61]
	v_mfma_f32_16x16x32_bf16 v[54:57], v[184:187], v[154:157], v[54:57]
	v_mfma_f32_16x16x32_bf16 v[50:53], v[204:207], v[154:157], v[50:53]
	v_mfma_f32_16x16x32_bf16 v[46:49], v[184:187], v[170:173], v[46:49]
	v_mfma_f32_16x16x32_bf16 v[42:45], v[204:207], v[170:173], v[42:45]
	v_mfma_f32_16x16x32_bf16 v[70:73], v[200:203], v[142:145], v[70:73]
	v_mfma_f32_16x16x32_bf16 v[66:69], v[208:211], v[142:145], v[66:69]
	v_mfma_f32_16x16x32_bf16 v[62:65], v[200:203], v[150:153], v[62:65]
	v_mfma_f32_16x16x32_bf16 v[58:61], v[208:211], v[150:153], v[58:61]
	v_mfma_f32_16x16x32_bf16 v[54:57], v[200:203], v[166:169], v[54:57]
	v_mfma_f32_16x16x32_bf16 v[50:53], v[208:211], v[166:169], v[50:53]
	v_mfma_f32_16x16x32_bf16 v[46:49], v[200:203], v[174:177], v[46:49]
	v_mfma_f32_16x16x32_bf16 v[42:45], v[208:211], v[174:177], v[42:45]
	s_mov_b32 m0, s22
	v_lshl_add_u64 v[216:217], s[16:17], 0, v[192:193]
	s_barrier
	ds_read_b128 v[130:133], v247 offset:16384
	ds_read_b128 v[142:145], v247 offset:17408
	ds_read_b128 v[146:149], v247 offset:18432
	ds_read_b128 v[150:153], v247 offset:19456
	ds_read_b128 v[154:157], v247 offset:20480
	ds_read_b128 v[166:169], v247 offset:21504
	ds_read_b128 v[170:173], v247 offset:22528
	ds_read_b128 v[174:177], v247 offset:23552
	global_load_lds_dwordx4 v[216:217], off
	v_lshl_add_u64 v[216:217], s[16:17], 0, v[190:191]
	s_mov_b32 m0, s23
	s_nop 0
	global_load_lds_dwordx4 v[216:217], off
	s_barrier
	s_waitcnt lgkmcnt(0)
	s_waitcnt lgkmcnt(0)
	v_mfma_f32_16x16x32_bf16 v[110:113], v[26:29], v[130:133], v[110:113]
	v_mfma_f32_16x16x32_bf16 v[106:109], v[98:101], v[130:133], v[106:109]
	v_mfma_f32_16x16x32_bf16 v[94:97], v[26:29], v[146:149], v[94:97]
	v_mfma_f32_16x16x32_bf16 v[90:93], v[98:101], v[146:149], v[90:93]
	v_mfma_f32_16x16x32_bf16 v[86:89], v[26:29], v[154:157], v[86:89]
	v_mfma_f32_16x16x32_bf16 v[82:85], v[98:101], v[154:157], v[82:85]
	v_mfma_f32_16x16x32_bf16 v[26:29], v[26:29], v[170:173], v[78:81]
	v_mfma_f32_16x16x32_bf16 v[110:113], v[30:33], v[142:145], v[110:113]
	v_mfma_f32_16x16x32_bf16 v[106:109], v[102:105], v[142:145], v[106:109]
	v_mfma_f32_16x16x32_bf16 v[94:97], v[30:33], v[150:153], v[94:97]
	v_mfma_f32_16x16x32_bf16 v[90:93], v[102:105], v[150:153], v[90:93]
	v_mfma_f32_16x16x32_bf16 v[86:89], v[30:33], v[166:169], v[86:89]
	v_mfma_f32_16x16x32_bf16 v[82:85], v[102:105], v[166:169], v[82:85]
	v_mfma_f32_16x16x32_bf16 v[26:29], v[30:33], v[174:177], v[26:29]
	v_mfma_f32_16x16x32_bf16 v[30:33], v[98:101], v[170:173], v[74:77]
	v_mfma_f32_16x16x32_bf16 v[30:33], v[102:105], v[174:177], v[30:33]
	s_barrier
; #define PG8_STAGE(bufoff, gbase, voff) do { _Pragma("unroll") for (int _i = 0; _i < 2; ++_i) \
;         __builtin_amdgcn_global_load_lds((const unsigned*)((const char*)(gbase) + (voff)[_i]), (LAS unsigned*)(lds + (bufoff) + ldsw + _i * 8192), 16, 0, 0); } while (0)
; #define PG8_LDA(dst, b, h) do { _Pragma("unroll") for (int m = 0; m < 4; ++m) _Pragma("unroll") for (int k = 0; k < 2; ++k) dst[m][k] = *(const LAS bf16x8*)(lds + PG8_SA(b, h) + aoff + m * 2048 + k * 1024); } while (0)
; #define PG8_LDB(dst, b, h) do { _Pragma("unroll") for (int n = 0; n < 2; ++n) _Pragma("unroll") for (int k = 0; k < 2; ++k) dst[n][k] = *(const LAS bf16x8*)(lds + PG8_SB(b, h) + boff + n * 2048 + k * 1024); } while (0)
; #define PG8_MMA(ai, bj, At, Bt) do { __builtin_amdgcn_s_setprio(1); _Pragma("unroll") for (int m = 0; m < 4; ++m) _Pragma("unroll") for (int n = 0; n < 2; ++n) _Pragma("unroll") for (int k = 0; k < 2; ++k) \
;         acc[ai][bj][m][n] = __builtin_amdgcn_mfma_f32_16x16x32_bf16(Bt[n][k], At[m][k], acc[ai][bj][m][n], 0, 0, 0); __builtin_amdgcn_s_setprio(0); } while (0)
; #define PG8_WAIT_V(n) asm volatile("s_waitcnt vmcnt(" #n ")" ::: "memory")
; #define PG8_WAIT_L(n) asm volatile("s_waitcnt lgkmcnt(" #n ")" ::: "memory")
; #define PG8_BAR __builtin_amdgcn_s_barrier()
; #define PG8_SCHED __builtin_amdgcn_sched_barrier(0)
; template <class Epi>
; __device__ __forceinline__ void gemm_phase(LAS unsigned char* lds, const Gemm g, const StaticOrder& S, const Epi& E) {
;     ...
;             PG8_STAGE(PG8_SB(0, 1), b2 + hstepB, voffB);
;             PG8_WAIT_V(6); PG8_BAR; PG8_MMA(1, 1, At, B1); PG8_BAR;
;             PG8_LDB(B0, 1, 0); PG8_SCHED; PG8_LDA(At, 1, 0); PG8_STAGE(PG8_SA(0, 1), a2 + hstepA, voffA);
;             PG8_WAIT_L(8); PG8_BAR; PG8_WAIT_L(0); PG8_MMA(0, 0, At, B0); PG8_BAR; PG8_SCHED;
;             PG8_LDB(B1, 1, 1); PG8_STAGE(PG8_SB(1, 0), b3, voffB);
;             PG8_BAR; PG8_WAIT_L(0); PG8_MMA(0, 1, At, B1); PG8_BAR;
;             PG8_LDA(At, 1, 1); PG8_STAGE(PG8_SA(1, 0), a3, voffA);
;             PG8_BAR; PG8_WAIT_L(0); PG8_MMA(1, 0, At, B0); PG8_BAR; PG8_SCHED;
	s_add_u32 s58, s4, 0x100000
	s_addc_u32 s59, s5, 0
	s_add_i32 s60, s60, s21
	v_lshl_add_u64 v[74:75], s[58:59], 0, v[0:1]
	s_mov_b32 m0, s60
	s_nop 0
	global_load_lds_dwordx4 v[74:75], off
	v_lshl_add_u64 v[74:75], s[58:59], 0, v[188:189]
	s_add_i32 m0, s60, 0x2000
	s_nop 0
	global_load_lds_dwordx4 v[74:75], off
	s_waitcnt vmcnt(6)
	s_barrier
	v_mfma_f32_16x16x32_bf16 v[38:41], v[184:187], v[130:133], v[38:41]
	v_mfma_f32_16x16x32_bf16 v[34:37], v[204:207], v[130:133], v[34:37]
	v_mfma_f32_16x16x32_bf16 v[22:25], v[184:187], v[146:149], v[22:25]
	v_mfma_f32_16x16x32_bf16 v[18:21], v[204:207], v[146:149], v[18:21]
	v_mfma_f32_16x16x32_bf16 v[14:17], v[184:187], v[154:157], v[14:17]
	v_mfma_f32_16x16x32_bf16 v[10:13], v[204:207], v[154:157], v[10:13]
	v_mfma_f32_16x16x32_bf16 v[6:9], v[184:187], v[170:173], v[6:9]
	v_mfma_f32_16x16x32_bf16 v[2:5], v[204:207], v[170:173], v[2:5]
	v_mfma_f32_16x16x32_bf16 v[38:41], v[200:203], v[142:145], v[38:41]
	v_mfma_f32_16x16x32_bf16 v[34:37], v[208:211], v[142:145], v[34:37]
	v_mfma_f32_16x16x32_bf16 v[22:25], v[200:203], v[150:153], v[22:25]
	v_mfma_f32_16x16x32_bf16 v[18:21], v[208:211], v[150:153], v[18:21]
	v_mfma_f32_16x16x32_bf16 v[14:17], v[200:203], v[166:169], v[14:17]
	v_mfma_f32_16x16x32_bf16 v[10:13], v[208:211], v[166:169], v[10:13]
	v_mfma_f32_16x16x32_bf16 v[6:9], v[200:203], v[174:177], v[6:9]
	v_mfma_f32_16x16x32_bf16 v[2:5], v[208:211], v[174:177], v[2:5]
	s_add_i32 s58, 0, 0x18000
	v_add_u32_e32 v102, s58, v245
	s_barrier
	ds_read_b128 v[74:77], v102
	ds_read_b128 v[78:81], v102 offset:1024
	ds_read_b128 v[98:101], v102 offset:2048
	ds_read_b128 v[102:105], v102 offset:3072
	s_add_u32 s16, s16, 0x1000
	s_addc_u32 s17, s17, 0
	s_mov_b32 m0, s24
	v_lshl_add_u64 v[184:185], s[16:17], 0, v[192:193]
	ds_read_b128 v[130:133], v247 offset:32768
	ds_read_b128 v[142:145], v247 offset:33792
	ds_read_b128 v[146:149], v247 offset:34816
	ds_read_b128 v[150:153], v247 offset:35840
	ds_read_b128 v[154:157], v247 offset:36864
	ds_read_b128 v[166:169], v247 offset:37888
	ds_read_b128 v[170:173], v247 offset:38912
	ds_read_b128 v[174:177], v247 offset:39936
	global_load_lds_dwordx4 v[184:185], off
	v_lshl_add_u64 v[184:185], s[16:17], 0, v[190:191]
	s_mov_b32 m0, s25
	s_nop 0
	global_load_lds_dwordx4 v[184:185], off
	s_waitcnt lgkmcnt(8)
	s_barrier
	s_waitcnt lgkmcnt(0)
	s_waitcnt lgkmcnt(0)
	v_mfma_f32_16x16x32_bf16 v[162:165], v[74:77], v[130:133], v[162:165]
	v_mfma_f32_16x16x32_bf16 v[158:161], v[98:101], v[130:133], v[158:161]
	v_mfma_f32_16x16x32_bf16 v[138:141], v[74:77], v[146:149], v[138:141]
	v_mfma_f32_16x16x32_bf16 v[134:137], v[98:101], v[146:149], v[134:137]
	v_mfma_f32_16x16x32_bf16 v[126:129], v[74:77], v[154:157], v[126:129]
	v_mfma_f32_16x16x32_bf16 v[122:125], v[98:101], v[154:157], v[122:125]
	v_mfma_f32_16x16x32_bf16 v[118:121], v[74:77], v[170:173], v[118:121]
	v_mfma_f32_16x16x32_bf16 v[114:117], v[98:101], v[170:173], v[114:117]
	v_mfma_f32_16x16x32_bf16 v[162:165], v[78:81], v[142:145], v[162:165]
	v_mfma_f32_16x16x32_bf16 v[158:161], v[102:105], v[142:145], v[158:161]
	v_mfma_f32_16x16x32_bf16 v[138:141], v[78:81], v[150:153], v[138:141]
	v_mfma_f32_16x16x32_bf16 v[134:137], v[102:105], v[150:153], v[134:137]
	v_mfma_f32_16x16x32_bf16 v[126:129], v[78:81], v[166:169], v[126:129]
	v_mfma_f32_16x16x32_bf16 v[122:125], v[102:105], v[166:169], v[122:125]
	v_mfma_f32_16x16x32_bf16 v[118:121], v[78:81], v[174:177], v[118:121]
	v_mfma_f32_16x16x32_bf16 v[114:117], v[102:105], v[174:177], v[114:117]
	s_barrier
	s_add_i32 s16, 0, 0x1c000
	s_add_i32 s17, s58, s21
	v_add_u32_e32 v208, s16, v245
	v_lshl_add_u64 v[212:213], v[212:213], 0, s[6:7]
	s_mov_b32 m0, s17
	ds_read_b128 v[184:187], v208
	ds_read_b128 v[200:203], v208 offset:1024
	ds_read_b128 v[204:207], v208 offset:2048
	ds_read_b128 v[208:211], v208 offset:3072
	global_load_lds_dwordx4 v[212:213], off
	v_lshl_add_u64 v[212:213], v[214:215], 0, s[6:7]
	s_add_i32 m0, s17, 0x2000
	s_nop 0
	global_load_lds_dwordx4 v[212:213], off
	s_barrier
	s_waitcnt lgkmcnt(0)
	s_waitcnt lgkmcnt(0)
	v_mfma_f32_16x16x32_bf16 v[70:73], v[184:187], v[130:133], v[70:73]
	v_mfma_f32_16x16x32_bf16 v[66:69], v[204:207], v[130:133], v[66:69]
	v_mfma_f32_16x16x32_bf16 v[62:65], v[184:187], v[146:149], v[62:65]
	v_mfma_f32_16x16x32_bf16 v[58:61], v[204:207], v[146:149], v[58:61]
	v_mfma_f32_16x16x32_bf16 v[54:57], v[184:187], v[154:157], v[54:57]
	v_mfma_f32_16x16x32_bf16 v[50:53], v[204:207], v[154:157], v[50:53]
	v_mfma_f32_16x16x32_bf16 v[46:49], v[184:187], v[170:173], v[46:49]
	v_mfma_f32_16x16x32_bf16 v[42:45], v[204:207], v[170:173], v[42:45]
	v_mfma_f32_16x16x32_bf16 v[70:73], v[200:203], v[142:145], v[70:73]
	v_mfma_f32_16x16x32_bf16 v[66:69], v[208:211], v[142:145], v[66:69]
	v_mfma_f32_16x16x32_bf16 v[62:65], v[200:203], v[150:153], v[62:65]
	v_mfma_f32_16x16x32_bf16 v[58:61], v[208:211], v[150:153], v[58:61]
	v_mfma_f32_16x16x32_bf16 v[54:57], v[200:203], v[166:169], v[54:57]
	v_mfma_f32_16x16x32_bf16 v[50:53], v[208:211], v[166:169], v[50:53]
	v_mfma_f32_16x16x32_bf16 v[46:49], v[200:203], v[174:177], v[46:49]
	v_mfma_f32_16x16x32_bf16 v[42:45], v[208:211], v[174:177], v[42:45]
	s_mov_b32 m0, s26
	v_lshl_add_u64 v[212:213], s[14:15], 0, v[192:193]
	s_barrier
	ds_read_b128 v[130:133], v247 offset:49152
	ds_read_b128 v[142:145], v247 offset:50176
	ds_read_b128 v[146:149], v247 offset:51200
	ds_read_b128 v[150:153], v247 offset:52224
	ds_read_b128 v[154:157], v247 offset:53248
	ds_read_b128 v[166:169], v247 offset:54272
	ds_read_b128 v[170:173], v247 offset:55296
	ds_read_b128 v[174:177], v247 offset:56320
	global_load_lds_dwordx4 v[212:213], off
	v_lshl_add_u64 v[212:213], s[14:15], 0, v[190:191]
	s_mov_b32 m0, s27
	s_nop 0
	global_load_lds_dwordx4 v[212:213], off
	s_barrier
; #define PG8_STAGE(bufoff, gbase, voff) do { _Pragma("unroll") for (int _i = 0; _i < 2; ++_i) \
;         __builtin_amdgcn_global_load_lds((const unsigned*)((const char*)(gbase) + (voff)[_i]), (LAS unsigned*)(lds + (bufoff) + ldsw + _i * 8192), 16, 0, 0); } while (0)
; #define PG8_MMA(ai, bj, At, Bt) do { __builtin_amdgcn_s_setprio(1); _Pragma("unroll") for (int m = 0; m < 4; ++m) _Pragma("unroll") for (int n = 0; n < 2; ++n) _Pragma("unroll") for (int k = 0; k < 2; ++k) \
;         acc[ai][bj][m][n] = __builtin_amdgcn_mfma_f32_16x16x32_bf16(Bt[n][k], At[m][k], acc[ai][bj][m][n], 0, 0, 0); __builtin_amdgcn_s_setprio(0); } while (0)
; #define PG8_WAIT_V(n) asm volatile("s_waitcnt vmcnt(" #n ")" ::: "memory")
; #define PG8_WAIT_L(n) asm volatile("s_waitcnt lgkmcnt(" #n ")" ::: "memory")
; #define PG8_BAR __builtin_amdgcn_s_barrier()
; #define PG8_SCHED __builtin_amdgcn_sched_barrier(0)
; template <class Epi>
; __device__ __forceinline__ void gemm_phase(LAS unsigned char* lds, const Gemm g, const StaticOrder& S, const Epi& E) {
;     ...
;             PG8_BAR; PG8_WAIT_L(0); PG8_MMA(1, 0, At, B0); PG8_BAR; PG8_SCHED;
;             PG8_STAGE(PG8_SB(1, 1), b3 + hstepB, voffB);
;             PG8_WAIT_V(6); PG8_BAR; PG8_MMA(1, 1, At, B1); PG8_BAR;
;         }
;         if constexpr (!Epi::AFTER_DRAIN) E(acc, cur, wr, wc, fr, fq, pre);
;     __device__ __forceinline__ void operator()(const f32x4 (&acc)[2][2][4][2], const Unit& u, int wr, int wc, int fr, int fq, const Pre&) const {
;         const int row0 = u.pm * BM + wr * 64 + fr, col0 = u.pn * BM + wc * 32 + 8 * fq;
;         f32x4 bs[2][2];
; #pragma unroll
;         for (int bj = 0; bj < 2; ++bj) { bs[bj][0] = *(const f32x4*)(bias + col0 + bj * HALF); bs[bj][1] = *(const f32x4*)(bias + col0 + bj * HALF + 4); }
; #pragma unroll
;         for (int bj = 0; bj < 2; ++bj) { const int c = col0 + bj * HALF;
; #pragma unroll
;             for (int ai = 0; ai < 2; ++ai) { u32x4 zv[4], gv[4];
; #pragma unroll
;                 for (int m = 0; m < 4; ++m) { const int r = row0 + ai * HALF + m * 16; zv[m] = *(const u32x4*)(Z + (size_t)r * DE2 + c); gv[m] = *(const u32x4*)(Gm + (size_t)(c >> 4) * GSTR + r * 16 + (c & 15)); }
	s_waitcnt lgkmcnt(0)
	s_waitcnt lgkmcnt(0)
	v_mfma_f32_16x16x32_bf16 v[110:113], v[74:77], v[130:133], v[110:113]
	v_mfma_f32_16x16x32_bf16 v[94:97], v[74:77], v[146:149], v[94:97]
	v_mfma_f32_16x16x32_bf16 v[86:89], v[74:77], v[154:157], v[86:89]
	v_mfma_f32_16x16x32_bf16 v[26:29], v[74:77], v[170:173], v[26:29]
	v_mfma_f32_16x16x32_bf16 v[110:113], v[78:81], v[142:145], v[110:113]
	v_mfma_f32_16x16x32_bf16 v[106:109], v[98:101], v[130:133], v[106:109]
	v_mfma_f32_16x16x32_bf16 v[94:97], v[78:81], v[150:153], v[94:97]
	v_mfma_f32_16x16x32_bf16 v[90:93], v[98:101], v[146:149], v[90:93]
	v_mfma_f32_16x16x32_bf16 v[86:89], v[78:81], v[166:169], v[86:89]
	v_mfma_f32_16x16x32_bf16 v[82:85], v[98:101], v[154:157], v[82:85]
	v_mfma_f32_16x16x32_bf16 v[78:81], v[78:81], v[174:177], v[26:29]
	v_mfma_f32_16x16x32_bf16 v[26:29], v[98:101], v[170:173], v[30:33]
	v_mfma_f32_16x16x32_bf16 v[106:109], v[102:105], v[142:145], v[106:109]
	v_mfma_f32_16x16x32_bf16 v[90:93], v[102:105], v[150:153], v[90:93]
	v_mfma_f32_16x16x32_bf16 v[82:85], v[102:105], v[166:169], v[82:85]
	v_mfma_f32_16x16x32_bf16 v[74:77], v[102:105], v[174:177], v[26:29]
	s_barrier
	s_add_u32 s4, s4, 0x100080
	s_addc_u32 s5, s5, 0
	s_add_i32 s14, s16, s21
	v_lshl_add_u64 v[26:27], s[4:5], 0, v[0:1]
	s_mov_b32 m0, s14
	s_nop 0
	global_load_lds_dwordx4 v[26:27], off
	v_lshl_add_u64 v[26:27], s[4:5], 0, v[188:189]
	s_add_i32 m0, s14, 0x2000
	s_nop 0
	global_load_lds_dwordx4 v[26:27], off
	s_waitcnt vmcnt(6)
	s_barrier
	v_mfma_f32_16x16x32_bf16 v[26:29], v[184:187], v[130:133], v[38:41]
	v_mfma_f32_16x16x32_bf16 v[38:41], v[200:203], v[142:145], v[26:29]
	v_mfma_f32_16x16x32_bf16 v[26:29], v[204:207], v[130:133], v[34:37]
	v_mfma_f32_16x16x32_bf16 v[22:25], v[184:187], v[146:149], v[22:25]
	v_mfma_f32_16x16x32_bf16 v[18:21], v[204:207], v[146:149], v[18:21]
	v_mfma_f32_16x16x32_bf16 v[14:17], v[184:187], v[154:157], v[14:17]
	v_mfma_f32_16x16x32_bf16 v[10:13], v[204:207], v[154:157], v[10:13]
	v_mfma_f32_16x16x32_bf16 v[6:9], v[184:187], v[170:173], v[6:9]
	v_mfma_f32_16x16x32_bf16 v[2:5], v[204:207], v[170:173], v[2:5]
	v_mfma_f32_16x16x32_bf16 v[34:37], v[208:211], v[142:145], v[26:29]
	v_mfma_f32_16x16x32_bf16 v[22:25], v[200:203], v[150:153], v[22:25]
	v_mfma_f32_16x16x32_bf16 v[18:21], v[208:211], v[150:153], v[18:21]
	v_mfma_f32_16x16x32_bf16 v[14:17], v[200:203], v[166:169], v[14:17]
	v_mfma_f32_16x16x32_bf16 v[10:13], v[208:211], v[166:169], v[10:13]
	v_mfma_f32_16x16x32_bf16 v[6:9], v[200:203], v[174:177], v[6:9]
	v_mfma_f32_16x16x32_bf16 v[2:5], v[208:211], v[174:177], v[2:5]
	s_add_i32 s57, s57, 2
	s_add_u32 s51, s51, 0x100
	s_addc_u32 s56, s56, 0
	s_add_u32 s8, s8, 0x208800
	s_addc_u32 s9, s9, 0
	s_cmp_gt_u32 s57, 61
	s_barrier
	s_cbranch_scc0 .LBB0_796
	v_lshl_or_b32 v200, s36, 8, v246
	v_ashrrev_i32_e32 v201, 31, v200
	v_lshl_add_u32 v224, s35, 8, v244
	v_lshlrev_b64 v[204:205], 1, v[200:201]
	v_ashrrev_i32_e32 v225, 31, v224
	v_ashrrev_i32_e32 v130, 4, v200
	v_lshl_add_u64 v[222:223], s[46:47], 0, v[204:205]
	v_lshlrev_b64 v[202:203], 14, v[224:225]
	v_lshl_add_u64 v[30:31], v[200:201], 2, s[10:11]
	v_mad_i64_i32 v[220:221], s[4:5], v130, s94, v[194:195]
	v_lshl_add_u64 v[130:131], v[222:223], 0, v[202:203]
	global_load_dwordx4 v[98:101], v[30:31], off offset:16
	global_load_dwordx4 v[102:105], v[30:31], off
	global_load_dwordx4 v[26:29], v[30:31], off offset:528
	s_nop 0
	global_load_dwordx4 v[30:33], v[30:31], off offset:512
	v_or_b32_e32 v226, 48, v224
	global_load_dwordx4 v[170:173], v[130:131], off
	v_lshlrev_b32_e32 v142, 4, v226
	v_ashrrev_i32_e32 v143, 31, v142
	v_lshlrev_b64 v[218:219], 1, v[142:143]
	v_lshl_add_u64 v[142:143], v[220:221], 0, v[218:219]
	global_load_dwordx4 v[142:145], v[142:143], off
	v_lshlrev_b32_e32 v130, 4, v224
	v_ashrrev_i32_e32 v131, 31, v130
	v_lshlrev_b64 v[206:207], 1, v[130:131]
	v_lshl_add_u64 v[130:131], v[220:221], 0, v[206:207]
	global_load_dwordx4 v[174:177], v[130:131], off
	v_or_b32_e32 v230, 16, v224
	v_ashrrev_i32_e32 v231, 31, v230
	v_lshlrev_b64 v[210:211], 14, v[230:231]
	v_lshl_add_u64 v[130:131], v[222:223], 0, v[210:211]
	global_load_dwordx4 v[154:157], v[130:131], off
	v_lshlrev_b32_e32 v130, 4, v230
	v_ashrrev_i32_e32 v131, 31, v130
	v_or_b32_e32 v228, 32, v224
	v_lshlrev_b64 v[208:209], 1, v[130:131]
	v_ashrrev_i32_e32 v229, 31, v228
	v_lshl_add_u64 v[130:131], v[220:221], 0, v[208:209]
	v_lshlrev_b64 v[214:215], 14, v[228:229]
	global_load_dwordx4 v[166:169], v[130:131], off
	v_lshl_add_u64 v[130:131], v[222:223], 0, v[214:215]
	global_load_dwordx4 v[146:149], v[130:131], off
	v_lshlrev_b32_e32 v130, 4, v228
	v_ashrrev_i32_e32 v131, 31, v130
	v_lshlrev_b64 v[212:213], 1, v[130:131]
	v_ashrrev_i32_e32 v227, 31, v226
	v_lshl_add_u64 v[130:131], v[220:221], 0, v[212:213]
	v_lshlrev_b64 v[216:217], 14, v[226:227]
	global_load_dwordx4 v[150:153], v[130:131], off
	v_lshl_add_u64 v[130:131], v[222:223], 0, v[216:217]
	global_load_dwordx4 v[130:133], v[130:131], off
	s_and_b64 vcc, exec, s[40:41]
	s_mov_b32 s35, s50
	s_mov_b32 s36, s48
	s_mov_b64 s[8:9], s[54:55]
	s_mov_b64 s[14:15], s[52:53]
	s_waitcnt vmcnt(0)
; __device__ __forceinline__ unsigned cvt_pk_bf16(float lo, float hi) { unsigned r; asm volatile("v_cvt_pk_bf16_f32 %0, %1, %2" : "=v"(r) : "v"(lo), "v"(hi)); return r; }
; __device__ __forceinline__ float bf_lo(unsigned w) { return __uint_as_float(w << 16); }
; __device__ __forceinline__ float bf_hi(unsigned w) { return __uint_as_float(w & 0xffff0000u); }
;     __device__ __forceinline__ void operator()(const f32x4 (&acc)[2][2][4][2], const Unit& u, int wr, int wc, int fr, int fq, const Pre&) const {
;     ...
;         for (int bj = 0; bj < 2; ++bj) { const int c = col0 + bj * HALF;
; #pragma unroll
;             for (int ai = 0; ai < 2; ++ai) { u32x4 zv[4], gv[4];
; #pragma unroll
;                 for (int m = 0; m < 4; ++m) { const int r = row0 + ai * HALF + m * 16; zv[m] = *(const u32x4*)(Z + (size_t)r * DE2 + c); gv[m] = *(const u32x4*)(Gm + (size_t)(c >> 4) * GSTR + r * 16 + (c & 15)); }
; #pragma unroll
;                 for (int m = 0; m < 4; ++m) { const int r = row0 + ai * HALF + m * 16;
;                     const u32x4 zw = zv[m], gw = gv[m];
;                     const f32x4 a0 = acc[ai][bj][m][0] + bs[bj][0], a1 = acc[ai][bj][m][1] + bs[bj][1];
;                     u32x4 w;
;                     w.x = cvt_pk_bf16(glu_gate_f(bf_lo(gw.x), a0[0], bf_lo(zw.x)), glu_gate_f(bf_hi(gw.x), a0[1], bf_hi(zw.x)));
;                     w.y = cvt_pk_bf16(glu_gate_f(bf_lo(gw.y), a0[2], bf_lo(zw.y)), glu_gate_f(bf_hi(gw.y), a0[3], bf_hi(zw.y)));
;                     w.z = cvt_pk_bf16(glu_gate_f(bf_lo(gw.z), a1[0], bf_lo(zw.z)), glu_gate_f(bf_hi(gw.z), a1[1], bf_hi(zw.z)));
;                     w.w = cvt_pk_bf16(glu_gate_f(bf_lo(gw.w), a1[2], bf_lo(zw.w)), glu_gate_f(bf_hi(gw.w), a1[3], bf_hi(zw.w)));
;                     *(u32x4*)(O + (size_t)r * DE + c) = w; } } }
	v_pk_add_f32 v[134:135], v[134:135], v[98:99]
	v_pk_add_f32 v[184:185], v[162:163], v[102:103]
	v_pk_add_f32 v[162:163], v[160:161], v[100:101]
	v_pk_add_f32 v[160:161], v[158:159], v[98:99]
	v_mul_f32_e32 v158, 0xbfb8aa3b, v184
	v_lshlrev_b32_e32 v186, 16, v170
	v_mul_f32_e32 v159, 0xbfb8aa3b, v186
	v_exp_f32_e32 v158, v158
	v_exp_f32_e32 v159, v159
	v_and_b32_e32 v170, 0xffff0000, v170
	v_pk_add_f32 v[164:165], v[164:165], v[104:105]
	v_mul_f32_e32 v160, 0xbfb8aa3b, v160
	v_pk_add_f32 v[158:159], v[158:159], 1.0 op_sel_hi:[1,0]
	v_mul_f32_e32 v164, 0xbfb8aa3b, v164
	v_mul_f32_e32 v158, v158, v159
	v_rcp_f32_e32 v158, v158
	v_lshlrev_b32_e32 v187, 16, v174
	v_mul_f32_e32 v184, v187, v186
	v_mul_f32_e32 v159, 0xbfb8aa3b, v170
	v_mul_f32_e32 v184, v184, v158
	v_mul_f32_e32 v158, 0xbfb8aa3b, v185
	v_exp_f32_e32 v158, v158
	v_exp_f32_e32 v159, v159
	v_and_b32_e32 v174, 0xffff0000, v174
	v_mul_f32_e32 v170, v174, v170
	v_mul_f32_e32 v162, 0xbfb8aa3b, v162
	v_pk_add_f32 v[158:159], v[158:159], 1.0 op_sel_hi:[1,0]
	v_pk_add_f32 v[138:139], v[138:139], v[102:103]
	v_mul_f32_e32 v158, v158, v159
	v_rcp_f32_e32 v158, v158
	v_lshlrev_b32_e32 v159, 16, v171
	v_and_b32_e32 v171, 0xffff0000, v171
	v_mul_f32_e32 v138, 0xbfb8aa3b, v138
	v_mul_f32_e32 v158, v170, v158
	v_cvt_pk_bf16_f32 v158, v184, v158
	v_exp_f32_e32 v184, v164
	v_mul_f32_e32 v164, 0xbfb8aa3b, v159
	v_exp_f32_e32 v185, v164
	v_lshlrev_b32_e32 v170, 16, v175
	v_mul_f32_e32 v159, v170, v159
	v_and_b32_e32 v170, 0xffff0000, v175
	v_pk_add_f32 v[184:185], v[184:185], 1.0 op_sel_hi:[1,0]
	v_mul_f32_e32 v170, v170, v171
	v_mul_f32_e32 v164, v184, v185
	v_rcp_f32_e32 v164, v164
	v_pk_add_f32 v[140:141], v[140:141], v[104:105]
	v_mul_f32_e32 v134, 0xbfb8aa3b, v134
	v_mul_f32_e32 v140, 0xbfb8aa3b, v140
	v_mul_f32_e32 v159, v159, v164
	v_mul_f32_e32 v164, 0xbfb8aa3b, v165
	v_mul_f32_e32 v165, 0xbfb8aa3b, v171
	v_exp_f32_e32 v164, v164
	v_exp_f32_e32 v165, v165
	v_lshlrev_b32_e32 v171, 16, v176
	v_pk_add_f32 v[136:137], v[136:137], v[100:101]
	v_pk_add_f32 v[126:127], v[126:127], v[102:103]
	v_pk_add_f32 v[164:165], v[164:165], 1.0 op_sel_hi:[1,0]
	v_mul_f32_e32 v126, 0xbfb8aa3b, v126
	v_mul_f32_e32 v164, v164, v165
	v_rcp_f32_e32 v164, v164
	v_pk_add_f32 v[128:129], v[128:129], v[104:105]
	v_pk_add_f32 v[122:123], v[122:123], v[98:99]
	v_mul_f32_e32 v128, 0xbfb8aa3b, v128
	v_mul_f32_e32 v164, v170, v164
	v_lshlrev_b32_e32 v170, 16, v172
	v_cvt_pk_bf16_f32 v159, v159, v164
	v_exp_f32_e32 v164, v160
	v_mul_f32_e32 v160, 0xbfb8aa3b, v170
	v_exp_f32_e32 v165, v160
	v_mul_f32_e32 v160, v171, v170
	v_and_b32_e32 v170, 0xffff0000, v172
	v_mul_f32_e32 v122, 0xbfb8aa3b, v122
	v_pk_add_f32 v[164:165], v[164:165], 1.0 op_sel_hi:[1,0]
	v_pk_add_f32 v[124:125], v[124:125], v[100:101]
	v_mul_f32_e32 v164, v164, v165
	v_rcp_f32_e32 v164, v164
	v_and_b32_e32 v165, 0xffff0000, v176
	v_mul_f32_e32 v165, v165, v170
	v_pk_add_f32 v[118:119], v[118:119], v[102:103]
	v_mul_f32_e32 v164, v160, v164
	v_mul_f32_e32 v160, 0xbfb8aa3b, v161
	v_mul_f32_e32 v161, 0xbfb8aa3b, v170
	v_exp_f32_e32 v160, v160
	v_exp_f32_e32 v161, v161
	v_lshlrev_b32_e32 v170, 16, v177
	v_mul_f32_e32 v118, 0xbfb8aa3b, v118
	v_pk_add_f32 v[120:121], v[120:121], v[104:105]
	v_pk_add_f32 v[160:161], v[160:161], 1.0 op_sel_hi:[1,0]
	v_mul_f32_e32 v120, 0xbfb8aa3b, v120
	v_mul_f32_e32 v160, v160, v161
	v_rcp_f32_e32 v160, v160
	v_lshlrev_b32_e32 v161, 16, v173
	v_pk_add_f32 v[114:115], v[114:115], v[98:99]
	v_pk_add_f32 v[116:117], v[116:117], v[100:101]
	v_mul_f32_e32 v160, v165, v160
	v_cvt_pk_bf16_f32 v160, v164, v160
	v_exp_f32_e32 v164, v162
	v_mul_f32_e32 v162, 0xbfb8aa3b, v161
	v_exp_f32_e32 v165, v162
	v_mul_f32_e32 v161, v170, v161
	v_mul_f32_e32 v114, 0xbfb8aa3b, v114
	v_add_u32_e32 v176, 0x80, v224
	v_pk_add_f32 v[164:165], v[164:165], 1.0 op_sel_hi:[1,0]
	v_add_u32_e32 v170, 0xb0, v224
	v_mul_f32_e32 v162, v164, v165
	v_rcp_f32_e32 v162, v162
	v_and_b32_e32 v165, 0xffff0000, v173
	v_and_b32_e32 v164, 0xffff0000, v177
	v_mul_f32_e32 v164, v164, v165
	v_mul_f32_e32 v161, v161, v162
	v_mul_f32_e32 v162, 0xbfb8aa3b, v163
	v_mul_f32_e32 v163, 0xbfb8aa3b, v165
	v_exp_f32_e32 v162, v162
	v_exp_f32_e32 v163, v163
	v_ashrrev_i32_e32 v177, 31, v176
	v_pk_add_f32 v[110:111], v[110:111], v[102:103]
	v_add_u32_e32 v174, 0x90, v224
	v_pk_add_f32 v[162:163], v[162:163], 1.0 op_sel_hi:[1,0]
	v_mul_f32_e32 v110, 0xbfb8aa3b, v110
	v_mul_f32_e32 v162, v162, v163
	v_rcp_f32_e32 v162, v162
	v_exp_f32_e32 v184, v110
	v_ashrrev_i32_e32 v175, 31, v174
	v_add_u32_e32 v172, 0xa0, v224
	v_mul_f32_e32 v162, v164, v162
	v_cvt_pk_bf16_f32 v161, v161, v162
	v_lshlrev_b64 v[162:163], 13, v[224:225]
	v_lshl_add_u64 v[162:163], s[44:45], 0, v[162:163]
	v_lshl_add_u64 v[162:163], v[162:163], 0, v[204:205]
	global_store_dwordx4 v[162:163], v[158:161], off
	v_ashrrev_i32_e32 v173, 31, v172
	v_ashrrev_i32_e32 v171, 31, v170
	v_lshlrev_b32_e32 v160, 16, v154
	v_exp_f32_e32 v158, v138
	v_mul_f32_e32 v138, 0xbfb8aa3b, v160
	v_exp_f32_e32 v159, v138
	v_lshlrev_b32_e32 v161, 16, v166
	v_mul_f32_e32 v138, v161, v160
	v_and_b32_e32 v154, 0xffff0000, v154
	v_pk_add_f32 v[158:159], v[158:159], 1.0 op_sel_hi:[1,0]
	v_lshlrev_b64 v[160:161], 14, v[172:173]
	v_mul_f32_e32 v158, v158, v159
	v_rcp_f32_e32 v158, v158
	v_and_b32_e32 v159, 0xffff0000, v166
	v_pk_add_f32 v[112:113], v[112:113], v[104:105]
	v_pk_add_f32 v[106:107], v[106:107], v[98:99]
	v_mul_f32_e32 v158, v138, v158
	v_mul_f32_e32 v138, 0xbfb8aa3b, v139
	v_mul_f32_e32 v139, 0xbfb8aa3b, v154
	v_exp_f32_e32 v138, v138
	v_exp_f32_e32 v139, v139
	v_mul_f32_e32 v154, v159, v154
	v_mul_f32_e32 v112, 0xbfb8aa3b, v112
; __device__ __forceinline__ unsigned cvt_pk_bf16(float lo, float hi) { unsigned r; asm volatile("v_cvt_pk_bf16_f32 %0, %1, %2" : "=v"(r) : "v"(lo), "v"(hi)); return r; }
; __device__ __forceinline__ float bf_lo(unsigned w) { return __uint_as_float(w << 16); }
; __device__ __forceinline__ float bf_hi(unsigned w) { return __uint_as_float(w & 0xffff0000u); }
;     __device__ __forceinline__ void operator()(const f32x4 (&acc)[2][2][4][2], const Unit& u, int wr, int wc, int fr, int fq, const Pre&) const {
;     ...
;         for (int bj = 0; bj < 2; ++bj) { const int c = col0 + bj * HALF;
; #pragma unroll
;             for (int ai = 0; ai < 2; ++ai) { u32x4 zv[4], gv[4];
; #pragma unroll
;                 for (int m = 0; m < 4; ++m) { const int r = row0 + ai * HALF + m * 16; zv[m] = *(const u32x4*)(Z + (size_t)r * DE2 + c); gv[m] = *(const u32x4*)(Gm + (size_t)(c >> 4) * GSTR + r * 16 + (c & 15)); }
; #pragma unroll
;                 for (int m = 0; m < 4; ++m) { const int r = row0 + ai * HALF + m * 16;
;                     const u32x4 zw = zv[m], gw = gv[m];
;                     const f32x4 a0 = acc[ai][bj][m][0] + bs[bj][0], a1 = acc[ai][bj][m][1] + bs[bj][1];
;                     u32x4 w;
;                     w.x = cvt_pk_bf16(glu_gate_f(bf_lo(gw.x), a0[0], bf_lo(zw.x)), glu_gate_f(bf_hi(gw.x), a0[1], bf_hi(zw.x)));
;                     w.y = cvt_pk_bf16(glu_gate_f(bf_lo(gw.y), a0[2], bf_lo(zw.y)), glu_gate_f(bf_hi(gw.y), a0[3], bf_hi(zw.y)));
;                     w.z = cvt_pk_bf16(glu_gate_f(bf_lo(gw.z), a1[0], bf_lo(zw.z)), glu_gate_f(bf_hi(gw.z), a1[1], bf_hi(zw.z)));
;                     w.w = cvt_pk_bf16(glu_gate_f(bf_lo(gw.w), a1[2], bf_lo(zw.w)), glu_gate_f(bf_hi(gw.w), a1[3], bf_hi(zw.w)));
;                     *(u32x4*)(O + (size_t)r * DE + c) = w; } } }
	v_mul_f32_e32 v106, 0xbfb8aa3b, v106
	v_pk_add_f32 v[138:139], v[138:139], 1.0 op_sel_hi:[1,0]
	v_pk_add_f32 v[108:109], v[108:109], v[100:101]
	v_mul_f32_e32 v138, v138, v139
	v_rcp_f32_e32 v138, v138
	v_lshlrev_b32_e32 v139, 16, v155
	v_and_b32_e32 v155, 0xffff0000, v155
	v_pk_add_f32 v[94:95], v[94:95], v[102:103]
	v_mul_f32_e32 v138, v154, v138
	v_cvt_pk_bf16_f32 v138, v158, v138
	v_exp_f32_e32 v158, v140
	v_mul_f32_e32 v140, 0xbfb8aa3b, v139
	v_exp_f32_e32 v159, v140
	v_lshlrev_b32_e32 v154, 16, v167
	v_mul_f32_e32 v139, v154, v139
	v_and_b32_e32 v154, 0xffff0000, v167
	v_pk_add_f32 v[158:159], v[158:159], 1.0 op_sel_hi:[1,0]
	v_mul_f32_e32 v154, v154, v155
	v_mul_f32_e32 v140, v158, v159
	v_rcp_f32_e32 v140, v140
	v_lshlrev_b64 v[166:167], 14, v[170:171]
	v_mul_f32_e32 v94, 0xbfb8aa3b, v94
	v_pk_add_f32 v[96:97], v[96:97], v[104:105]
	v_mul_f32_e32 v139, v139, v140
	v_mul_f32_e32 v140, 0xbfb8aa3b, v141
	v_mul_f32_e32 v141, 0xbfb8aa3b, v155
	v_exp_f32_e32 v140, v140
	v_exp_f32_e32 v141, v141
	v_lshlrev_b32_e32 v155, 16, v168
	v_mul_f32_e32 v96, 0xbfb8aa3b, v96
	v_pk_add_f32 v[90:91], v[90:91], v[98:99]
	v_pk_add_f32 v[140:141], v[140:141], 1.0 op_sel_hi:[1,0]
	v_mul_f32_e32 v90, 0xbfb8aa3b, v90
	v_mul_f32_e32 v140, v140, v141
	v_rcp_f32_e32 v140, v140
	v_pk_add_f32 v[92:93], v[92:93], v[100:101]
	v_pk_add_f32 v[86:87], v[86:87], v[102:103]
	v_pk_add_f32 v[88:89], v[88:89], v[104:105]
	v_mul_f32_e32 v140, v154, v140
	v_lshlrev_b32_e32 v154, 16, v156
	v_cvt_pk_bf16_f32 v139, v139, v140
	v_exp_f32_e32 v140, v134
	v_mul_f32_e32 v134, 0xbfb8aa3b, v154
	v_exp_f32_e32 v141, v134
	v_mul_f32_e32 v134, v155, v154
	v_and_b32_e32 v154, 0xffff0000, v156
	v_mul_f32_e32 v86, 0xbfb8aa3b, v86
	v_pk_add_f32 v[140:141], v[140:141], 1.0 op_sel_hi:[1,0]
	v_mul_f32_e32 v88, 0xbfb8aa3b, v88
	v_mul_f32_e32 v140, v140, v141
	v_rcp_f32_e32 v140, v140
	v_and_b32_e32 v141, 0xffff0000, v168
	v_mul_f32_e32 v141, v141, v154
	v_pk_add_f32 v[82:83], v[82:83], v[98:99]
	v_mul_f32_e32 v140, v134, v140
	v_mul_f32_e32 v134, 0xbfb8aa3b, v135
	v_mul_f32_e32 v135, 0xbfb8aa3b, v154
	v_exp_f32_e32 v134, v134
	v_exp_f32_e32 v135, v135
	v_lshlrev_b32_e32 v154, 16, v169
	v_mul_f32_e32 v82, 0xbfb8aa3b, v82
	v_pk_add_f32 v[84:85], v[84:85], v[100:101]
	v_pk_add_f32 v[134:135], v[134:135], 1.0 op_sel_hi:[1,0]
	v_pk_add_f32 v[78:79], v[78:79], v[102:103]
	v_mul_f32_e32 v134, v134, v135
	v_rcp_f32_e32 v134, v134
	v_mul_f32_e32 v78, 0xbfb8aa3b, v78
	v_pk_add_f32 v[80:81], v[80:81], v[104:105]
	v_pk_add_f32 v[74:75], v[74:75], v[98:99]
	v_mul_f32_e32 v134, v141, v134
	v_lshlrev_b32_e32 v141, 16, v157
	v_cvt_pk_bf16_f32 v140, v140, v134
	v_mul_f32_e32 v134, 0xbfb8aa3b, v136
	v_mul_f32_e32 v135, 0xbfb8aa3b, v141
	v_exp_f32_e32 v134, v134
	v_exp_f32_e32 v135, v135
	v_mul_f32_e32 v136, v154, v141
	v_and_b32_e32 v154, 0xffff0000, v157
	v_and_b32_e32 v141, 0xffff0000, v169
	v_pk_add_f32 v[134:135], v[134:135], 1.0 op_sel_hi:[1,0]
	v_lshlrev_b64 v[156:157], 14, v[174:175]
	v_mul_f32_e32 v134, v134, v135
	v_rcp_f32_e32 v134, v134
	v_mul_f32_e32 v135, 0xbfb8aa3b, v154
	v_exp_f32_e32 v135, v135
	v_mul_f32_e32 v80, 0xbfb8aa3b, v80
	v_mul_f32_e32 v136, v136, v134
	v_mul_f32_e32 v134, 0xbfb8aa3b, v137
	v_exp_f32_e32 v134, v134
	v_mul_f32_e32 v137, v141, v154
	v_mul_f32_e32 v74, 0xbfb8aa3b, v74
	v_pk_add_f32 v[76:77], v[76:77], v[100:101]
	v_pk_add_f32 v[134:135], v[134:135], 1.0 op_sel_hi:[1,0]
	v_pk_add_f32 v[70:71], v[70:71], v[30:31]
	v_mul_f32_e32 v134, v134, v135
	v_rcp_f32_e32 v134, v134
	v_mul_f32_e32 v70, 0xbfb8aa3b, v70
	v_pk_add_f32 v[72:73], v[72:73], v[32:33]
	v_pk_add_f32 v[66:67], v[66:67], v[26:27]
	v_mul_f32_e32 v134, v137, v134
	v_cvt_pk_bf16_f32 v141, v136, v134
	v_lshlrev_b64 v[134:135], 13, v[230:231]
	v_lshl_add_u64 v[134:135], s[44:45], 0, v[134:135]
	v_lshlrev_b32_e32 v136, 16, v146
	v_lshl_add_u64 v[154:155], v[134:135], 0, v[204:205]
	v_exp_f32_e32 v134, v126
	v_mul_f32_e32 v126, 0xbfb8aa3b, v136
	v_exp_f32_e32 v135, v126
	v_lshlrev_b32_e32 v137, 16, v150
	v_mul_f32_e32 v126, v137, v136
	v_and_b32_e32 v136, 0xffff0000, v146
	v_pk_add_f32 v[134:135], v[134:135], 1.0 op_sel_hi:[1,0]
	global_store_dwordx4 v[154:155], v[138:141], off
	v_mul_f32_e32 v134, v134, v135
	v_rcp_f32_e32 v134, v134
	v_and_b32_e32 v135, 0xffff0000, v150
	v_mul_f32_e32 v135, v135, v136
	v_mul_f32_e32 v72, 0xbfb8aa3b, v72
	v_mul_f32_e32 v134, v126, v134
	v_mul_f32_e32 v126, 0xbfb8aa3b, v127
	v_mul_f32_e32 v127, 0xbfb8aa3b, v136
	v_exp_f32_e32 v126, v126
	v_exp_f32_e32 v127, v127
	v_lshlrev_b32_e32 v136, 16, v151
	v_mul_f32_e32 v66, 0xbfb8aa3b, v66
	v_pk_add_f32 v[68:69], v[68:69], v[28:29]
	v_pk_add_f32 v[126:127], v[126:127], 1.0 op_sel_hi:[1,0]
	v_pk_add_f32 v[62:63], v[62:63], v[30:31]
	v_mul_f32_e32 v126, v126, v127
	v_rcp_f32_e32 v126, v126
	v_lshlrev_b32_e32 v127, 16, v147
	v_mul_f32_e32 v62, 0xbfb8aa3b, v62
	v_pk_add_f32 v[64:65], v[64:65], v[32:33]
	v_mul_f32_e32 v126, v135, v126
	v_cvt_pk_bf16_f32 v126, v134, v126
	v_exp_f32_e32 v134, v128
	v_mul_f32_e32 v128, 0xbfb8aa3b, v127
	v_exp_f32_e32 v135, v128
	v_mul_f32_e32 v127, v136, v127
	v_mul_f32_e32 v64, 0xbfb8aa3b, v64
	v_pk_add_f32 v[58:59], v[58:59], v[26:27]
	v_pk_add_f32 v[134:135], v[134:135], 1.0 op_sel_hi:[1,0]
	v_mul_f32_e32 v58, 0xbfb8aa3b, v58
	v_mul_f32_e32 v128, v134, v135
	v_rcp_f32_e32 v128, v128
	v_and_b32_e32 v135, 0xffff0000, v147
	v_and_b32_e32 v134, 0xffff0000, v151
	v_mul_f32_e32 v134, v134, v135
	v_mul_f32_e32 v127, v127, v128
	v_mul_f32_e32 v128, 0xbfb8aa3b, v129
	v_mul_f32_e32 v129, 0xbfb8aa3b, v135
	v_exp_f32_e32 v128, v128
	v_exp_f32_e32 v129, v129
	v_lshlrev_b32_e32 v135, 16, v152
	v_lshlrev_b64 v[150:151], 14, v[176:177]
; __device__ __forceinline__ unsigned cvt_pk_bf16(float lo, float hi) { unsigned r; asm volatile("v_cvt_pk_bf16_f32 %0, %1, %2" : "=v"(r) : "v"(lo), "v"(hi)); return r; }
; __device__ __forceinline__ float bf_lo(unsigned w) { return __uint_as_float(w << 16); }
; __device__ __forceinline__ float bf_hi(unsigned w) { return __uint_as_float(w & 0xffff0000u); }
;     __device__ __forceinline__ void operator()(const f32x4 (&acc)[2][2][4][2], const Unit& u, int wr, int wc, int fr, int fq, const Pre&) const {
;     ...
;         for (int bj = 0; bj < 2; ++bj) { const int c = col0 + bj * HALF;
; #pragma unroll
;             for (int ai = 0; ai < 2; ++ai) { u32x4 zv[4], gv[4];
; #pragma unroll
;                 for (int m = 0; m < 4; ++m) { const int r = row0 + ai * HALF + m * 16; zv[m] = *(const u32x4*)(Z + (size_t)r * DE2 + c); gv[m] = *(const u32x4*)(Gm + (size_t)(c >> 4) * GSTR + r * 16 + (c & 15)); }
; #pragma unroll
;                 for (int m = 0; m < 4; ++m) { const int r = row0 + ai * HALF + m * 16;
;                     const u32x4 zw = zv[m], gw = gv[m];
;                     const f32x4 a0 = acc[ai][bj][m][0] + bs[bj][0], a1 = acc[ai][bj][m][1] + bs[bj][1];
;                     u32x4 w;
;                     w.x = cvt_pk_bf16(glu_gate_f(bf_lo(gw.x), a0[0], bf_lo(zw.x)), glu_gate_f(bf_hi(gw.x), a0[1], bf_hi(zw.x)));
;                     w.y = cvt_pk_bf16(glu_gate_f(bf_lo(gw.y), a0[2], bf_lo(zw.y)), glu_gate_f(bf_hi(gw.y), a0[3], bf_hi(zw.y)));
;                     w.z = cvt_pk_bf16(glu_gate_f(bf_lo(gw.z), a1[0], bf_lo(zw.z)), glu_gate_f(bf_hi(gw.z), a1[1], bf_hi(zw.z)));
;                     w.w = cvt_pk_bf16(glu_gate_f(bf_lo(gw.w), a1[2], bf_lo(zw.w)), glu_gate_f(bf_hi(gw.w), a1[3], bf_hi(zw.w)));
;                     *(u32x4*)(O + (size_t)r * DE + c) = w; } } }
	v_pk_add_f32 v[60:61], v[60:61], v[28:29]
	v_pk_add_f32 v[128:129], v[128:129], 1.0 op_sel_hi:[1,0]
	v_pk_add_f32 v[54:55], v[54:55], v[30:31]
	v_mul_f32_e32 v128, v128, v129
	v_rcp_f32_e32 v128, v128
	v_mul_f32_e32 v54, 0xbfb8aa3b, v54
	v_pk_add_f32 v[56:57], v[56:57], v[32:33]
	v_pk_add_f32 v[50:51], v[50:51], v[26:27]
	v_mul_f32_e32 v128, v134, v128
	v_lshlrev_b32_e32 v134, 16, v148
	v_cvt_pk_bf16_f32 v127, v127, v128
	v_exp_f32_e32 v128, v122
	v_mul_f32_e32 v122, 0xbfb8aa3b, v134
	v_exp_f32_e32 v129, v122
	v_mul_f32_e32 v122, v135, v134
	v_and_b32_e32 v134, 0xffff0000, v148
	v_mul_f32_e32 v56, 0xbfb8aa3b, v56
	v_pk_add_f32 v[128:129], v[128:129], 1.0 op_sel_hi:[1,0]
	v_mul_f32_e32 v50, 0xbfb8aa3b, v50
	v_mul_f32_e32 v128, v128, v129
	v_rcp_f32_e32 v128, v128
	v_and_b32_e32 v129, 0xffff0000, v152
	v_mul_f32_e32 v129, v129, v134
	v_pk_add_f32 v[52:53], v[52:53], v[28:29]
	v_mul_f32_e32 v128, v122, v128
	v_mul_f32_e32 v122, 0xbfb8aa3b, v123
	v_mul_f32_e32 v123, 0xbfb8aa3b, v134
	v_exp_f32_e32 v122, v122
	v_exp_f32_e32 v123, v123
	v_lshlrev_b32_e32 v134, 16, v153
	v_pk_add_f32 v[46:47], v[46:47], v[30:31]
	v_pk_add_f32 v[48:49], v[48:49], v[32:33]
	v_pk_add_f32 v[122:123], v[122:123], 1.0 op_sel_hi:[1,0]
	v_mul_f32_e32 v46, 0xbfb8aa3b, v46
	v_mul_f32_e32 v122, v122, v123
	v_rcp_f32_e32 v122, v122
	v_mul_f32_e32 v48, 0xbfb8aa3b, v48
	v_pk_add_f32 v[42:43], v[42:43], v[26:27]
	v_pk_add_f32 v[44:45], v[44:45], v[28:29]
	v_mul_f32_e32 v122, v129, v122
	v_lshlrev_b32_e32 v129, 16, v149
	v_cvt_pk_bf16_f32 v128, v128, v122
	v_mul_f32_e32 v122, 0xbfb8aa3b, v124
	v_mul_f32_e32 v123, 0xbfb8aa3b, v129
	v_exp_f32_e32 v122, v122
	v_exp_f32_e32 v123, v123
	v_mul_f32_e32 v124, v134, v129
	v_and_b32_e32 v134, 0xffff0000, v149
	v_and_b32_e32 v129, 0xffff0000, v153
	v_pk_add_f32 v[122:123], v[122:123], 1.0 op_sel_hi:[1,0]
	v_mul_f32_e32 v42, 0xbfb8aa3b, v42
	v_mul_f32_e32 v122, v122, v123
	v_rcp_f32_e32 v122, v122
	v_mul_f32_e32 v123, 0xbfb8aa3b, v134
	v_exp_f32_e32 v123, v123
	v_pk_add_f32 v[38:39], v[38:39], v[30:31]
	v_mul_f32_e32 v124, v124, v122
	v_mul_f32_e32 v122, 0xbfb8aa3b, v125
	v_exp_f32_e32 v122, v122
	v_mul_f32_e32 v125, v129, v134
	v_mul_f32_e32 v38, 0xbfb8aa3b, v38
	v_pk_add_f32 v[40:41], v[40:41], v[32:33]
	v_pk_add_f32 v[122:123], v[122:123], 1.0 op_sel_hi:[1,0]
	v_mul_f32_e32 v40, 0xbfb8aa3b, v40
	v_mul_f32_e32 v122, v122, v123
	v_rcp_f32_e32 v122, v122
	v_pk_add_f32 v[34:35], v[34:35], v[26:27]
	v_pk_add_f32 v[36:37], v[36:37], v[28:29]
	v_mul_f32_e32 v34, 0xbfb8aa3b, v34
	v_mul_f32_e32 v122, v125, v122
	v_cvt_pk_bf16_f32 v129, v124, v122
	v_lshlrev_b64 v[122:123], 13, v[228:229]
	v_lshl_add_u64 v[122:123], s[44:45], 0, v[122:123]
	v_lshlrev_b32_e32 v124, 16, v130
	v_lshl_add_u64 v[146:147], v[122:123], 0, v[204:205]
	v_exp_f32_e32 v122, v118
	v_mul_f32_e32 v118, 0xbfb8aa3b, v124
	v_exp_f32_e32 v123, v118
	v_lshlrev_b32_e32 v125, 16, v142
	v_mul_f32_e32 v118, v125, v124
	v_and_b32_e32 v124, 0xffff0000, v130
	v_pk_add_f32 v[122:123], v[122:123], 1.0 op_sel_hi:[1,0]
	global_store_dwordx4 v[146:147], v[126:129], off
	v_mul_f32_e32 v122, v122, v123
	v_rcp_f32_e32 v122, v122
	v_and_b32_e32 v123, 0xffff0000, v142
	v_mul_f32_e32 v123, v123, v124
	v_pk_add_f32 v[22:23], v[22:23], v[30:31]
	v_mul_f32_e32 v122, v118, v122
	v_mul_f32_e32 v118, 0xbfb8aa3b, v119
	v_mul_f32_e32 v119, 0xbfb8aa3b, v124
	v_exp_f32_e32 v118, v118
	v_exp_f32_e32 v119, v119
	v_lshlrev_b32_e32 v124, 16, v143
	v_mul_f32_e32 v22, 0xbfb8aa3b, v22
	v_pk_add_f32 v[24:25], v[24:25], v[32:33]
	v_pk_add_f32 v[118:119], v[118:119], 1.0 op_sel_hi:[1,0]
	v_mul_f32_e32 v24, 0xbfb8aa3b, v24
	v_mul_f32_e32 v118, v118, v119
	v_rcp_f32_e32 v118, v118
	v_lshlrev_b32_e32 v119, 16, v131
	v_pk_add_f32 v[18:19], v[18:19], v[26:27]
	v_pk_add_f32 v[20:21], v[20:21], v[28:29]
	v_mul_f32_e32 v118, v123, v118
	v_cvt_pk_bf16_f32 v118, v122, v118
	v_exp_f32_e32 v122, v120
	v_mul_f32_e32 v120, 0xbfb8aa3b, v119
	v_exp_f32_e32 v123, v120
	v_mul_f32_e32 v119, v124, v119
	v_mul_f32_e32 v18, 0xbfb8aa3b, v18
	v_pk_add_f32 v[14:15], v[14:15], v[30:31]
	v_pk_add_f32 v[122:123], v[122:123], 1.0 op_sel_hi:[1,0]
	v_mul_f32_e32 v14, 0xbfb8aa3b, v14
	v_mul_f32_e32 v120, v122, v123
	v_rcp_f32_e32 v120, v120
	v_and_b32_e32 v123, 0xffff0000, v131
	v_and_b32_e32 v122, 0xffff0000, v143
	v_mul_f32_e32 v122, v122, v123
	v_mul_f32_e32 v119, v119, v120
	v_mul_f32_e32 v120, 0xbfb8aa3b, v121
	v_mul_f32_e32 v121, 0xbfb8aa3b, v123
	v_exp_f32_e32 v120, v120
	v_exp_f32_e32 v121, v121
	v_lshlrev_b32_e32 v123, 16, v144
	v_pk_add_f32 v[16:17], v[16:17], v[32:33]
	v_pk_add_f32 v[10:11], v[10:11], v[26:27]
	v_pk_add_f32 v[120:121], v[120:121], 1.0 op_sel_hi:[1,0]
	v_mul_f32_e32 v16, 0xbfb8aa3b, v16
	v_mul_f32_e32 v120, v120, v121
	v_rcp_f32_e32 v120, v120
	v_mul_f32_e32 v10, 0xbfb8aa3b, v10
	v_pk_add_f32 v[12:13], v[12:13], v[28:29]
	v_pk_add_f32 v[6:7], v[6:7], v[30:31]
	v_mul_f32_e32 v120, v122, v120
	v_lshlrev_b32_e32 v122, 16, v132
	v_cvt_pk_bf16_f32 v119, v119, v120
	v_exp_f32_e32 v120, v114
	v_mul_f32_e32 v114, 0xbfb8aa3b, v122
	v_exp_f32_e32 v121, v114
	v_mul_f32_e32 v114, v123, v122
	v_and_b32_e32 v122, 0xffff0000, v132
	v_mul_f32_e32 v6, 0xbfb8aa3b, v6
	v_pk_add_f32 v[120:121], v[120:121], 1.0 op_sel_hi:[1,0]
	v_pk_add_f32 v[8:9], v[8:9], v[32:33]
	v_mul_f32_e32 v120, v120, v121
	v_rcp_f32_e32 v120, v120
	v_and_b32_e32 v121, 0xffff0000, v144
	v_mul_f32_e32 v121, v121, v122
	v_mul_f32_e32 v8, 0xbfb8aa3b, v8
	v_mul_f32_e32 v120, v114, v120
	v_mul_f32_e32 v114, 0xbfb8aa3b, v115
	v_mul_f32_e32 v115, 0xbfb8aa3b, v122
	v_exp_f32_e32 v114, v114
	v_exp_f32_e32 v115, v115
	v_lshlrev_b32_e32 v122, 16, v145
	v_pk_add_f32 v[2:3], v[2:3], v[26:27]
; __device__ __forceinline__ unsigned cvt_pk_bf16(float lo, float hi) { unsigned r; asm volatile("v_cvt_pk_bf16_f32 %0, %1, %2" : "=v"(r) : "v"(lo), "v"(hi)); return r; }
; __device__ __forceinline__ float bf_lo(unsigned w) { return __uint_as_float(w << 16); }
; __device__ __forceinline__ float bf_hi(unsigned w) { return __uint_as_float(w & 0xffff0000u); }
;     __device__ __forceinline__ void operator()(const f32x4 (&acc)[2][2][4][2], const Unit& u, int wr, int wc, int fr, int fq, const Pre&) const {
;     ...
;             for (int ai = 0; ai < 2; ++ai) { u32x4 zv[4], gv[4];
; #pragma unroll
;                 for (int m = 0; m < 4; ++m) { const int r = row0 + ai * HALF + m * 16; zv[m] = *(const u32x4*)(Z + (size_t)r * DE2 + c); gv[m] = *(const u32x4*)(Gm + (size_t)(c >> 4) * GSTR + r * 16 + (c & 15)); }
; #pragma unroll
;                 for (int m = 0; m < 4; ++m) { const int r = row0 + ai * HALF + m * 16;
;                     const u32x4 zw = zv[m], gw = gv[m];
;                     const f32x4 a0 = acc[ai][bj][m][0] + bs[bj][0], a1 = acc[ai][bj][m][1] + bs[bj][1];
;                     u32x4 w;
;                     w.x = cvt_pk_bf16(glu_gate_f(bf_lo(gw.x), a0[0], bf_lo(zw.x)), glu_gate_f(bf_hi(gw.x), a0[1], bf_hi(zw.x)));
;                     w.y = cvt_pk_bf16(glu_gate_f(bf_lo(gw.y), a0[2], bf_lo(zw.y)), glu_gate_f(bf_hi(gw.y), a0[3], bf_hi(zw.y)));
;                     w.z = cvt_pk_bf16(glu_gate_f(bf_lo(gw.z), a1[0], bf_lo(zw.z)), glu_gate_f(bf_hi(gw.z), a1[1], bf_hi(zw.z)));
;                     w.w = cvt_pk_bf16(glu_gate_f(bf_lo(gw.w), a1[2], bf_lo(zw.w)), glu_gate_f(bf_hi(gw.w), a1[3], bf_hi(zw.w)));
;                     *(u32x4*)(O + (size_t)r * DE + c) = w; } } }
	v_pk_add_f32 v[4:5], v[4:5], v[28:29]
	v_pk_add_f32 v[114:115], v[114:115], 1.0 op_sel_hi:[1,0]
	v_mul_f32_e32 v2, 0xbfb8aa3b, v2
	v_mul_f32_e32 v114, v114, v115
	v_rcp_f32_e32 v114, v114
	s_nop 0
	v_mul_f32_e32 v114, v121, v114
	v_lshlrev_b32_e32 v121, 16, v133
	v_cvt_pk_bf16_f32 v120, v120, v114
	v_mul_f32_e32 v114, 0xbfb8aa3b, v116
	v_mul_f32_e32 v115, 0xbfb8aa3b, v121
	v_exp_f32_e32 v114, v114
	v_exp_f32_e32 v115, v115
	v_mul_f32_e32 v116, v122, v121
	v_and_b32_e32 v122, 0xffff0000, v133
	v_and_b32_e32 v121, 0xffff0000, v145
	v_pk_add_f32 v[114:115], v[114:115], 1.0 op_sel_hi:[1,0]
	s_nop 0
	v_mul_f32_e32 v114, v114, v115
	v_rcp_f32_e32 v114, v114
	v_mul_f32_e32 v115, 0xbfb8aa3b, v122
	v_exp_f32_e32 v115, v115
	v_mul_f32_e32 v116, v116, v114
	v_mul_f32_e32 v114, 0xbfb8aa3b, v117
	v_exp_f32_e32 v114, v114
	v_mul_f32_e32 v117, v121, v122
	v_pk_add_f32 v[114:115], v[114:115], 1.0 op_sel_hi:[1,0]
	s_nop 0
	v_mul_f32_e32 v114, v114, v115
	v_rcp_f32_e32 v114, v114
	s_nop 0
	v_mul_f32_e32 v114, v117, v114
	v_cvt_pk_bf16_f32 v121, v116, v114
	v_lshlrev_b64 v[114:115], 13, v[226:227]
	v_lshl_add_u64 v[114:115], s[44:45], 0, v[114:115]
	v_lshl_add_u64 v[148:149], v[114:115], 0, v[204:205]
	global_store_dwordx4 v[148:149], v[118:121], off
	v_lshl_add_u64 v[114:115], v[222:223], 0, v[150:151]
	global_load_dwordx4 v[138:141], v[114:115], off
	v_lshlrev_b32_e32 v118, 4, v170
	v_ashrrev_i32_e32 v119, 31, v118
	v_lshlrev_b64 v[168:169], 1, v[118:119]
	v_lshl_add_u64 v[118:119], v[220:221], 0, v[168:169]
	global_load_dwordx4 v[118:121], v[118:119], off
	v_lshlrev_b32_e32 v114, 4, v176
	v_ashrrev_i32_e32 v115, 31, v114
	v_lshlrev_b64 v[152:153], 1, v[114:115]
	v_lshl_add_u64 v[114:115], v[220:221], 0, v[152:153]
	global_load_dwordx4 v[142:145], v[114:115], off
	v_lshl_add_u64 v[114:115], v[222:223], 0, v[156:157]
	global_load_dwordx4 v[130:133], v[114:115], off
	v_lshlrev_b32_e32 v114, 4, v174
	v_ashrrev_i32_e32 v115, 31, v114
	v_lshlrev_b64 v[158:159], 1, v[114:115]
	v_lshl_add_u64 v[114:115], v[220:221], 0, v[158:159]
	global_load_dwordx4 v[134:137], v[114:115], off
	v_lshl_add_u64 v[114:115], v[222:223], 0, v[160:161]
	global_load_dwordx4 v[122:125], v[114:115], off
	v_lshlrev_b32_e32 v114, 4, v172
	v_ashrrev_i32_e32 v115, 31, v114
	v_lshlrev_b64 v[164:165], 1, v[114:115]
	v_lshl_add_u64 v[114:115], v[220:221], 0, v[164:165]
	global_load_dwordx4 v[126:129], v[114:115], off
	v_lshl_add_u64 v[114:115], v[222:223], 0, v[166:167]
	global_load_dwordx4 v[114:117], v[114:115], off
	s_waitcnt vmcnt(0)
	v_lshlrev_b32_e32 v186, 16, v138
	v_mul_f32_e32 v110, 0xbfb8aa3b, v186
	v_exp_f32_e32 v185, v110
	v_and_b32_e32 v138, 0xffff0000, v138
	v_pk_add_f32 v[184:185], v[184:185], 1.0 op_sel_hi:[1,0]
	s_nop 0
	v_mul_f32_e32 v184, v184, v185
	v_rcp_f32_e32 v184, v184
	v_lshlrev_b32_e32 v187, 16, v142
	v_mul_f32_e32 v110, v187, v186
	v_mul_f32_e32 v184, v110, v184
	v_mul_f32_e32 v110, 0xbfb8aa3b, v111
	v_mul_f32_e32 v111, 0xbfb8aa3b, v138
	v_exp_f32_e32 v110, v110
	v_exp_f32_e32 v111, v111
	v_and_b32_e32 v142, 0xffff0000, v142
	v_mul_f32_e32 v138, v142, v138
	v_pk_add_f32 v[110:111], v[110:111], 1.0 op_sel_hi:[1,0]
	s_nop 0
	v_mul_f32_e32 v110, v110, v111
	v_rcp_f32_e32 v110, v110
	v_lshlrev_b32_e32 v111, 16, v139
	v_and_b32_e32 v139, 0xffff0000, v139
	v_mul_f32_e32 v110, v138, v110
	v_cvt_pk_bf16_f32 v110, v184, v110
	v_exp_f32_e32 v184, v112
	v_mul_f32_e32 v112, 0xbfb8aa3b, v111
	v_exp_f32_e32 v185, v112
	v_lshlrev_b32_e32 v138, 16, v143
	v_mul_f32_e32 v111, v138, v111
	v_and_b32_e32 v138, 0xffff0000, v143
	v_pk_add_f32 v[184:185], v[184:185], 1.0 op_sel_hi:[1,0]
	v_mul_f32_e32 v138, v138, v139
	v_mul_f32_e32 v112, v184, v185
	v_rcp_f32_e32 v112, v112
	s_nop 0
	v_mul_f32_e32 v111, v111, v112
	v_mul_f32_e32 v112, 0xbfb8aa3b, v113
	v_mul_f32_e32 v113, 0xbfb8aa3b, v139
	v_exp_f32_e32 v112, v112
	v_exp_f32_e32 v113, v113
	v_lshlrev_b32_e32 v139, 16, v144
	v_pk_add_f32 v[112:113], v[112:113], 1.0 op_sel_hi:[1,0]
	s_nop 0
	v_mul_f32_e32 v112, v112, v113
	v_rcp_f32_e32 v112, v112
	s_nop 0
	v_mul_f32_e32 v112, v138, v112
	v_lshlrev_b32_e32 v138, 16, v140
	v_cvt_pk_bf16_f32 v111, v111, v112
	v_exp_f32_e32 v112, v106
	v_mul_f32_e32 v106, 0xbfb8aa3b, v138
	v_exp_f32_e32 v113, v106
	v_mul_f32_e32 v106, v139, v138
	v_and_b32_e32 v138, 0xffff0000, v140
	v_pk_add_f32 v[112:113], v[112:113], 1.0 op_sel_hi:[1,0]
	s_nop 0
	v_mul_f32_e32 v112, v112, v113
	v_rcp_f32_e32 v112, v112
	v_and_b32_e32 v113, 0xffff0000, v144
	v_mul_f32_e32 v113, v113, v138
	v_mul_f32_e32 v112, v106, v112
	v_mul_f32_e32 v106, 0xbfb8aa3b, v107
	v_mul_f32_e32 v107, 0xbfb8aa3b, v138
	v_exp_f32_e32 v106, v106
	v_exp_f32_e32 v107, v107
	v_lshlrev_b32_e32 v138, 16, v145
	v_pk_add_f32 v[106:107], v[106:107], 1.0 op_sel_hi:[1,0]
	s_nop 0
	v_mul_f32_e32 v106, v106, v107
	v_rcp_f32_e32 v106, v106
	s_nop 0
	v_mul_f32_e32 v106, v113, v106
	v_lshlrev_b32_e32 v113, 16, v141
	v_cvt_pk_bf16_f32 v112, v112, v106
	v_mul_f32_e32 v106, 0xbfb8aa3b, v108
	v_mul_f32_e32 v107, 0xbfb8aa3b, v113
	v_exp_f32_e32 v106, v106
	v_exp_f32_e32 v107, v107
	v_mul_f32_e32 v108, v138, v113
	v_and_b32_e32 v138, 0xffff0000, v141
	v_and_b32_e32 v113, 0xffff0000, v145
	v_pk_add_f32 v[106:107], v[106:107], 1.0 op_sel_hi:[1,0]
	s_nop 0
	v_mul_f32_e32 v106, v106, v107
	v_rcp_f32_e32 v106, v106
	v_mul_f32_e32 v107, 0xbfb8aa3b, v138
	v_exp_f32_e32 v107, v107
	v_mul_f32_e32 v108, v108, v106
	v_mul_f32_e32 v106, 0xbfb8aa3b, v109
	v_exp_f32_e32 v106, v106
	v_mul_f32_e32 v109, v113, v138
	v_pk_add_f32 v[106:107], v[106:107], 1.0 op_sel_hi:[1,0]
	s_nop 0
	v_mul_f32_e32 v106, v106, v107
	v_rcp_f32_e32 v106, v106
	s_nop 0
	v_mul_f32_e32 v106, v109, v106
; __device__ __forceinline__ unsigned cvt_pk_bf16(float lo, float hi) { unsigned r; asm volatile("v_cvt_pk_bf16_f32 %0, %1, %2" : "=v"(r) : "v"(lo), "v"(hi)); return r; }
; __device__ __forceinline__ float bf_lo(unsigned w) { return __uint_as_float(w << 16); }
; __device__ __forceinline__ float bf_hi(unsigned w) { return __uint_as_float(w & 0xffff0000u); }
;     __device__ __forceinline__ void operator()(const f32x4 (&acc)[2][2][4][2], const Unit& u, int wr, int wc, int fr, int fq, const Pre&) const {
;     ...
;                 for (int m = 0; m < 4; ++m) { const int r = row0 + ai * HALF + m * 16;
;                     const u32x4 zw = zv[m], gw = gv[m];
;                     const f32x4 a0 = acc[ai][bj][m][0] + bs[bj][0], a1 = acc[ai][bj][m][1] + bs[bj][1];
;                     u32x4 w;
;                     w.x = cvt_pk_bf16(glu_gate_f(bf_lo(gw.x), a0[0], bf_lo(zw.x)), glu_gate_f(bf_hi(gw.x), a0[1], bf_hi(zw.x)));
;                     w.y = cvt_pk_bf16(glu_gate_f(bf_lo(gw.y), a0[2], bf_lo(zw.y)), glu_gate_f(bf_hi(gw.y), a0[3], bf_hi(zw.y)));
;                     w.z = cvt_pk_bf16(glu_gate_f(bf_lo(gw.z), a1[0], bf_lo(zw.z)), glu_gate_f(bf_hi(gw.z), a1[1], bf_hi(zw.z)));
;                     w.w = cvt_pk_bf16(glu_gate_f(bf_lo(gw.w), a1[2], bf_lo(zw.w)), glu_gate_f(bf_hi(gw.w), a1[3], bf_hi(zw.w)));
;                     *(u32x4*)(O + (size_t)r * DE + c) = w; } } }
	v_cvt_pk_bf16_f32 v113, v108, v106
	v_lshlrev_b64 v[106:107], 13, v[176:177]
	v_lshl_add_u64 v[106:107], s[44:45], 0, v[106:107]
	v_lshl_add_u64 v[106:107], v[106:107], 0, v[204:205]
	global_store_dwordx4 v[106:107], v[110:113], off
	v_exp_f32_e32 v108, v94
	s_nop 0
	v_lshlrev_b32_e32 v110, 16, v130
	v_mul_f32_e32 v94, 0xbfb8aa3b, v110
	v_exp_f32_e32 v109, v94
	v_lshlrev_b32_e32 v111, 16, v134
	v_mul_f32_e32 v94, v111, v110
	v_and_b32_e32 v110, 0xffff0000, v130
	v_pk_add_f32 v[108:109], v[108:109], 1.0 op_sel_hi:[1,0]
	s_nop 0
	v_mul_f32_e32 v108, v108, v109
	v_rcp_f32_e32 v108, v108
	v_and_b32_e32 v109, 0xffff0000, v134
	v_mul_f32_e32 v109, v109, v110
	v_mul_f32_e32 v108, v94, v108
	v_mul_f32_e32 v94, 0xbfb8aa3b, v95
	v_mul_f32_e32 v95, 0xbfb8aa3b, v110
	v_exp_f32_e32 v94, v94
	v_exp_f32_e32 v95, v95
	v_lshlrev_b32_e32 v110, 16, v135
	v_pk_add_f32 v[94:95], v[94:95], 1.0 op_sel_hi:[1,0]
	s_nop 0
	v_mul_f32_e32 v94, v94, v95
	v_rcp_f32_e32 v94, v94
	v_lshlrev_b32_e32 v95, 16, v131
	v_mul_f32_e32 v94, v109, v94
	v_cvt_pk_bf16_f32 v94, v108, v94
	v_exp_f32_e32 v108, v96
	v_mul_f32_e32 v96, 0xbfb8aa3b, v95
	v_exp_f32_e32 v109, v96
	v_mul_f32_e32 v95, v110, v95
	v_pk_add_f32 v[108:109], v[108:109], 1.0 op_sel_hi:[1,0]
	s_nop 0
	v_mul_f32_e32 v96, v108, v109
	v_rcp_f32_e32 v96, v96
	v_and_b32_e32 v109, 0xffff0000, v131
	v_and_b32_e32 v108, 0xffff0000, v135
	v_mul_f32_e32 v108, v108, v109
	v_mul_f32_e32 v95, v95, v96
	v_mul_f32_e32 v96, 0xbfb8aa3b, v97
	v_mul_f32_e32 v97, 0xbfb8aa3b, v109
	v_exp_f32_e32 v96, v96
	v_exp_f32_e32 v97, v97
	v_lshlrev_b32_e32 v109, 16, v136
	v_pk_add_f32 v[96:97], v[96:97], 1.0 op_sel_hi:[1,0]
	s_nop 0
	v_mul_f32_e32 v96, v96, v97
	v_rcp_f32_e32 v96, v96
	s_nop 0
	v_mul_f32_e32 v96, v108, v96
	v_lshlrev_b32_e32 v108, 16, v132
	v_cvt_pk_bf16_f32 v95, v95, v96
	v_exp_f32_e32 v96, v90
	v_mul_f32_e32 v90, 0xbfb8aa3b, v108
	v_exp_f32_e32 v97, v90
	v_mul_f32_e32 v90, v109, v108
	v_and_b32_e32 v108, 0xffff0000, v132
	v_pk_add_f32 v[96:97], v[96:97], 1.0 op_sel_hi:[1,0]
	s_nop 0
	v_mul_f32_e32 v96, v96, v97
	v_rcp_f32_e32 v96, v96
	v_and_b32_e32 v97, 0xffff0000, v136
	v_mul_f32_e32 v97, v97, v108
	v_mul_f32_e32 v96, v90, v96
	v_mul_f32_e32 v90, 0xbfb8aa3b, v91
	v_mul_f32_e32 v91, 0xbfb8aa3b, v108
	v_exp_f32_e32 v90, v90
	v_exp_f32_e32 v91, v91
	v_lshlrev_b32_e32 v108, 16, v137
	v_pk_add_f32 v[90:91], v[90:91], 1.0 op_sel_hi:[1,0]
	s_nop 0
	v_mul_f32_e32 v90, v90, v91
	v_rcp_f32_e32 v90, v90
	s_nop 0
	v_mul_f32_e32 v90, v97, v90
	v_lshlrev_b32_e32 v97, 16, v133
	v_cvt_pk_bf16_f32 v96, v96, v90
	v_mul_f32_e32 v90, 0xbfb8aa3b, v92
	v_mul_f32_e32 v91, 0xbfb8aa3b, v97
	v_exp_f32_e32 v90, v90
	v_exp_f32_e32 v91, v91
	v_mul_f32_e32 v92, v108, v97
	v_and_b32_e32 v108, 0xffff0000, v133
	v_and_b32_e32 v97, 0xffff0000, v137
	v_pk_add_f32 v[90:91], v[90:91], 1.0 op_sel_hi:[1,0]
	s_nop 0
	v_mul_f32_e32 v90, v90, v91
	v_rcp_f32_e32 v90, v90
	v_mul_f32_e32 v91, 0xbfb8aa3b, v108
	v_exp_f32_e32 v91, v91
	v_mul_f32_e32 v92, v92, v90
	v_mul_f32_e32 v90, 0xbfb8aa3b, v93
	v_exp_f32_e32 v90, v90
	v_mul_f32_e32 v93, v97, v108
	v_pk_add_f32 v[90:91], v[90:91], 1.0 op_sel_hi:[1,0]
	s_nop 0
	v_mul_f32_e32 v90, v90, v91
	v_rcp_f32_e32 v90, v90
	s_nop 0
	v_mul_f32_e32 v90, v93, v90
	v_cvt_pk_bf16_f32 v97, v92, v90
	v_lshlrev_b64 v[90:91], 13, v[174:175]
	v_lshl_add_u64 v[90:91], s[44:45], 0, v[90:91]
	v_lshlrev_b32_e32 v92, 16, v122
	v_lshl_add_u64 v[108:109], v[90:91], 0, v[204:205]
	v_exp_f32_e32 v90, v86
	v_mul_f32_e32 v86, 0xbfb8aa3b, v92
	v_exp_f32_e32 v91, v86
	v_lshlrev_b32_e32 v93, 16, v126
	v_mul_f32_e32 v86, v93, v92
	v_and_b32_e32 v92, 0xffff0000, v122
	v_pk_add_f32 v[90:91], v[90:91], 1.0 op_sel_hi:[1,0]
	global_store_dwordx4 v[108:109], v[94:97], off
	v_mul_f32_e32 v90, v90, v91
	v_rcp_f32_e32 v90, v90
	v_and_b32_e32 v91, 0xffff0000, v126
	v_mul_f32_e32 v91, v91, v92
	v_mul_f32_e32 v90, v86, v90
	v_mul_f32_e32 v86, 0xbfb8aa3b, v87
	v_mul_f32_e32 v87, 0xbfb8aa3b, v92
	v_exp_f32_e32 v86, v86
	v_exp_f32_e32 v87, v87
	v_lshlrev_b32_e32 v92, 16, v127
	v_pk_add_f32 v[86:87], v[86:87], 1.0 op_sel_hi:[1,0]
	s_nop 0
	v_mul_f32_e32 v86, v86, v87
	v_rcp_f32_e32 v86, v86
	v_lshlrev_b32_e32 v87, 16, v123
	v_mul_f32_e32 v86, v91, v86
	v_cvt_pk_bf16_f32 v86, v90, v86
	v_exp_f32_e32 v90, v88
	v_mul_f32_e32 v88, 0xbfb8aa3b, v87
	v_exp_f32_e32 v91, v88
	v_mul_f32_e32 v87, v92, v87
	v_pk_add_f32 v[90:91], v[90:91], 1.0 op_sel_hi:[1,0]
	s_nop 0
	v_mul_f32_e32 v88, v90, v91
	v_rcp_f32_e32 v88, v88
	v_and_b32_e32 v91, 0xffff0000, v123
	v_and_b32_e32 v90, 0xffff0000, v127
	v_mul_f32_e32 v90, v90, v91
	v_mul_f32_e32 v87, v87, v88
	v_mul_f32_e32 v88, 0xbfb8aa3b, v89
	v_mul_f32_e32 v89, 0xbfb8aa3b, v91
	v_exp_f32_e32 v88, v88
	v_exp_f32_e32 v89, v89
	v_lshlrev_b32_e32 v91, 16, v128
	v_pk_add_f32 v[88:89], v[88:89], 1.0 op_sel_hi:[1,0]
	s_nop 0
	v_mul_f32_e32 v88, v88, v89
	v_rcp_f32_e32 v88, v88
	s_nop 0
	v_mul_f32_e32 v88, v90, v88
	v_lshlrev_b32_e32 v90, 16, v124
	v_cvt_pk_bf16_f32 v87, v87, v88
	v_exp_f32_e32 v88, v82
	v_mul_f32_e32 v82, 0xbfb8aa3b, v90
	v_exp_f32_e32 v89, v82
	v_mul_f32_e32 v82, v91, v90
	v_and_b32_e32 v90, 0xffff0000, v124
	v_pk_add_f32 v[88:89], v[88:89], 1.0 op_sel_hi:[1,0]
	s_nop 0
	v_mul_f32_e32 v88, v88, v89
	v_rcp_f32_e32 v88, v88
	v_and_b32_e32 v89, 0xffff0000, v128
	v_mul_f32_e32 v89, v89, v90
	v_mul_f32_e32 v88, v82, v88
	v_mul_f32_e32 v82, 0xbfb8aa3b, v83
	v_mul_f32_e32 v83, 0xbfb8aa3b, v90
	v_exp_f32_e32 v82, v82
	v_exp_f32_e32 v83, v83
	v_lshlrev_b32_e32 v90, 16, v129
	v_pk_add_f32 v[82:83], v[82:83], 1.0 op_sel_hi:[1,0]
	s_nop 0
	v_mul_f32_e32 v82, v82, v83
	v_rcp_f32_e32 v82, v82
	s_nop 0
	v_mul_f32_e32 v82, v89, v82
; __device__ __forceinline__ unsigned cvt_pk_bf16(float lo, float hi) { unsigned r; asm volatile("v_cvt_pk_bf16_f32 %0, %1, %2" : "=v"(r) : "v"(lo), "v"(hi)); return r; }
; __device__ __forceinline__ float bf_lo(unsigned w) { return __uint_as_float(w << 16); }
; __device__ __forceinline__ float bf_hi(unsigned w) { return __uint_as_float(w & 0xffff0000u); }
;     __device__ __forceinline__ void operator()(const f32x4 (&acc)[2][2][4][2], const Unit& u, int wr, int wc, int fr, int fq, const Pre&) const {
;     ...
;         for (int bj = 0; bj < 2; ++bj) { const int c = col0 + bj * HALF;
; #pragma unroll
;             for (int ai = 0; ai < 2; ++ai) { u32x4 zv[4], gv[4];
; #pragma unroll
;                 for (int m = 0; m < 4; ++m) { const int r = row0 + ai * HALF + m * 16; zv[m] = *(const u32x4*)(Z + (size_t)r * DE2 + c); gv[m] = *(const u32x4*)(Gm + (size_t)(c >> 4) * GSTR + r * 16 + (c & 15)); }
; #pragma unroll
;                 for (int m = 0; m < 4; ++m) { const int r = row0 + ai * HALF + m * 16;
;                     const u32x4 zw = zv[m], gw = gv[m];
;                     const f32x4 a0 = acc[ai][bj][m][0] + bs[bj][0], a1 = acc[ai][bj][m][1] + bs[bj][1];
;                     u32x4 w;
;                     w.x = cvt_pk_bf16(glu_gate_f(bf_lo(gw.x), a0[0], bf_lo(zw.x)), glu_gate_f(bf_hi(gw.x), a0[1], bf_hi(zw.x)));
;                     w.y = cvt_pk_bf16(glu_gate_f(bf_lo(gw.y), a0[2], bf_lo(zw.y)), glu_gate_f(bf_hi(gw.y), a0[3], bf_hi(zw.y)));
;                     w.z = cvt_pk_bf16(glu_gate_f(bf_lo(gw.z), a1[0], bf_lo(zw.z)), glu_gate_f(bf_hi(gw.z), a1[1], bf_hi(zw.z)));
;                     w.w = cvt_pk_bf16(glu_gate_f(bf_lo(gw.w), a1[2], bf_lo(zw.w)), glu_gate_f(bf_hi(gw.w), a1[3], bf_hi(zw.w)));
;                     *(u32x4*)(O + (size_t)r * DE + c) = w; } } }
	v_lshlrev_b32_e32 v89, 16, v125
	v_cvt_pk_bf16_f32 v88, v88, v82
	v_mul_f32_e32 v82, 0xbfb8aa3b, v84
	v_mul_f32_e32 v83, 0xbfb8aa3b, v89
	v_exp_f32_e32 v82, v82
	v_exp_f32_e32 v83, v83
	v_mul_f32_e32 v84, v90, v89
	v_and_b32_e32 v90, 0xffff0000, v125
	v_and_b32_e32 v89, 0xffff0000, v129
	v_pk_add_f32 v[82:83], v[82:83], 1.0 op_sel_hi:[1,0]
	s_nop 0
	v_mul_f32_e32 v82, v82, v83
	v_rcp_f32_e32 v82, v82
	v_mul_f32_e32 v83, 0xbfb8aa3b, v90
	v_exp_f32_e32 v83, v83
	v_mul_f32_e32 v84, v84, v82
	v_mul_f32_e32 v82, 0xbfb8aa3b, v85
	v_exp_f32_e32 v82, v82
	v_mul_f32_e32 v85, v89, v90
	v_pk_add_f32 v[82:83], v[82:83], 1.0 op_sel_hi:[1,0]
	s_nop 0
	v_mul_f32_e32 v82, v82, v83
	v_rcp_f32_e32 v82, v82
	s_nop 0
	v_mul_f32_e32 v82, v85, v82
	v_cvt_pk_bf16_f32 v89, v84, v82
	v_lshlrev_b64 v[82:83], 13, v[172:173]
	v_lshl_add_u64 v[82:83], s[44:45], 0, v[82:83]
	v_lshlrev_b32_e32 v84, 16, v114
	v_lshl_add_u64 v[110:111], v[82:83], 0, v[204:205]
	v_exp_f32_e32 v82, v78
	v_mul_f32_e32 v78, 0xbfb8aa3b, v84
	v_exp_f32_e32 v83, v78
	v_lshlrev_b32_e32 v85, 16, v118
	v_mul_f32_e32 v78, v85, v84
	v_and_b32_e32 v84, 0xffff0000, v114
	v_pk_add_f32 v[82:83], v[82:83], 1.0 op_sel_hi:[1,0]
	global_store_dwordx4 v[110:111], v[86:89], off
	v_mul_f32_e32 v82, v82, v83
	v_rcp_f32_e32 v82, v82
	v_and_b32_e32 v83, 0xffff0000, v118
	v_mul_f32_e32 v83, v83, v84
	v_exp_f32_e32 v118, v70
	v_mul_f32_e32 v82, v78, v82
	v_mul_f32_e32 v78, 0xbfb8aa3b, v79
	v_mul_f32_e32 v79, 0xbfb8aa3b, v84
	v_exp_f32_e32 v78, v78
	v_exp_f32_e32 v79, v79
	v_lshlrev_b32_e32 v84, 16, v119
	v_pk_add_f32 v[78:79], v[78:79], 1.0 op_sel_hi:[1,0]
	s_nop 0
	v_mul_f32_e32 v78, v78, v79
	v_rcp_f32_e32 v78, v78
	v_lshlrev_b32_e32 v79, 16, v115
	v_mul_f32_e32 v78, v83, v78
	v_cvt_pk_bf16_f32 v78, v82, v78
	v_exp_f32_e32 v82, v80
	v_mul_f32_e32 v80, 0xbfb8aa3b, v79
	v_exp_f32_e32 v83, v80
	v_mul_f32_e32 v79, v84, v79
	v_pk_add_f32 v[82:83], v[82:83], 1.0 op_sel_hi:[1,0]
	s_nop 0
	v_mul_f32_e32 v80, v82, v83
	v_rcp_f32_e32 v80, v80
	v_and_b32_e32 v83, 0xffff0000, v115
	v_and_b32_e32 v82, 0xffff0000, v119
	v_mul_f32_e32 v82, v82, v83
	v_mul_f32_e32 v79, v79, v80
	v_mul_f32_e32 v80, 0xbfb8aa3b, v81
	v_mul_f32_e32 v81, 0xbfb8aa3b, v83
	v_exp_f32_e32 v80, v80
	v_exp_f32_e32 v81, v81
	v_lshlrev_b32_e32 v83, 16, v120
	v_pk_add_f32 v[80:81], v[80:81], 1.0 op_sel_hi:[1,0]
	s_nop 0
	v_mul_f32_e32 v80, v80, v81
	v_rcp_f32_e32 v80, v80
	s_nop 0
	v_mul_f32_e32 v80, v82, v80
	v_lshlrev_b32_e32 v82, 16, v116
	v_cvt_pk_bf16_f32 v79, v79, v80
	v_exp_f32_e32 v80, v74
	v_mul_f32_e32 v74, 0xbfb8aa3b, v82
	v_exp_f32_e32 v81, v74
	v_mul_f32_e32 v74, v83, v82
	v_and_b32_e32 v82, 0xffff0000, v116
	v_pk_add_f32 v[80:81], v[80:81], 1.0 op_sel_hi:[1,0]
	s_nop 0
	v_mul_f32_e32 v80, v80, v81
	v_rcp_f32_e32 v80, v80
	v_and_b32_e32 v81, 0xffff0000, v120
	v_mul_f32_e32 v81, v81, v82
	v_mul_f32_e32 v80, v74, v80
	v_mul_f32_e32 v74, 0xbfb8aa3b, v75
	v_mul_f32_e32 v75, 0xbfb8aa3b, v82
	v_exp_f32_e32 v74, v74
	v_exp_f32_e32 v75, v75
	v_lshlrev_b32_e32 v82, 16, v121
	v_pk_add_f32 v[74:75], v[74:75], 1.0 op_sel_hi:[1,0]
	s_nop 0
	v_mul_f32_e32 v74, v74, v75
	v_rcp_f32_e32 v74, v74
	s_nop 0
	v_mul_f32_e32 v74, v81, v74
	v_lshlrev_b32_e32 v81, 16, v117
	v_cvt_pk_bf16_f32 v80, v80, v74
	v_mul_f32_e32 v74, 0xbfb8aa3b, v76
	v_mul_f32_e32 v75, 0xbfb8aa3b, v81
	v_exp_f32_e32 v74, v74
	v_exp_f32_e32 v75, v75
	v_mul_f32_e32 v76, v82, v81
	v_and_b32_e32 v82, 0xffff0000, v117
	v_and_b32_e32 v81, 0xffff0000, v121
	v_pk_add_f32 v[74:75], v[74:75], 1.0 op_sel_hi:[1,0]
	s_nop 0
	v_mul_f32_e32 v74, v74, v75
	v_rcp_f32_e32 v74, v74
	v_mul_f32_e32 v75, 0xbfb8aa3b, v82
	v_exp_f32_e32 v75, v75
	v_mul_f32_e32 v76, v76, v74
	v_mul_f32_e32 v74, 0xbfb8aa3b, v77
	v_exp_f32_e32 v74, v74
	v_mul_f32_e32 v77, v81, v82
	v_pk_add_f32 v[74:75], v[74:75], 1.0 op_sel_hi:[1,0]
	s_nop 0
	v_mul_f32_e32 v74, v74, v75
	v_rcp_f32_e32 v74, v74
	s_nop 0
	v_mul_f32_e32 v74, v77, v74
	v_cvt_pk_bf16_f32 v81, v76, v74
	v_lshlrev_b64 v[74:75], 13, v[170:171]
	v_lshl_add_u64 v[74:75], s[44:45], 0, v[74:75]
	v_lshl_add_u64 v[112:113], v[74:75], 0, v[204:205]
	v_or_b32_e32 v74, 0x80, v200
	v_ashrrev_i32_e32 v75, 31, v74
	v_ashrrev_i32_e32 v76, 4, v74
	v_mad_i64_i32 v[114:115], s[4:5], v76, s94, v[194:195]
	v_lshl_add_u64 v[76:77], s[46:47], 0, v[202:203]
	v_lshlrev_b64 v[116:117], 1, v[74:75]
	v_lshl_add_u64 v[74:75], v[76:77], 0, v[116:117]
	global_load_dwordx4 v[98:101], v[74:75], off
	s_nop 0
	global_store_dwordx4 v[112:113], v[78:81], off
	s_nop 1
	v_lshl_add_u64 v[78:79], v[114:115], 0, v[218:219]
	global_load_dwordx4 v[78:81], v[78:79], off
	v_lshl_add_u64 v[74:75], v[114:115], 0, v[206:207]
	global_load_dwordx4 v[102:105], v[74:75], off
	v_lshl_add_u64 v[74:75], s[46:47], 0, v[210:211]
	v_lshl_add_u64 v[74:75], v[74:75], 0, v[116:117]
	global_load_dwordx4 v[90:93], v[74:75], off
	v_lshl_add_u64 v[74:75], v[114:115], 0, v[208:209]
	global_load_dwordx4 v[94:97], v[74:75], off
	v_lshl_add_u64 v[74:75], s[46:47], 0, v[214:215]
	v_lshl_add_u64 v[74:75], v[74:75], 0, v[116:117]
	global_load_dwordx4 v[82:85], v[74:75], off
	v_lshl_add_u64 v[74:75], v[114:115], 0, v[212:213]
	global_load_dwordx4 v[86:89], v[74:75], off
	v_lshl_add_u64 v[74:75], s[46:47], 0, v[216:217]
	v_lshl_add_u64 v[74:75], v[74:75], 0, v[116:117]
	global_load_dwordx4 v[74:77], v[74:75], off
	s_waitcnt vmcnt(0)
; __device__ __forceinline__ unsigned cvt_pk_bf16(float lo, float hi) { unsigned r; asm volatile("v_cvt_pk_bf16_f32 %0, %1, %2" : "=v"(r) : "v"(lo), "v"(hi)); return r; }
; __device__ __forceinline__ float bf_lo(unsigned w) { return __uint_as_float(w << 16); }
; __device__ __forceinline__ float bf_hi(unsigned w) { return __uint_as_float(w & 0xffff0000u); }
;     __device__ __forceinline__ void operator()(const f32x4 (&acc)[2][2][4][2], const Unit& u, int wr, int wc, int fr, int fq, const Pre&) const {
;     ...
;                 for (int m = 0; m < 4; ++m) { const int r = row0 + ai * HALF + m * 16;
;                     const u32x4 zw = zv[m], gw = gv[m];
;                     const f32x4 a0 = acc[ai][bj][m][0] + bs[bj][0], a1 = acc[ai][bj][m][1] + bs[bj][1];
;                     u32x4 w;
;                     w.x = cvt_pk_bf16(glu_gate_f(bf_lo(gw.x), a0[0], bf_lo(zw.x)), glu_gate_f(bf_hi(gw.x), a0[1], bf_hi(zw.x)));
;                     w.y = cvt_pk_bf16(glu_gate_f(bf_lo(gw.y), a0[2], bf_lo(zw.y)), glu_gate_f(bf_hi(gw.y), a0[3], bf_hi(zw.y)));
;                     w.z = cvt_pk_bf16(glu_gate_f(bf_lo(gw.z), a1[0], bf_lo(zw.z)), glu_gate_f(bf_hi(gw.z), a1[1], bf_hi(zw.z)));
;                     w.w = cvt_pk_bf16(glu_gate_f(bf_lo(gw.w), a1[2], bf_lo(zw.w)), glu_gate_f(bf_hi(gw.w), a1[3], bf_hi(zw.w)));
;                     *(u32x4*)(O + (size_t)r * DE + c) = w; } } }
	v_lshlrev_b32_e32 v120, 16, v98
	v_mul_f32_e32 v70, 0xbfb8aa3b, v120
	v_exp_f32_e32 v119, v70
	v_and_b32_e32 v98, 0xffff0000, v98
	v_pk_add_f32 v[118:119], v[118:119], 1.0 op_sel_hi:[1,0]
	s_nop 0
	v_mul_f32_e32 v118, v118, v119
	v_rcp_f32_e32 v118, v118
	v_lshlrev_b32_e32 v121, 16, v102
	v_mul_f32_e32 v70, v121, v120
	v_and_b32_e32 v102, 0xffff0000, v102
	v_mul_f32_e32 v118, v70, v118
	v_mul_f32_e32 v70, 0xbfb8aa3b, v71
	v_mul_f32_e32 v71, 0xbfb8aa3b, v98
	v_exp_f32_e32 v70, v70
	v_exp_f32_e32 v71, v71
	v_mul_f32_e32 v98, v102, v98
	v_pk_add_f32 v[70:71], v[70:71], 1.0 op_sel_hi:[1,0]
	s_nop 0
	v_mul_f32_e32 v70, v70, v71
	v_rcp_f32_e32 v70, v70
	v_lshlrev_b32_e32 v71, 16, v99
	v_and_b32_e32 v99, 0xffff0000, v99
	v_mul_f32_e32 v70, v98, v70
	v_cvt_pk_bf16_f32 v70, v118, v70
	v_exp_f32_e32 v118, v72
	v_mul_f32_e32 v72, 0xbfb8aa3b, v71
	v_exp_f32_e32 v119, v72
	v_lshlrev_b32_e32 v98, 16, v103
	v_mul_f32_e32 v71, v98, v71
	v_and_b32_e32 v98, 0xffff0000, v103
	v_pk_add_f32 v[118:119], v[118:119], 1.0 op_sel_hi:[1,0]
	v_mul_f32_e32 v98, v98, v99
	v_mul_f32_e32 v72, v118, v119
	v_rcp_f32_e32 v72, v72
	s_nop 0
	v_mul_f32_e32 v71, v71, v72
	v_mul_f32_e32 v72, 0xbfb8aa3b, v73
	v_mul_f32_e32 v73, 0xbfb8aa3b, v99
	v_exp_f32_e32 v72, v72
	v_exp_f32_e32 v73, v73
	v_lshlrev_b32_e32 v99, 16, v104
	v_pk_add_f32 v[72:73], v[72:73], 1.0 op_sel_hi:[1,0]
	s_nop 0
	v_mul_f32_e32 v72, v72, v73
	v_rcp_f32_e32 v72, v72
	s_nop 0
	v_mul_f32_e32 v72, v98, v72
	v_lshlrev_b32_e32 v98, 16, v100
	v_cvt_pk_bf16_f32 v71, v71, v72
	v_exp_f32_e32 v72, v66
	v_mul_f32_e32 v66, 0xbfb8aa3b, v98
	v_exp_f32_e32 v73, v66
	v_mul_f32_e32 v66, v99, v98
	v_and_b32_e32 v98, 0xffff0000, v100
	v_pk_add_f32 v[72:73], v[72:73], 1.0 op_sel_hi:[1,0]
	s_nop 0
	v_mul_f32_e32 v72, v72, v73
	v_rcp_f32_e32 v72, v72
	v_and_b32_e32 v73, 0xffff0000, v104
	v_mul_f32_e32 v73, v73, v98
	v_mul_f32_e32 v72, v66, v72
	v_mul_f32_e32 v66, 0xbfb8aa3b, v67
	v_mul_f32_e32 v67, 0xbfb8aa3b, v98
	v_exp_f32_e32 v66, v66
	v_exp_f32_e32 v67, v67
	v_lshlrev_b32_e32 v98, 16, v105
	v_pk_add_f32 v[66:67], v[66:67], 1.0 op_sel_hi:[1,0]
	s_nop 0
	v_mul_f32_e32 v66, v66, v67
	v_rcp_f32_e32 v66, v66
	s_nop 0
	v_mul_f32_e32 v66, v73, v66
	v_lshlrev_b32_e32 v73, 16, v101
	v_cvt_pk_bf16_f32 v72, v72, v66
	v_mul_f32_e32 v66, 0xbfb8aa3b, v68
	v_mul_f32_e32 v67, 0xbfb8aa3b, v73
	v_exp_f32_e32 v66, v66
	v_exp_f32_e32 v67, v67
	v_mul_f32_e32 v68, v98, v73
	v_and_b32_e32 v98, 0xffff0000, v101
	v_and_b32_e32 v73, 0xffff0000, v105
	v_pk_add_f32 v[66:67], v[66:67], 1.0 op_sel_hi:[1,0]
	s_nop 0
	v_mul_f32_e32 v66, v66, v67
	v_rcp_f32_e32 v66, v66
	v_mul_f32_e32 v67, 0xbfb8aa3b, v98
	v_exp_f32_e32 v67, v67
	v_mul_f32_e32 v68, v68, v66
	v_mul_f32_e32 v66, 0xbfb8aa3b, v69
	v_exp_f32_e32 v66, v66
	v_mul_f32_e32 v69, v73, v98
	v_pk_add_f32 v[66:67], v[66:67], 1.0 op_sel_hi:[1,0]
	s_nop 0
	v_mul_f32_e32 v66, v66, v67
	v_rcp_f32_e32 v66, v66
	s_nop 0
	v_mul_f32_e32 v66, v69, v66
	v_cvt_pk_bf16_f32 v73, v68, v66
	v_lshlrev_b32_e32 v68, 16, v90
	v_exp_f32_e32 v66, v62
	v_mul_f32_e32 v62, 0xbfb8aa3b, v68
	v_exp_f32_e32 v67, v62
	v_lshlrev_b32_e32 v69, 16, v94
	v_mul_f32_e32 v62, v69, v68
	v_and_b32_e32 v68, 0xffff0000, v90
	v_pk_add_f32 v[66:67], v[66:67], 1.0 op_sel_hi:[1,0]
	global_store_dwordx4 v[162:163], v[70:73], off offset:256
	v_mul_f32_e32 v66, v66, v67
	v_rcp_f32_e32 v66, v66
	v_and_b32_e32 v67, 0xffff0000, v94
	v_mul_f32_e32 v67, v67, v68
	v_mul_f32_e32 v66, v62, v66
	v_mul_f32_e32 v62, 0xbfb8aa3b, v63
	v_mul_f32_e32 v63, 0xbfb8aa3b, v68
	v_exp_f32_e32 v62, v62
	v_exp_f32_e32 v63, v63
	v_lshlrev_b32_e32 v68, 16, v95
	v_pk_add_f32 v[62:63], v[62:63], 1.0 op_sel_hi:[1,0]
	s_nop 0
	v_mul_f32_e32 v62, v62, v63
	v_rcp_f32_e32 v62, v62
	v_lshlrev_b32_e32 v63, 16, v91
	v_mul_f32_e32 v62, v67, v62
	v_cvt_pk_bf16_f32 v62, v66, v62
	v_exp_f32_e32 v66, v64
	v_mul_f32_e32 v64, 0xbfb8aa3b, v63
	v_exp_f32_e32 v67, v64
	v_mul_f32_e32 v63, v68, v63
	v_pk_add_f32 v[66:67], v[66:67], 1.0 op_sel_hi:[1,0]
	s_nop 0
	v_mul_f32_e32 v64, v66, v67
	v_rcp_f32_e32 v64, v64
	v_and_b32_e32 v67, 0xffff0000, v91
	v_and_b32_e32 v66, 0xffff0000, v95
	v_mul_f32_e32 v66, v66, v67
	v_mul_f32_e32 v63, v63, v64
	v_mul_f32_e32 v64, 0xbfb8aa3b, v65
	v_mul_f32_e32 v65, 0xbfb8aa3b, v67
	v_exp_f32_e32 v64, v64
	v_exp_f32_e32 v65, v65
	v_lshlrev_b32_e32 v67, 16, v96
	v_pk_add_f32 v[64:65], v[64:65], 1.0 op_sel_hi:[1,0]
	s_nop 0
	v_mul_f32_e32 v64, v64, v65
	v_rcp_f32_e32 v64, v64
	s_nop 0
	v_mul_f32_e32 v64, v66, v64
	v_lshlrev_b32_e32 v66, 16, v92
	v_cvt_pk_bf16_f32 v63, v63, v64
	v_exp_f32_e32 v64, v58
	v_mul_f32_e32 v58, 0xbfb8aa3b, v66
	v_exp_f32_e32 v65, v58
	v_mul_f32_e32 v58, v67, v66
	v_and_b32_e32 v66, 0xffff0000, v92
	v_pk_add_f32 v[64:65], v[64:65], 1.0 op_sel_hi:[1,0]
	s_nop 0
	v_mul_f32_e32 v64, v64, v65
	v_rcp_f32_e32 v64, v64
	v_and_b32_e32 v65, 0xffff0000, v96
	v_mul_f32_e32 v65, v65, v66
	v_mul_f32_e32 v64, v58, v64
	v_mul_f32_e32 v58, 0xbfb8aa3b, v59
	v_mul_f32_e32 v59, 0xbfb8aa3b, v66
	v_exp_f32_e32 v58, v58
	v_exp_f32_e32 v59, v59
	v_lshlrev_b32_e32 v66, 16, v97
	v_pk_add_f32 v[58:59], v[58:59], 1.0 op_sel_hi:[1,0]
	s_nop 0
	v_mul_f32_e32 v58, v58, v59
	v_rcp_f32_e32 v58, v58
	s_nop 0
	v_mul_f32_e32 v58, v65, v58
	v_lshlrev_b32_e32 v65, 16, v93
	v_cvt_pk_bf16_f32 v64, v64, v58
	v_mul_f32_e32 v58, 0xbfb8aa3b, v60
	v_mul_f32_e32 v59, 0xbfb8aa3b, v65
	v_exp_f32_e32 v58, v58
	v_exp_f32_e32 v59, v59
	v_mul_f32_e32 v60, v66, v65
	v_and_b32_e32 v66, 0xffff0000, v93
	v_and_b32_e32 v65, 0xffff0000, v97
	v_pk_add_f32 v[58:59], v[58:59], 1.0 op_sel_hi:[1,0]
	s_nop 0
	v_mul_f32_e32 v58, v58, v59
	v_rcp_f32_e32 v58, v58
	v_mul_f32_e32 v59, 0xbfb8aa3b, v66
; __device__ __forceinline__ unsigned cvt_pk_bf16(float lo, float hi) { unsigned r; asm volatile("v_cvt_pk_bf16_f32 %0, %1, %2" : "=v"(r) : "v"(lo), "v"(hi)); return r; }
; __device__ __forceinline__ float bf_lo(unsigned w) { return __uint_as_float(w << 16); }
; __device__ __forceinline__ float bf_hi(unsigned w) { return __uint_as_float(w & 0xffff0000u); }
;     __device__ __forceinline__ void operator()(const f32x4 (&acc)[2][2][4][2], const Unit& u, int wr, int wc, int fr, int fq, const Pre&) const {
;     ...
;                 for (int m = 0; m < 4; ++m) { const int r = row0 + ai * HALF + m * 16;
;                     const u32x4 zw = zv[m], gw = gv[m];
;                     const f32x4 a0 = acc[ai][bj][m][0] + bs[bj][0], a1 = acc[ai][bj][m][1] + bs[bj][1];
;                     u32x4 w;
;                     w.x = cvt_pk_bf16(glu_gate_f(bf_lo(gw.x), a0[0], bf_lo(zw.x)), glu_gate_f(bf_hi(gw.x), a0[1], bf_hi(zw.x)));
;                     w.y = cvt_pk_bf16(glu_gate_f(bf_lo(gw.y), a0[2], bf_lo(zw.y)), glu_gate_f(bf_hi(gw.y), a0[3], bf_hi(zw.y)));
;                     w.z = cvt_pk_bf16(glu_gate_f(bf_lo(gw.z), a1[0], bf_lo(zw.z)), glu_gate_f(bf_hi(gw.z), a1[1], bf_hi(zw.z)));
;                     w.w = cvt_pk_bf16(glu_gate_f(bf_lo(gw.w), a1[2], bf_lo(zw.w)), glu_gate_f(bf_hi(gw.w), a1[3], bf_hi(zw.w)));
;                     *(u32x4*)(O + (size_t)r * DE + c) = w; } } }
	v_exp_f32_e32 v59, v59
	v_mul_f32_e32 v60, v60, v58
	v_mul_f32_e32 v58, 0xbfb8aa3b, v61
	v_exp_f32_e32 v58, v58
	v_mul_f32_e32 v61, v65, v66
	v_pk_add_f32 v[58:59], v[58:59], 1.0 op_sel_hi:[1,0]
	s_nop 0
	v_mul_f32_e32 v58, v58, v59
	v_rcp_f32_e32 v58, v58
	s_nop 0
	v_mul_f32_e32 v58, v61, v58
	v_cvt_pk_bf16_f32 v65, v60, v58
	v_lshlrev_b32_e32 v60, 16, v82
	v_exp_f32_e32 v58, v54
	v_mul_f32_e32 v54, 0xbfb8aa3b, v60
	v_exp_f32_e32 v59, v54
	v_lshlrev_b32_e32 v61, 16, v86
	v_mul_f32_e32 v54, v61, v60
	v_and_b32_e32 v60, 0xffff0000, v82
	v_pk_add_f32 v[58:59], v[58:59], 1.0 op_sel_hi:[1,0]
	global_store_dwordx4 v[154:155], v[62:65], off offset:256
	v_mul_f32_e32 v58, v58, v59
	v_rcp_f32_e32 v58, v58
	v_and_b32_e32 v59, 0xffff0000, v86
	v_mul_f32_e32 v59, v59, v60
	v_mul_f32_e32 v58, v54, v58
	v_mul_f32_e32 v54, 0xbfb8aa3b, v55
	v_mul_f32_e32 v55, 0xbfb8aa3b, v60
	v_exp_f32_e32 v54, v54
	v_exp_f32_e32 v55, v55
	v_lshlrev_b32_e32 v60, 16, v87
	v_pk_add_f32 v[54:55], v[54:55], 1.0 op_sel_hi:[1,0]
	s_nop 0
	v_mul_f32_e32 v54, v54, v55
	v_rcp_f32_e32 v54, v54
	v_lshlrev_b32_e32 v55, 16, v83
	v_mul_f32_e32 v54, v59, v54
	v_cvt_pk_bf16_f32 v54, v58, v54
	v_exp_f32_e32 v58, v56
	v_mul_f32_e32 v56, 0xbfb8aa3b, v55
	v_exp_f32_e32 v59, v56
	v_mul_f32_e32 v55, v60, v55
	v_pk_add_f32 v[58:59], v[58:59], 1.0 op_sel_hi:[1,0]
	s_nop 0
	v_mul_f32_e32 v56, v58, v59
	v_rcp_f32_e32 v56, v56
	v_and_b32_e32 v59, 0xffff0000, v83
	v_and_b32_e32 v58, 0xffff0000, v87
	v_mul_f32_e32 v58, v58, v59
	v_mul_f32_e32 v55, v55, v56
	v_mul_f32_e32 v56, 0xbfb8aa3b, v57
	v_mul_f32_e32 v57, 0xbfb8aa3b, v59
	v_exp_f32_e32 v56, v56
	v_exp_f32_e32 v57, v57
	v_lshlrev_b32_e32 v59, 16, v88
	v_pk_add_f32 v[56:57], v[56:57], 1.0 op_sel_hi:[1,0]
	s_nop 0
	v_mul_f32_e32 v56, v56, v57
	v_rcp_f32_e32 v56, v56
	s_nop 0
	v_mul_f32_e32 v56, v58, v56
	v_lshlrev_b32_e32 v58, 16, v84
	v_cvt_pk_bf16_f32 v55, v55, v56
	v_exp_f32_e32 v56, v50
	v_mul_f32_e32 v50, 0xbfb8aa3b, v58
	v_exp_f32_e32 v57, v50
	v_mul_f32_e32 v50, v59, v58
	v_and_b32_e32 v58, 0xffff0000, v84
	v_pk_add_f32 v[56:57], v[56:57], 1.0 op_sel_hi:[1,0]
	s_nop 0
	v_mul_f32_e32 v56, v56, v57
	v_rcp_f32_e32 v56, v56
	v_and_b32_e32 v57, 0xffff0000, v88
	v_mul_f32_e32 v57, v57, v58
	v_mul_f32_e32 v56, v50, v56
	v_mul_f32_e32 v50, 0xbfb8aa3b, v51
	v_mul_f32_e32 v51, 0xbfb8aa3b, v58
	v_exp_f32_e32 v50, v50
	v_exp_f32_e32 v51, v51
	v_lshlrev_b32_e32 v58, 16, v89
	v_pk_add_f32 v[50:51], v[50:51], 1.0 op_sel_hi:[1,0]
	s_nop 0
	v_mul_f32_e32 v50, v50, v51
	v_rcp_f32_e32 v50, v50
	s_nop 0
	v_mul_f32_e32 v50, v57, v50
	v_lshlrev_b32_e32 v57, 16, v85
	v_cvt_pk_bf16_f32 v56, v56, v50
	v_mul_f32_e32 v50, 0xbfb8aa3b, v52
	v_mul_f32_e32 v51, 0xbfb8aa3b, v57
	v_exp_f32_e32 v50, v50
	v_exp_f32_e32 v51, v51
	v_mul_f32_e32 v52, v58, v57
	v_and_b32_e32 v58, 0xffff0000, v85
	v_and_b32_e32 v57, 0xffff0000, v89
	v_pk_add_f32 v[50:51], v[50:51], 1.0 op_sel_hi:[1,0]
	s_nop 0
	v_mul_f32_e32 v50, v50, v51
	v_rcp_f32_e32 v50, v50
	v_mul_f32_e32 v51, 0xbfb8aa3b, v58
	v_exp_f32_e32 v51, v51
	v_mul_f32_e32 v52, v52, v50
	v_mul_f32_e32 v50, 0xbfb8aa3b, v53
	v_exp_f32_e32 v50, v50
	v_mul_f32_e32 v53, v57, v58
	v_pk_add_f32 v[50:51], v[50:51], 1.0 op_sel_hi:[1,0]
	s_nop 0
	v_mul_f32_e32 v50, v50, v51
	v_rcp_f32_e32 v50, v50
	s_nop 0
	v_mul_f32_e32 v50, v53, v50
	v_cvt_pk_bf16_f32 v57, v52, v50
	v_lshlrev_b32_e32 v52, 16, v74
	v_exp_f32_e32 v50, v46
	v_mul_f32_e32 v46, 0xbfb8aa3b, v52
	v_exp_f32_e32 v51, v46
	v_lshlrev_b32_e32 v53, 16, v78
	v_mul_f32_e32 v46, v53, v52
	v_and_b32_e32 v52, 0xffff0000, v74
	v_pk_add_f32 v[50:51], v[50:51], 1.0 op_sel_hi:[1,0]
	global_store_dwordx4 v[146:147], v[54:57], off offset:256
	v_mul_f32_e32 v50, v50, v51
	v_rcp_f32_e32 v50, v50
	v_and_b32_e32 v51, 0xffff0000, v78
	v_mul_f32_e32 v51, v51, v52
	v_exp_f32_e32 v74, v38
	v_mul_f32_e32 v50, v46, v50
	v_mul_f32_e32 v46, 0xbfb8aa3b, v47
	v_mul_f32_e32 v47, 0xbfb8aa3b, v52
	v_exp_f32_e32 v46, v46
	v_exp_f32_e32 v47, v47
	v_lshlrev_b32_e32 v52, 16, v79
	v_pk_add_f32 v[46:47], v[46:47], 1.0 op_sel_hi:[1,0]
	s_nop 0
	v_mul_f32_e32 v46, v46, v47
	v_rcp_f32_e32 v46, v46
	v_lshlrev_b32_e32 v47, 16, v75
	v_mul_f32_e32 v46, v51, v46
	v_cvt_pk_bf16_f32 v46, v50, v46
	v_exp_f32_e32 v50, v48
	v_mul_f32_e32 v48, 0xbfb8aa3b, v47
	v_exp_f32_e32 v51, v48
	v_mul_f32_e32 v47, v52, v47
	v_pk_add_f32 v[50:51], v[50:51], 1.0 op_sel_hi:[1,0]
	s_nop 0
	v_mul_f32_e32 v48, v50, v51
	v_rcp_f32_e32 v48, v48
	v_and_b32_e32 v51, 0xffff0000, v75
	v_and_b32_e32 v50, 0xffff0000, v79
	v_mul_f32_e32 v50, v50, v51
	v_mul_f32_e32 v47, v47, v48
	v_mul_f32_e32 v48, 0xbfb8aa3b, v49
	v_mul_f32_e32 v49, 0xbfb8aa3b, v51
	v_exp_f32_e32 v48, v48
	v_exp_f32_e32 v49, v49
	v_lshlrev_b32_e32 v51, 16, v80
	v_pk_add_f32 v[48:49], v[48:49], 1.0 op_sel_hi:[1,0]
	s_nop 0
	v_mul_f32_e32 v48, v48, v49
	v_rcp_f32_e32 v48, v48
	s_nop 0
	v_mul_f32_e32 v48, v50, v48
	v_lshlrev_b32_e32 v50, 16, v76
	v_cvt_pk_bf16_f32 v47, v47, v48
	v_exp_f32_e32 v48, v42
	v_mul_f32_e32 v42, 0xbfb8aa3b, v50
	v_exp_f32_e32 v49, v42
	v_mul_f32_e32 v42, v51, v50
	v_and_b32_e32 v50, 0xffff0000, v76
	v_pk_add_f32 v[48:49], v[48:49], 1.0 op_sel_hi:[1,0]
	s_nop 0
	v_mul_f32_e32 v48, v48, v49
	v_rcp_f32_e32 v48, v48
	v_and_b32_e32 v49, 0xffff0000, v80
	v_mul_f32_e32 v49, v49, v50
	v_mul_f32_e32 v48, v42, v48
	v_mul_f32_e32 v42, 0xbfb8aa3b, v43
	v_mul_f32_e32 v43, 0xbfb8aa3b, v50
	v_exp_f32_e32 v42, v42
	v_exp_f32_e32 v43, v43
	v_lshlrev_b32_e32 v50, 16, v81
	v_pk_add_f32 v[42:43], v[42:43], 1.0 op_sel_hi:[1,0]
	s_nop 0
	v_mul_f32_e32 v42, v42, v43
	v_rcp_f32_e32 v42, v42
	s_nop 0
	v_mul_f32_e32 v42, v49, v42
	v_lshlrev_b32_e32 v49, 16, v77
	v_cvt_pk_bf16_f32 v48, v48, v42
; __device__ __forceinline__ unsigned cvt_pk_bf16(float lo, float hi) { unsigned r; asm volatile("v_cvt_pk_bf16_f32 %0, %1, %2" : "=v"(r) : "v"(lo), "v"(hi)); return r; }
; __device__ __forceinline__ float bf_lo(unsigned w) { return __uint_as_float(w << 16); }
; __device__ __forceinline__ float bf_hi(unsigned w) { return __uint_as_float(w & 0xffff0000u); }
;     __device__ __forceinline__ void operator()(const f32x4 (&acc)[2][2][4][2], const Unit& u, int wr, int wc, int fr, int fq, const Pre&) const {
;     ...
;             for (int ai = 0; ai < 2; ++ai) { u32x4 zv[4], gv[4];
; #pragma unroll
;                 for (int m = 0; m < 4; ++m) { const int r = row0 + ai * HALF + m * 16; zv[m] = *(const u32x4*)(Z + (size_t)r * DE2 + c); gv[m] = *(const u32x4*)(Gm + (size_t)(c >> 4) * GSTR + r * 16 + (c & 15)); }
; #pragma unroll
;                 for (int m = 0; m < 4; ++m) { const int r = row0 + ai * HALF + m * 16;
;                     const u32x4 zw = zv[m], gw = gv[m];
;                     const f32x4 a0 = acc[ai][bj][m][0] + bs[bj][0], a1 = acc[ai][bj][m][1] + bs[bj][1];
;                     u32x4 w;
;                     w.x = cvt_pk_bf16(glu_gate_f(bf_lo(gw.x), a0[0], bf_lo(zw.x)), glu_gate_f(bf_hi(gw.x), a0[1], bf_hi(zw.x)));
;                     w.y = cvt_pk_bf16(glu_gate_f(bf_lo(gw.y), a0[2], bf_lo(zw.y)), glu_gate_f(bf_hi(gw.y), a0[3], bf_hi(zw.y)));
;                     w.z = cvt_pk_bf16(glu_gate_f(bf_lo(gw.z), a1[0], bf_lo(zw.z)), glu_gate_f(bf_hi(gw.z), a1[1], bf_hi(zw.z)));
;                     w.w = cvt_pk_bf16(glu_gate_f(bf_lo(gw.w), a1[2], bf_lo(zw.w)), glu_gate_f(bf_hi(gw.w), a1[3], bf_hi(zw.w)));
;                     *(u32x4*)(O + (size_t)r * DE + c) = w; } } }
	v_mul_f32_e32 v42, 0xbfb8aa3b, v44
	v_mul_f32_e32 v43, 0xbfb8aa3b, v49
	v_exp_f32_e32 v42, v42
	v_exp_f32_e32 v43, v43
	v_mul_f32_e32 v44, v50, v49
	v_and_b32_e32 v50, 0xffff0000, v77
	v_and_b32_e32 v49, 0xffff0000, v81
	v_pk_add_f32 v[42:43], v[42:43], 1.0 op_sel_hi:[1,0]
	s_nop 0
	v_mul_f32_e32 v42, v42, v43
	v_rcp_f32_e32 v42, v42
	v_mul_f32_e32 v43, 0xbfb8aa3b, v50
	v_exp_f32_e32 v43, v43
	v_mul_f32_e32 v44, v44, v42
	v_mul_f32_e32 v42, 0xbfb8aa3b, v45
	v_exp_f32_e32 v42, v42
	v_mul_f32_e32 v45, v49, v50
	v_pk_add_f32 v[42:43], v[42:43], 1.0 op_sel_hi:[1,0]
	s_nop 0
	v_mul_f32_e32 v42, v42, v43
	v_rcp_f32_e32 v42, v42
	s_nop 0
	v_mul_f32_e32 v42, v45, v42
	v_cvt_pk_bf16_f32 v49, v44, v42
	v_lshl_add_u64 v[42:43], s[46:47], 0, v[150:151]
	global_store_dwordx4 v[148:149], v[46:49], off offset:256
	v_lshl_add_u64 v[42:43], v[42:43], 0, v[116:117]
	global_load_dwordx4 v[66:69], v[42:43], off
	v_lshl_add_u64 v[46:47], v[114:115], 0, v[168:169]
	global_load_dwordx4 v[46:49], v[46:47], off
	v_lshl_add_u64 v[42:43], v[114:115], 0, v[152:153]
	global_load_dwordx4 v[70:73], v[42:43], off
	v_lshl_add_u64 v[42:43], s[46:47], 0, v[156:157]
	v_lshl_add_u64 v[42:43], v[42:43], 0, v[116:117]
	global_load_dwordx4 v[58:61], v[42:43], off
	v_lshl_add_u64 v[42:43], v[114:115], 0, v[158:159]
	global_load_dwordx4 v[62:65], v[42:43], off
	v_lshl_add_u64 v[42:43], s[46:47], 0, v[160:161]
	v_lshl_add_u64 v[42:43], v[42:43], 0, v[116:117]
	global_load_dwordx4 v[50:53], v[42:43], off
	v_lshl_add_u64 v[42:43], v[114:115], 0, v[164:165]
	global_load_dwordx4 v[54:57], v[42:43], off
	v_lshl_add_u64 v[42:43], s[46:47], 0, v[166:167]
	v_lshl_add_u64 v[42:43], v[42:43], 0, v[116:117]
	global_load_dwordx4 v[42:45], v[42:43], off
	s_waitcnt vmcnt(0)
	v_lshlrev_b32_e32 v76, 16, v66
	v_mul_f32_e32 v38, 0xbfb8aa3b, v76
	v_exp_f32_e32 v75, v38
	v_and_b32_e32 v66, 0xffff0000, v66
	v_lshlrev_b32_e32 v77, 16, v70
	v_mul_f32_e32 v38, v77, v76
	v_pk_add_f32 v[74:75], v[74:75], 1.0 op_sel_hi:[1,0]
	v_and_b32_e32 v70, 0xffff0000, v70
	v_mul_f32_e32 v74, v74, v75
	v_rcp_f32_e32 v74, v74
	s_nop 0
	v_mul_f32_e32 v74, v38, v74
	v_mul_f32_e32 v38, 0xbfb8aa3b, v39
	v_mul_f32_e32 v39, 0xbfb8aa3b, v66
	v_exp_f32_e32 v38, v38
	v_exp_f32_e32 v39, v39
	v_mul_f32_e32 v66, v70, v66
	v_pk_add_f32 v[38:39], v[38:39], 1.0 op_sel_hi:[1,0]
	s_nop 0
	v_mul_f32_e32 v38, v38, v39
	v_rcp_f32_e32 v38, v38
	v_lshlrev_b32_e32 v39, 16, v67
	v_and_b32_e32 v67, 0xffff0000, v67
	v_mul_f32_e32 v38, v66, v38
	v_cvt_pk_bf16_f32 v38, v74, v38
	v_exp_f32_e32 v74, v40
	v_mul_f32_e32 v40, 0xbfb8aa3b, v39
	v_exp_f32_e32 v75, v40
	v_lshlrev_b32_e32 v66, 16, v71
	v_mul_f32_e32 v39, v66, v39
	v_and_b32_e32 v66, 0xffff0000, v71
	v_pk_add_f32 v[74:75], v[74:75], 1.0 op_sel_hi:[1,0]
	v_mul_f32_e32 v66, v66, v67
	v_mul_f32_e32 v40, v74, v75
	v_rcp_f32_e32 v40, v40
	s_nop 0
	v_mul_f32_e32 v39, v39, v40
	v_mul_f32_e32 v40, 0xbfb8aa3b, v41
	v_mul_f32_e32 v41, 0xbfb8aa3b, v67
	v_exp_f32_e32 v40, v40
	v_exp_f32_e32 v41, v41
	v_lshlrev_b32_e32 v67, 16, v72
	v_pk_add_f32 v[40:41], v[40:41], 1.0 op_sel_hi:[1,0]
	s_nop 0
	v_mul_f32_e32 v40, v40, v41
	v_rcp_f32_e32 v40, v40
	s_nop 0
	v_mul_f32_e32 v40, v66, v40
	v_lshlrev_b32_e32 v66, 16, v68
	v_cvt_pk_bf16_f32 v39, v39, v40
	v_exp_f32_e32 v40, v34
	v_mul_f32_e32 v34, 0xbfb8aa3b, v66
	v_exp_f32_e32 v41, v34
	v_mul_f32_e32 v34, v67, v66
	v_and_b32_e32 v66, 0xffff0000, v68
	v_pk_add_f32 v[40:41], v[40:41], 1.0 op_sel_hi:[1,0]
	s_nop 0
	v_mul_f32_e32 v40, v40, v41
	v_rcp_f32_e32 v40, v40
	v_and_b32_e32 v41, 0xffff0000, v72
	v_mul_f32_e32 v41, v41, v66
	v_mul_f32_e32 v40, v34, v40
	v_mul_f32_e32 v34, 0xbfb8aa3b, v35
	v_mul_f32_e32 v35, 0xbfb8aa3b, v66
	v_exp_f32_e32 v34, v34
	v_exp_f32_e32 v35, v35
	v_lshlrev_b32_e32 v66, 16, v73
	v_pk_add_f32 v[34:35], v[34:35], 1.0 op_sel_hi:[1,0]
	s_nop 0
	v_mul_f32_e32 v34, v34, v35
	v_rcp_f32_e32 v34, v34
	s_nop 0
	v_mul_f32_e32 v34, v41, v34
	v_lshlrev_b32_e32 v41, 16, v69
	v_cvt_pk_bf16_f32 v40, v40, v34
	v_mul_f32_e32 v34, 0xbfb8aa3b, v36
	v_mul_f32_e32 v35, 0xbfb8aa3b, v41
	v_exp_f32_e32 v34, v34
	v_exp_f32_e32 v35, v35
	v_mul_f32_e32 v36, v66, v41
	v_and_b32_e32 v66, 0xffff0000, v69
	v_and_b32_e32 v41, 0xffff0000, v73
	v_pk_add_f32 v[34:35], v[34:35], 1.0 op_sel_hi:[1,0]
	s_nop 0
	v_mul_f32_e32 v34, v34, v35
	v_rcp_f32_e32 v34, v34
	v_mul_f32_e32 v35, 0xbfb8aa3b, v66
	v_exp_f32_e32 v35, v35
	v_mul_f32_e32 v36, v36, v34
	v_mul_f32_e32 v34, 0xbfb8aa3b, v37
	v_exp_f32_e32 v34, v34
	v_mul_f32_e32 v37, v41, v66
	v_pk_add_f32 v[34:35], v[34:35], 1.0 op_sel_hi:[1,0]
	s_nop 0
	v_mul_f32_e32 v34, v34, v35
	v_rcp_f32_e32 v34, v34
	s_nop 0
	v_mul_f32_e32 v34, v37, v34
	v_cvt_pk_bf16_f32 v41, v36, v34
	v_lshlrev_b32_e32 v36, 16, v58
	v_exp_f32_e32 v34, v22
	v_mul_f32_e32 v22, 0xbfb8aa3b, v36
	v_exp_f32_e32 v35, v22
	v_lshlrev_b32_e32 v37, 16, v62
	v_mul_f32_e32 v22, v37, v36
	v_and_b32_e32 v36, 0xffff0000, v58
	v_pk_add_f32 v[34:35], v[34:35], 1.0 op_sel_hi:[1,0]
	global_store_dwordx4 v[106:107], v[38:41], off offset:256
	v_mul_f32_e32 v34, v34, v35
	v_rcp_f32_e32 v34, v34
	v_and_b32_e32 v35, 0xffff0000, v62
	v_mul_f32_e32 v35, v35, v36
	v_mul_f32_e32 v34, v22, v34
	v_mul_f32_e32 v22, 0xbfb8aa3b, v23
	v_mul_f32_e32 v23, 0xbfb8aa3b, v36
	v_exp_f32_e32 v22, v22
	v_exp_f32_e32 v23, v23
	v_lshlrev_b32_e32 v36, 16, v63
	v_pk_add_f32 v[22:23], v[22:23], 1.0 op_sel_hi:[1,0]
	s_nop 0
	v_mul_f32_e32 v22, v22, v23
	v_rcp_f32_e32 v22, v22
	v_lshlrev_b32_e32 v23, 16, v59
	v_mul_f32_e32 v22, v35, v22
	v_cvt_pk_bf16_f32 v22, v34, v22
	v_exp_f32_e32 v34, v24
	v_mul_f32_e32 v24, 0xbfb8aa3b, v23
	v_exp_f32_e32 v35, v24
	v_mul_f32_e32 v23, v36, v23
; __device__ __forceinline__ unsigned cvt_pk_bf16(float lo, float hi) { unsigned r; asm volatile("v_cvt_pk_bf16_f32 %0, %1, %2" : "=v"(r) : "v"(lo), "v"(hi)); return r; }
; __device__ __forceinline__ float bf_lo(unsigned w) { return __uint_as_float(w << 16); }
; __device__ __forceinline__ float bf_hi(unsigned w) { return __uint_as_float(w & 0xffff0000u); }
; __device__ __forceinline__ float fast_rcp(float x) { return __builtin_amdgcn_rcpf(x); }
; __device__ __forceinline__ float glu_gate_f(float g, float v, float z) {
;     const float ev = __builtin_amdgcn_exp2f(v * -1.44269504f), ez = __builtin_amdgcn_exp2f(z * -1.44269504f);
;     return g * z * fast_rcp((1.0f + ev) * (1.0f + ez));
; }
;     __device__ __forceinline__ void operator()(const f32x4 (&acc)[2][2][4][2], const Unit& u, int wr, int wc, int fr, int fq, const Pre&) const {
;     ...
;                 for (int m = 0; m < 4; ++m) { const int r = row0 + ai * HALF + m * 16;
;                     const u32x4 zw = zv[m], gw = gv[m];
;                     const f32x4 a0 = acc[ai][bj][m][0] + bs[bj][0], a1 = acc[ai][bj][m][1] + bs[bj][1];
;                     u32x4 w;
;                     w.x = cvt_pk_bf16(glu_gate_f(bf_lo(gw.x), a0[0], bf_lo(zw.x)), glu_gate_f(bf_hi(gw.x), a0[1], bf_hi(zw.x)));
;                     w.y = cvt_pk_bf16(glu_gate_f(bf_lo(gw.y), a0[2], bf_lo(zw.y)), glu_gate_f(bf_hi(gw.y), a0[3], bf_hi(zw.y)));
;                     w.z = cvt_pk_bf16(glu_gate_f(bf_lo(gw.z), a1[0], bf_lo(zw.z)), glu_gate_f(bf_hi(gw.z), a1[1], bf_hi(zw.z)));
;                     w.w = cvt_pk_bf16(glu_gate_f(bf_lo(gw.w), a1[2], bf_lo(zw.w)), glu_gate_f(bf_hi(gw.w), a1[3], bf_hi(zw.w)));
;                     *(u32x4*)(O + (size_t)r * DE + c) = w; } } }
	v_pk_add_f32 v[34:35], v[34:35], 1.0 op_sel_hi:[1,0]
	s_nop 0
	v_mul_f32_e32 v24, v34, v35
	v_rcp_f32_e32 v24, v24
	v_and_b32_e32 v35, 0xffff0000, v59
	v_and_b32_e32 v34, 0xffff0000, v63
	v_mul_f32_e32 v34, v34, v35
	v_mul_f32_e32 v23, v23, v24
	v_mul_f32_e32 v24, 0xbfb8aa3b, v25
	v_mul_f32_e32 v25, 0xbfb8aa3b, v35
	v_exp_f32_e32 v24, v24
	v_exp_f32_e32 v25, v25
	v_lshlrev_b32_e32 v35, 16, v64
	v_pk_add_f32 v[24:25], v[24:25], 1.0 op_sel_hi:[1,0]
	s_nop 0
	v_mul_f32_e32 v24, v24, v25
	v_rcp_f32_e32 v24, v24
	s_nop 0
	v_mul_f32_e32 v24, v34, v24
	v_lshlrev_b32_e32 v34, 16, v60
	v_cvt_pk_bf16_f32 v23, v23, v24
	v_exp_f32_e32 v24, v18
	v_mul_f32_e32 v18, 0xbfb8aa3b, v34
	v_exp_f32_e32 v25, v18
	v_mul_f32_e32 v18, v35, v34
	v_and_b32_e32 v34, 0xffff0000, v60
	v_pk_add_f32 v[24:25], v[24:25], 1.0 op_sel_hi:[1,0]
	s_nop 0
	v_mul_f32_e32 v24, v24, v25
	v_rcp_f32_e32 v24, v24
	v_and_b32_e32 v25, 0xffff0000, v64
	v_mul_f32_e32 v25, v25, v34
	v_mul_f32_e32 v24, v18, v24
	v_mul_f32_e32 v18, 0xbfb8aa3b, v19
	v_mul_f32_e32 v19, 0xbfb8aa3b, v34
	v_exp_f32_e32 v18, v18
	v_exp_f32_e32 v19, v19
	v_lshlrev_b32_e32 v34, 16, v65
	v_pk_add_f32 v[18:19], v[18:19], 1.0 op_sel_hi:[1,0]
	s_nop 0
	v_mul_f32_e32 v18, v18, v19
	v_rcp_f32_e32 v18, v18
	s_nop 0
	v_mul_f32_e32 v18, v25, v18
	v_lshlrev_b32_e32 v25, 16, v61
	v_cvt_pk_bf16_f32 v24, v24, v18
	v_mul_f32_e32 v18, 0xbfb8aa3b, v20
	v_mul_f32_e32 v19, 0xbfb8aa3b, v25
	v_exp_f32_e32 v18, v18
	v_exp_f32_e32 v19, v19
	v_mul_f32_e32 v20, v34, v25
	v_and_b32_e32 v34, 0xffff0000, v61
	v_and_b32_e32 v25, 0xffff0000, v65
	v_pk_add_f32 v[18:19], v[18:19], 1.0 op_sel_hi:[1,0]
	s_nop 0
	v_mul_f32_e32 v18, v18, v19
	v_rcp_f32_e32 v18, v18
	v_mul_f32_e32 v19, 0xbfb8aa3b, v34
	v_exp_f32_e32 v19, v19
	v_mul_f32_e32 v20, v20, v18
	v_mul_f32_e32 v18, 0xbfb8aa3b, v21
	v_exp_f32_e32 v18, v18
	v_mul_f32_e32 v21, v25, v34
	v_pk_add_f32 v[18:19], v[18:19], 1.0 op_sel_hi:[1,0]
	s_nop 0
	v_mul_f32_e32 v18, v18, v19
	v_rcp_f32_e32 v18, v18
	s_nop 0
	v_mul_f32_e32 v18, v21, v18
	v_cvt_pk_bf16_f32 v25, v20, v18
	v_lshlrev_b32_e32 v20, 16, v50
	v_exp_f32_e32 v18, v14
	v_mul_f32_e32 v14, 0xbfb8aa3b, v20
	v_exp_f32_e32 v19, v14
	v_lshlrev_b32_e32 v21, 16, v54
	v_mul_f32_e32 v14, v21, v20
	v_and_b32_e32 v20, 0xffff0000, v50
	v_pk_add_f32 v[18:19], v[18:19], 1.0 op_sel_hi:[1,0]
	global_store_dwordx4 v[108:109], v[22:25], off offset:256
	v_mul_f32_e32 v18, v18, v19
	v_rcp_f32_e32 v18, v18
	v_and_b32_e32 v19, 0xffff0000, v54
	v_mul_f32_e32 v19, v19, v20
	v_mul_f32_e32 v18, v14, v18
	v_mul_f32_e32 v14, 0xbfb8aa3b, v15
	v_mul_f32_e32 v15, 0xbfb8aa3b, v20
	v_exp_f32_e32 v14, v14
	v_exp_f32_e32 v15, v15
	v_lshlrev_b32_e32 v20, 16, v55
	v_pk_add_f32 v[14:15], v[14:15], 1.0 op_sel_hi:[1,0]
	s_nop 0
	v_mul_f32_e32 v14, v14, v15
	v_rcp_f32_e32 v14, v14
	v_lshlrev_b32_e32 v15, 16, v51
	v_mul_f32_e32 v14, v19, v14
	v_cvt_pk_bf16_f32 v14, v18, v14
	v_exp_f32_e32 v18, v16
	v_mul_f32_e32 v16, 0xbfb8aa3b, v15
	v_exp_f32_e32 v19, v16
	v_mul_f32_e32 v15, v20, v15
	v_pk_add_f32 v[18:19], v[18:19], 1.0 op_sel_hi:[1,0]
	s_nop 0
	v_mul_f32_e32 v16, v18, v19
	v_rcp_f32_e32 v16, v16
	v_and_b32_e32 v19, 0xffff0000, v51
	v_and_b32_e32 v18, 0xffff0000, v55
	v_mul_f32_e32 v18, v18, v19
	v_mul_f32_e32 v15, v15, v16
	v_mul_f32_e32 v16, 0xbfb8aa3b, v17
	v_mul_f32_e32 v17, 0xbfb8aa3b, v19
	v_exp_f32_e32 v16, v16
	v_exp_f32_e32 v17, v17
	v_lshlrev_b32_e32 v19, 16, v56
	v_pk_add_f32 v[16:17], v[16:17], 1.0 op_sel_hi:[1,0]
	s_nop 0
	v_mul_f32_e32 v16, v16, v17
	v_rcp_f32_e32 v16, v16
	s_nop 0
	v_mul_f32_e32 v16, v18, v16
	v_lshlrev_b32_e32 v18, 16, v52
	v_cvt_pk_bf16_f32 v15, v15, v16
	v_exp_f32_e32 v16, v10
	v_mul_f32_e32 v10, 0xbfb8aa3b, v18
	v_exp_f32_e32 v17, v10
	v_mul_f32_e32 v10, v19, v18
	v_and_b32_e32 v18, 0xffff0000, v52
	v_pk_add_f32 v[16:17], v[16:17], 1.0 op_sel_hi:[1,0]
	s_nop 0
	v_mul_f32_e32 v16, v16, v17
	v_rcp_f32_e32 v16, v16
	v_and_b32_e32 v17, 0xffff0000, v56
	v_mul_f32_e32 v17, v17, v18
	v_mul_f32_e32 v16, v10, v16
	v_mul_f32_e32 v10, 0xbfb8aa3b, v11
	v_mul_f32_e32 v11, 0xbfb8aa3b, v18
	v_exp_f32_e32 v10, v10
; __device__ __forceinline__ unsigned cvt_pk_bf16(float lo, float hi) { unsigned r; asm volatile("v_cvt_pk_bf16_f32 %0, %1, %2" : "=v"(r) : "v"(lo), "v"(hi)); return r; }
; __device__ __forceinline__ float bf_lo(unsigned w) { return __uint_as_float(w << 16); }
; __device__ __forceinline__ float bf_hi(unsigned w) { return __uint_as_float(w & 0xffff0000u); }
; __device__ __forceinline__ float fast_rcp(float x) { return __builtin_amdgcn_rcpf(x); }
; __device__ __forceinline__ float glu_gate_f(float g, float v, float z) {
;     const float ev = __builtin_amdgcn_exp2f(v * -1.44269504f), ez = __builtin_amdgcn_exp2f(z * -1.44269504f);
;     return g * z * fast_rcp((1.0f + ev) * (1.0f + ez));
; }
;     __device__ __forceinline__ void operator()(const f32x4 (&acc)[2][2][4][2], const Unit& u, int wr, int wc, int fr, int fq, const Pre&) const {
;     ...
;                 for (int m = 0; m < 4; ++m) { const int r = row0 + ai * HALF + m * 16;
;                     const u32x4 zw = zv[m], gw = gv[m];
;                     const f32x4 a0 = acc[ai][bj][m][0] + bs[bj][0], a1 = acc[ai][bj][m][1] + bs[bj][1];
;                     u32x4 w;
;                     w.x = cvt_pk_bf16(glu_gate_f(bf_lo(gw.x), a0[0], bf_lo(zw.x)), glu_gate_f(bf_hi(gw.x), a0[1], bf_hi(zw.x)));
;                     w.y = cvt_pk_bf16(glu_gate_f(bf_lo(gw.y), a0[2], bf_lo(zw.y)), glu_gate_f(bf_hi(gw.y), a0[3], bf_hi(zw.y)));
;                     w.z = cvt_pk_bf16(glu_gate_f(bf_lo(gw.z), a1[0], bf_lo(zw.z)), glu_gate_f(bf_hi(gw.z), a1[1], bf_hi(zw.z)));
;                     w.w = cvt_pk_bf16(glu_gate_f(bf_lo(gw.w), a1[2], bf_lo(zw.w)), glu_gate_f(bf_hi(gw.w), a1[3], bf_hi(zw.w)));
;                     *(u32x4*)(O + (size_t)r * DE + c) = w; } } }
	v_exp_f32_e32 v11, v11
	v_lshlrev_b32_e32 v18, 16, v57
	v_pk_add_f32 v[10:11], v[10:11], 1.0 op_sel_hi:[1,0]
	s_nop 0
	v_mul_f32_e32 v10, v10, v11
	v_rcp_f32_e32 v10, v10
	s_nop 0
	v_mul_f32_e32 v10, v17, v10
	v_lshlrev_b32_e32 v17, 16, v53
	v_cvt_pk_bf16_f32 v16, v16, v10
	v_mul_f32_e32 v10, 0xbfb8aa3b, v12
	v_mul_f32_e32 v11, 0xbfb8aa3b, v17
	v_exp_f32_e32 v10, v10
	v_exp_f32_e32 v11, v11
	v_mul_f32_e32 v12, v18, v17
	v_and_b32_e32 v18, 0xffff0000, v53
	v_and_b32_e32 v17, 0xffff0000, v57
	v_pk_add_f32 v[10:11], v[10:11], 1.0 op_sel_hi:[1,0]
	s_nop 0
	v_mul_f32_e32 v10, v10, v11
	v_rcp_f32_e32 v10, v10
	v_mul_f32_e32 v11, 0xbfb8aa3b, v18
	v_exp_f32_e32 v11, v11
	v_mul_f32_e32 v12, v12, v10
	v_mul_f32_e32 v10, 0xbfb8aa3b, v13
	v_exp_f32_e32 v10, v10
	v_mul_f32_e32 v13, v17, v18
	v_pk_add_f32 v[10:11], v[10:11], 1.0 op_sel_hi:[1,0]
	s_nop 0
	v_mul_f32_e32 v10, v10, v11
	v_rcp_f32_e32 v10, v10
	s_nop 0
	v_mul_f32_e32 v10, v13, v10
	v_cvt_pk_bf16_f32 v17, v12, v10
	v_lshlrev_b32_e32 v12, 16, v42
	v_exp_f32_e32 v10, v6
	v_mul_f32_e32 v6, 0xbfb8aa3b, v12
	v_exp_f32_e32 v11, v6
	v_lshlrev_b32_e32 v13, 16, v46
	v_mul_f32_e32 v6, v13, v12
	v_and_b32_e32 v12, 0xffff0000, v42
	v_pk_add_f32 v[10:11], v[10:11], 1.0 op_sel_hi:[1,0]
	global_store_dwordx4 v[110:111], v[14:17], off offset:256
	v_mul_f32_e32 v10, v10, v11
	v_rcp_f32_e32 v10, v10
	v_and_b32_e32 v11, 0xffff0000, v46
	v_mul_f32_e32 v11, v11, v12
	v_mul_f32_e32 v10, v6, v10
	v_mul_f32_e32 v6, 0xbfb8aa3b, v7
	v_mul_f32_e32 v7, 0xbfb8aa3b, v12
	v_exp_f32_e32 v6, v6
	v_exp_f32_e32 v7, v7
	v_lshlrev_b32_e32 v12, 16, v47
	v_pk_add_f32 v[6:7], v[6:7], 1.0 op_sel_hi:[1,0]
	s_nop 0
	v_mul_f32_e32 v6, v6, v7
	v_rcp_f32_e32 v6, v6
	v_lshlrev_b32_e32 v7, 16, v43
	v_mul_f32_e32 v6, v11, v6
	v_cvt_pk_bf16_f32 v6, v10, v6
	v_exp_f32_e32 v10, v8
	v_mul_f32_e32 v8, 0xbfb8aa3b, v7
	v_exp_f32_e32 v11, v8
	v_mul_f32_e32 v7, v12, v7
	v_pk_add_f32 v[10:11], v[10:11], 1.0 op_sel_hi:[1,0]
	s_nop 0
	v_mul_f32_e32 v8, v10, v11
	v_rcp_f32_e32 v8, v8
	v_and_b32_e32 v11, 0xffff0000, v43
	v_and_b32_e32 v10, 0xffff0000, v47
	v_mul_f32_e32 v10, v10, v11
	v_mul_f32_e32 v7, v7, v8
	v_mul_f32_e32 v8, 0xbfb8aa3b, v9
	v_mul_f32_e32 v9, 0xbfb8aa3b, v11
	v_exp_f32_e32 v8, v8
	v_exp_f32_e32 v9, v9
	v_lshlrev_b32_e32 v11, 16, v48
	v_pk_add_f32 v[8:9], v[8:9], 1.0 op_sel_hi:[1,0]
	s_nop 0
	v_mul_f32_e32 v8, v8, v9
	v_rcp_f32_e32 v8, v8
	s_nop 0
	v_mul_f32_e32 v8, v10, v8
	v_lshlrev_b32_e32 v10, 16, v44
	v_cvt_pk_bf16_f32 v7, v7, v8
	v_exp_f32_e32 v8, v2
	v_mul_f32_e32 v2, 0xbfb8aa3b, v10
	v_exp_f32_e32 v9, v2
	v_mul_f32_e32 v2, v11, v10
	v_and_b32_e32 v10, 0xffff0000, v44
	v_pk_add_f32 v[8:9], v[8:9], 1.0 op_sel_hi:[1,0]
	s_nop 0
	v_mul_f32_e32 v8, v8, v9
	v_rcp_f32_e32 v8, v8
	v_and_b32_e32 v9, 0xffff0000, v48
	v_mul_f32_e32 v9, v9, v10
	v_mul_f32_e32 v8, v2, v8
	v_mul_f32_e32 v2, 0xbfb8aa3b, v3
	v_mul_f32_e32 v3, 0xbfb8aa3b, v10
	v_exp_f32_e32 v2, v2
	v_exp_f32_e32 v3, v3
	v_lshlrev_b32_e32 v10, 16, v49
	v_pk_add_f32 v[2:3], v[2:3], 1.0 op_sel_hi:[1,0]
	s_nop 0
	v_mul_f32_e32 v2, v2, v3
	v_rcp_f32_e32 v2, v2
	s_nop 0
	v_mul_f32_e32 v2, v9, v2
	v_lshlrev_b32_e32 v9, 16, v45
	v_cvt_pk_bf16_f32 v8, v8, v2
	v_mul_f32_e32 v2, 0xbfb8aa3b, v4
	v_mul_f32_e32 v3, 0xbfb8aa3b, v9
	v_exp_f32_e32 v2, v2
	v_exp_f32_e32 v3, v3
	v_mul_f32_e32 v4, v10, v9
	v_and_b32_e32 v10, 0xffff0000, v45
	v_and_b32_e32 v9, 0xffff0000, v49
	v_pk_add_f32 v[2:3], v[2:3], 1.0 op_sel_hi:[1,0]
	s_nop 0
	v_mul_f32_e32 v2, v2, v3
	v_rcp_f32_e32 v2, v2
	v_mul_f32_e32 v3, 0xbfb8aa3b, v10
	v_exp_f32_e32 v3, v3
	v_mul_f32_e32 v4, v4, v2
	v_mul_f32_e32 v2, 0xbfb8aa3b, v5
	v_exp_f32_e32 v2, v2
	v_mul_f32_e32 v5, v9, v10
	v_pk_add_f32 v[2:3], v[2:3], 1.0 op_sel_hi:[1,0]
	s_nop 0
	v_mul_f32_e32 v2, v2, v3
	v_rcp_f32_e32 v2, v2
	s_nop 0
	v_mul_f32_e32 v2, v5, v2
	v_cvt_pk_bf16_f32 v9, v4, v2
	global_store_dwordx4 v[112:113], v[6:9], off offset:256
	s_cbranch_vccz .LBB0_789
	s_waitcnt vmcnt(0)
	v_readlane_b32 s36, v254, 56
	s_cmpk_gt_u32 s18, 0xff
	v_readlane_b32 s37, v254, 57
	s_cbranch_scc1 .LBB0_800
	s_barrier
